# replace bit-trick RNE bf16 pair packing (bfe/add3/lshr/and_or) with v_cvt_pk_bf16_f32 (same RNE), removed instrs as s_nop 0
# speedup vs baseline: 1.0067x; 1.0010x over previous
; __device__ __forceinline__ unsigned pk2(float lo, float hi) { return f2bf(lo) | (f2bf(hi) << 16); }
; __device__ __forceinline__ void phase_prep(const Args& A, const Ctx& C0, int l) {
;     ...
;     bf16x8 wfr[2][4][2];
;     { const int fr = C.lane & 15, fq = C.lane >> 4;
; #pragma unroll
;       for (int mat = 0; mat < 2; ++mat) { const float* W = A.in[mat ? I_AUP : I_WUP] + (size_t)l * 64 * 512 + head * 64 + fr;
; #pragma unroll
;           for (int ct = 0; ct < 4; ++ct)
; #pragma unroll
;               for (int ks = 0; ks < 2; ++ks) { const float* p = W + (size_t)(ks * 32 + 8 * fq) * 512 + ct * 16;
;                   union { bf16x8 v; unsigned w[4]; } f;
; #pragma unroll
;                   for (int e = 0; e < 4; ++e) f.w[e] = pk2(p[(2 * e) * 512], p[(2 * e + 1) * 512]);
;                   wfr[mat][ct][ks] = f.v; } } }
.LBB0_43:
	v_and_b32_e32 v166, 63, v94
	s_andn2_b64 vcc, exec, s[40:41]
	s_cbranch_vccnz .LBB0_116
	s_waitcnt vmcnt(0)
	s_nop 0
	s_nop 0
	s_nop 0
	s_nop 0
	s_nop 0
	v_cvt_pk_bf16_f32 v18, v19, v18
	s_nop 0
	s_nop 0
	s_nop 0
	s_nop 0
	s_nop 0
	v_cvt_pk_bf16_f32 v19, v159, v20
	s_nop 0
	s_nop 0
	s_nop 0
	s_nop 0
	s_nop 0
	v_cvt_pk_bf16_f32 v20, v158, v22
	s_nop 0
	s_nop 0
	s_nop 0
	s_nop 0
	s_nop 0
	v_cvt_pk_bf16_f32 v21, v21, v164
	s_nop 0
	s_nop 0
	s_nop 0
	s_nop 0
	s_nop 0
	v_cvt_pk_bf16_f32 v22, v161, v162
	s_nop 0
	s_nop 0
	s_nop 0
	s_nop 0
	s_nop 0
	v_cvt_pk_bf16_f32 v23, v23, v165
	s_nop 0
	s_nop 0
	s_nop 0
	s_nop 0
	s_nop 0
	v_cvt_pk_bf16_f32 v24, v25, v24
	s_nop 0
	s_nop 0
	s_nop 0
	s_nop 0
	s_nop 0
	v_cvt_pk_bf16_f32 v25, v160, v163
	s_nop 0
	s_nop 0
	s_nop 0
	s_nop 0
	s_nop 0
	v_cvt_pk_bf16_f32 v26, v27, v26
	s_nop 0
	s_nop 0
	s_nop 0
	s_nop 0
	s_nop 0
	v_cvt_pk_bf16_f32 v27, v29, v28
	s_nop 0
	s_nop 0
	s_nop 0
	s_nop 0
	s_nop 0
	v_cvt_pk_bf16_f32 v28, v31, v30
	s_nop 0
	s_nop 0
	s_nop 0
	s_nop 0
	s_nop 0
	v_cvt_pk_bf16_f32 v29, v157, v156
	s_nop 0
	s_nop 0
	s_nop 0
	s_nop 0
	s_nop 0
	v_cvt_pk_bf16_f32 v30, v154, v153
	s_nop 0
	s_nop 0
	s_nop 0
	s_nop 0
	s_nop 0
	v_cvt_pk_bf16_f32 v31, v151, v155
	s_nop 0
	s_nop 0
	s_nop 0
	s_nop 0
	s_nop 0
	v_cvt_pk_bf16_f32 v32, v33, v32
	s_nop 0
	s_nop 0
	s_nop 0
	s_nop 0
	s_nop 0
	v_cvt_pk_bf16_f32 v33, v150, v152
	s_nop 0
	s_nop 0
	s_nop 0
	s_nop 0
	s_nop 0
	v_cvt_pk_bf16_f32 v34, v35, v34
	s_nop 0
	s_nop 0
	s_nop 0
	s_nop 0
	s_nop 0
	v_cvt_pk_bf16_f32 v35, v37, v36
	s_nop 0
	s_nop 0
	s_nop 0
	s_nop 0
	s_nop 0
	v_cvt_pk_bf16_f32 v36, v39, v38
	s_nop 0
	s_nop 0
	s_nop 0
	s_nop 0
	s_nop 0
	v_cvt_pk_bf16_f32 v37, v133, v129
	s_nop 0
	s_nop 0
	s_nop 0
	s_nop 0
	s_nop 0
	v_cvt_pk_bf16_f32 v38, v130, v127
	s_nop 0
	s_nop 0
	s_nop 0
	s_nop 0
	s_nop 0
	v_cvt_pk_bf16_f32 v39, v134, v131
	s_nop 0
	s_nop 0
	s_nop 0
	s_nop 0
	s_nop 0
	v_cvt_pk_bf16_f32 v40, v40, v126
	s_nop 0
	s_nop 0
	s_nop 0
	s_nop 0
	s_nop 0
	v_cvt_pk_bf16_f32 v41, v128, v41
	s_nop 0
	s_nop 0
	s_nop 0
	s_nop 0
	s_nop 0
	v_cvt_pk_bf16_f32 v42, v44, v42
	s_nop 0
	s_nop 0
	s_nop 0
	s_nop 0
	s_nop 0
	v_cvt_pk_bf16_f32 v43, v45, v43
	s_nop 0
	s_nop 0
	s_nop 0
	s_nop 0
	s_nop 0
	v_cvt_pk_bf16_f32 v44, v46, v51
	s_nop 0
	s_nop 0
	s_nop 0
	s_nop 0
	s_nop 0
	v_cvt_pk_bf16_f32 v45, v56, v52
	s_nop 0
	s_nop 0
	s_nop 0
	s_nop 0
	s_nop 0
	v_cvt_pk_bf16_f32 v46, v55, v47
	s_nop 0
	s_nop 0
	s_nop 0
	s_nop 0
	s_nop 0
	v_cvt_pk_bf16_f32 v47, v57, v53
	s_nop 0
	s_nop 0
	s_nop 0
	s_nop 0
	s_nop 0
	v_cvt_pk_bf16_f32 v48, v48, v49
	s_nop 0
	s_nop 0
	s_nop 0
	s_nop 0
	s_nop 0
	v_cvt_pk_bf16_f32 v49, v54, v50
	s_nop 0
	s_nop 0
	s_nop 0
	s_nop 0
	s_nop 0
	v_cvt_pk_bf16_f32 v50, v124, v112
	s_nop 0
	s_nop 0
	s_nop 0
	s_nop 0
	s_nop 0
	v_cvt_pk_bf16_f32 v51, v141, v138
	s_nop 0
	s_nop 0
	s_nop 0
	s_nop 0
	s_nop 0
	v_cvt_pk_bf16_f32 v52, v140, v139
	s_nop 0
	s_nop 0
	s_nop 0
	s_nop 0
	s_nop 0
	v_cvt_pk_bf16_f32 v53, v136, v148
	s_nop 0
	s_nop 0
	s_nop 0
	s_nop 0
	s_nop 0
	v_cvt_pk_bf16_f32 v54, v145, v146
	s_nop 0
	s_nop 0
	s_nop 0
	s_nop 0
	s_nop 0
	v_cvt_pk_bf16_f32 v55, v137, v149
	s_nop 0
	s_nop 0
	s_nop 0
	s_nop 0
	s_nop 0
	v_cvt_pk_bf16_f32 v56, v135, v132
	s_nop 0
	s_nop 0
	s_nop 0
	s_nop 0
	s_nop 0
	v_cvt_pk_bf16_f32 v57, v144, v147
	s_nop 0
	s_nop 0
	s_nop 0
	s_nop 0
	s_nop 0
	v_cvt_pk_bf16_f32 v58, v59, v58
	s_nop 0
	s_nop 0
	s_nop 0
	s_nop 0
	s_nop 0
	v_cvt_pk_bf16_f32 v59, v61, v60
	s_nop 0
	s_nop 0
	s_nop 0
	s_nop 0
	s_nop 0
	v_cvt_pk_bf16_f32 v60, v63, v62
	s_nop 0
	s_nop 0
	s_nop 0
	s_nop 0
	s_nop 0
	v_cvt_pk_bf16_f32 v61, v125, v115
	s_nop 0
	s_nop 0
	s_nop 0
	s_nop 0
	s_nop 0
	v_cvt_pk_bf16_f32 v62, v113, v111
	s_nop 0
	s_nop 0
	s_nop 0
	s_nop 0
	s_nop 0
	v_cvt_pk_bf16_f32 v63, v109, v114
	s_nop 0
	s_nop 0
	s_nop 0
	s_nop 0
	s_nop 0
	v_cvt_pk_bf16_f32 v64, v65, v64
	s_nop 0
	s_nop 0
	s_nop 0
	s_nop 0
	s_nop 0
	v_cvt_pk_bf16_f32 v65, v108, v110
	s_nop 0
	s_nop 0
	s_nop 0
	s_nop 0
	s_nop 0
	v_cvt_pk_bf16_f32 v66, v67, v66
	s_nop 0
	s_nop 0
	s_nop 0
	s_nop 0
	s_nop 0
	v_cvt_pk_bf16_f32 v67, v69, v68
	s_nop 0
	s_nop 0
	s_nop 0
	s_nop 0
	s_nop 0
	v_cvt_pk_bf16_f32 v68, v71, v70
	s_nop 0
	s_nop 0
	s_nop 0
	s_nop 0
	s_nop 0
	v_cvt_pk_bf16_f32 v69, v106, v103
	s_nop 0
	s_nop 0
	s_nop 0
	s_nop 0
	s_nop 0
	v_cvt_pk_bf16_f32 v70, v104, v96
	s_nop 0
	s_nop 0
	s_nop 0
	s_nop 0
	s_nop 0
	v_cvt_pk_bf16_f32 v71, v107, v105
	s_nop 0
	s_nop 0
	s_nop 0
	s_nop 0
	s_nop 0
	v_cvt_pk_bf16_f32 v72, v72, v93
	s_nop 0
	s_nop 0
	s_nop 0
	s_nop 0
	s_nop 0
	v_cvt_pk_bf16_f32 v73, v102, v73
	s_nop 0
	s_nop 0
	s_nop 0
	s_nop 0
	s_nop 0
	v_cvt_pk_bf16_f32 v74, v76, v74
	s_nop 0
	s_nop 0
	s_nop 0
	s_nop 0
	s_nop 0
	v_cvt_pk_bf16_f32 v75, v77, v75
	s_nop 0
	s_nop 0
	s_nop 0
	s_nop 0
; #define LAS __attribute__((address_space(3)))
; __device__ __forceinline__ unsigned pk2(float lo, float hi) { return f2bf(lo) | (f2bf(hi) << 16); }
; __device__ __forceinline__ void phase_prep(const Args& A, const Ctx& C0, int l) {
;     ...
;                   for (int e = 0; e < 4; ++e) f.w[e] = pk2(p[(2 * e) * 512], p[(2 * e + 1) * 512]);
;                   wfr[mat][ct][ks] = f.v; } } }
;     LAS bf16* lob = (LAS bf16*)(C.lds + 9 * DSH * 4);
;     LAS float* outw = (LAS float*)(C.lds + 9 * DSH * 4 + 16 * 136 * 2);
;     LAS float* outa = outw + 8 * 512;
;     const float w0 = A.in[I_W0][l * 512 + c], a0 = A.in[I_A0][l * 512 + c], kkc = A.in[I_KK][l * 512 + c], kac = A.in[I_KA][l * 512 + c], rkc = A.in[I_RK][l * 512 + c];
;     const float* mul = A.in[I_MU] + (size_t)l * DSH;
;     const float mu_r = mul[c], mu_k = mul[512 + c], mu_v = mul[1024 + c];
;     v4u px[4];
;     ...
;     if (C.bid < M / 8) PREP_FETCH(C.bid);
	s_nop 0
	v_cvt_pk_bf16_f32 v76, v78, v86
	s_nop 0
	s_nop 0
	s_nop 0
	s_nop 0
	s_nop 0
	v_cvt_pk_bf16_f32 v77, v91, v87
	s_nop 0
	s_nop 0
	s_nop 0
	s_nop 0
	s_nop 0
	v_cvt_pk_bf16_f32 v78, v90, v79
	s_nop 0
	s_nop 0
	s_nop 0
	s_nop 0
	s_nop 0
	v_cvt_pk_bf16_f32 v79, v92, v88
	s_nop 0
	s_nop 0
	s_nop 0
	s_nop 0
	s_nop 0
	v_cvt_pk_bf16_f32 v80, v80, v81
	s_nop 0
	s_mov_b32 s11, 0x4ec4ec4f
	s_nop 0
	s_nop 0
	s_ashr_i32 s1, s9, 6
	v_mul_hi_i32 v92, v84, s11
	s_nop 0
	s_nop 0
	s_add_u32 s9, s42, 0x7984000
	s_mul_i32 s2, s1, 0x180
	v_lshrrev_b32_e32 v93, 31, v92
	v_ashrrev_i32_e32 v92, 6, v92
	v_cvt_pk_bf16_f32 v81, v89, v85
	s_addc_u32 s15, s43, 0
	v_and_b32_e32 v85, 0x7f, v94
	s_ashr_i32 s3, s2, 31
	v_add_u32_e32 v126, v92, v93
	v_add_u32_e32 v93, 0x600, v94
	v_lshlrev_b32_e32 v88, 2, v85
	s_lshl_b64 s[2:3], s[2:3], 2
	v_mul_hi_i32 v96, v93, s11
	v_or_b32_e32 v86, 0x1800, v88
	v_mov_b32_e32 v87, v1
	s_movk_i32 s13, 0x110
	s_add_u32 s2, s42, s2
	v_lshrrev_b32_e32 v112, 31, v96
	v_ashrrev_i32_e32 v96, 6, v96
	v_lshl_add_u64 v[102:103], s[38:39], 0, v[86:87]
	v_mad_u32_u24 v86, v83, s13, 0
	v_lshlrev_b32_e32 v89, 13, v82
	s_addc_u32 s3, s43, s3
	v_lshlrev_b32_e32 v82, 2, v166
	v_mov_b32_e32 v83, v1
	s_movk_i32 s12, 0xd0
	v_add_u32_e32 v127, v96, v112
	v_lshl_add_u64 v[82:83], s[2:3], 0, v[82:83]
	s_mov_b64 s[2:3], 0x256d7900
	v_mul_lo_u32 v96, v127, s12
	s_lshl_b32 s0, s0, 2
	v_lshl_add_u64 v[104:105], v[82:83], 0, s[2:3]
	s_movk_i32 s2, 0x680
	s_movk_i32 s14, 0x19f
	s_movk_i32 s3, 0x1a00
	v_sub_u32_e32 v93, v93, v96
	v_add_u32_e32 v96, 0x6cf, v94
	s_add_i32 s0, s0, 0
	v_cmp_gt_i32_e64 s[44:45], s2, v94
	s_movk_i32 s2, 0x74f
	v_cmp_gt_u32_e64 s[68:69], s14, v96
	v_mul_lo_u32 v96, v127, s3
	v_add3_u32 v130, s0, v89, v0
	s_add_i32 s0, s0, 0x13b00
	v_cmp_lt_i32_e64 s[46:47], s2, v94
	s_movk_i32 s2, 0x750
	v_add_u32_e32 v115, 0, v96
	v_ashrrev_i32_e32 v96, 7, v94
	v_add3_u32 v0, s0, v89, v0
	v_max_i32_e32 v89, 0x480, v94
	v_mul_hi_i32 v82, v94, s11
	v_cmp_gt_i32_e64 s[48:49], s2, v94
	v_mul_hi_i32 v90, v97, s11
	s_movk_i32 s2, 0x54f
	v_mul_lo_u32 v114, v96, s3
	v_mul_lo_u32 v139, v96, s13
	v_ashrrev_i32_e32 v96, 7, v97
	v_sub_u32_e32 v89, v89, v94
	v_lshrrev_b32_e32 v83, 31, v82
	v_ashrrev_i32_e32 v82, 6, v82
	v_lshrrev_b32_e32 v91, 31, v90
	v_ashrrev_i32_e32 v90, 6, v90
	v_cmp_lt_i32_e64 s[52:53], s2, v94
	s_movk_i32 s2, 0x550
	v_add3_u32 v128, 0, v114, v88
	v_mul_lo_u32 v114, v96, s3
	v_add_u32_e32 v89, 0x1ff, v89
	v_add_u32_e32 v124, v82, v83
	v_add_u32_e32 v125, v90, v91
	v_cmp_gt_i32_e64 s[54:55], s2, v94
	v_mul_lo_u32 v92, v126, s12
	s_movk_i32 s2, 0x34f
	v_add3_u32 v129, 0, v114, v88
	v_mul_lo_u32 v88, v96, s13
	v_lshrrev_b32_e32 v96, 9, v89
	v_mul_lo_u32 v82, v124, s12
	v_add_u32_e32 v83, 0xcf, v94
	v_mul_lo_u32 v90, v125, s12
	v_add_u32_e32 v91, 0x2cf, v94
	v_sub_u32_e32 v84, v84, v92
	v_cmp_lt_i32_e64 s[58:59], s2, v94
	s_movk_i32 s2, 0x350
	v_add_u32_e32 v92, 0x4cf, v94
	v_add_u32_e32 v133, 1, v96
	s_movk_i32 s0, 0x1ff
	v_sub_u32_e32 v82, v94, v82
	v_cmp_gt_u32_e64 s[50:51], s14, v83
	v_mul_lo_u32 v83, v124, s3
	v_sub_u32_e32 v90, v97, v90
	v_cmp_gt_u32_e64 s[56:57], s14, v91
	v_mul_lo_u32 v91, v125, s3
	v_cmp_gt_i32_e64 s[60:61], s2, v94
	v_cmp_gt_u32_e64 s[62:63], s14, v92
	v_mul_lo_u32 v92, v126, s3
	s_movk_i32 s2, 0x14f
	v_cmp_lt_u32_e64 s[70:71], s0, v89
	v_and_b32_e32 v132, 0xfffffe, v133
	s_lshl_b32 s0, s8, 6
	v_cmp_gt_u32_e64 s[38:39], 64, v85
	v_lshl_add_u32 v85, v85, 1, 0
	v_and_b32_e32 v87, 48, v94
	v_lshlrev_b32_e32 v106, 3, v82
	v_add_u32_e32 v83, 0, v83
	v_lshlrev_b32_e32 v82, 5, v82
	v_lshlrev_b32_e32 v108, 3, v90
	v_add_u32_e32 v91, 0, v91
	v_lshlrev_b32_e32 v90, 5, v90
	v_lshlrev_b32_e32 v110, 3, v84
	v_add_u32_e32 v92, 0, v92
	v_lshlrev_b32_e32 v84, 5, v84
	v_cmp_lt_i32_e64 s[64:65], s2, v94
	s_movk_i32 s2, 0x150
	v_lshlrev_b32_e32 v112, 3, v93
	v_lshlrev_b32_e32 v93, 5, v93
	v_cmp_ne_u32_e64 s[26:27], v133, v132
	v_lshlrev_b32_e32 v133, 2, v94
	s_add_i32 s19, s1, s0
	v_readlane_b32 s0, v254, 60
	v_cmp_gt_u32_e64 s[40:41], 32, v166
	v_cmp_eq_u32_e64 s[42:43], 0, v166
	v_ashrrev_i32_e32 v107, 31, v106
	v_ashrrev_i32_e32 v109, 31, v108
	v_ashrrev_i32_e32 v111, 31, v110
	v_cmp_gt_i32_e64 s[66:67], s2, v94
	v_ashrrev_i32_e32 v113, 31, v112
	v_add_u32_e32 v131, 0xfb00, v130
	v_lshl_add_u32 v114, v132, 9, v94
	v_mov_b32_e32 v96, v94
	s_lshl_b32 s12, s10, 6
	s_lshl_b32 s18, s8, 3
	s_lshl_b32 s14, s10, 3
	v_add_u32_e32 v134, s0, v133
	v_add_u32_e32 v135, v83, v82
	v_add_u32_e32 v136, v91, v90
	v_add_u32_e32 v137, v92, v84
	v_add_u32_e32 v138, v115, v93
	v_add_u32_e32 v139, v85, v139
	v_add_u32_e32 v140, v85, v88
	v_add_u32_e32 v141, v86, v87
	s_mov_b32 s16, s8
	global_load_dword v168, v[102:103], off
	s_waitcnt vmcnt(0)
	s_branch .LBB0_46

; __device__ __forceinline__ unsigned pk2(float lo, float hi) { return f2bf(lo) | (f2bf(hi) << 16); }
; __device__ __forceinline__ void pool_item(const Args& A, const Ctx& C0, int l, int row0, int t0, int pos0, const float* hist, float* outpool) {
;     ...
;         for (int it = 0; it < 6; ++it) { const int idx = C.tid + 512 * it; const int rr = idx >> 6, v = idx & 63;
;             xs[it] = (v4u){0u, 0u, 0u, 0u};
;             if (idx < 47 * 64) {
;                 if (rr < 15 && t0 == 0) { if (hist) { const f32x4 a0 = *(const f32x4*)(hist + rr * 512 + v * 8), a1 = *(const f32x4*)(hist + rr * 512 + v * 8 + 4);
;                         xs[it] = (v4u){pk2(a0.x, a0.y), pk2(a0.z, a0.w), pk2(a1.x, a1.y), pk2(a1.z, a1.w)}; } }
;                 else xs[it] = *(const v4u*)(U + (size_t)(row0 - 15 + rr) * DIN + C_P + v * 8); } }
.LBB0_202:
	s_andn2_saveexec_b64 s[30:31], s[2:3]
	s_cbranch_execz .LBB0_206
	s_andn2_b64 vcc, exec, s[62:63]
	s_cbranch_vccnz .LBB0_205
	v_lshlrev_b32_e32 v4, 9, v30
	v_ashrrev_i32_e32 v5, 31, v4
	s_waitcnt vmcnt(0) lgkmcnt(0)
	v_lshl_add_u64 v[8:9], v[4:5], 2, v[26:27]
	global_load_dwordx4 v[4:7], v[8:9], off
	s_nop 0
	global_load_dwordx4 v[8:11], v[8:9], off offset:16
	s_waitcnt vmcnt(1)
	s_nop 0
	s_nop 0
	s_nop 0
	s_nop 0
	s_waitcnt vmcnt(0)
	s_nop 0
	s_nop 0
	s_nop 0
	s_nop 0
	s_nop 0
	s_nop 0
	s_nop 0
	s_nop 0
	s_nop 0
	s_nop 0
	s_nop 0
	v_cvt_pk_bf16_f32 v8, v8, v9
	s_nop 0
	s_nop 0
	s_nop 0
	s_nop 0
	s_nop 0
	v_cvt_pk_bf16_f32 v7, v6, v7
	v_cvt_pk_bf16_f32 v6, v4, v5
	s_nop 0
	s_nop 0
	v_cvt_pk_bf16_f32 v9, v10, v11
	s_branch .LBB0_206

; __device__ __forceinline__ unsigned pk2(float lo, float hi) { return f2bf(lo) | (f2bf(hi) << 16); }
; __device__ __forceinline__ void pool_item(const Args& A, const Ctx& C0, int l, int row0, int t0, int pos0, const float* hist, float* outpool) {
;     ...
;         for (int it = 0; it < 6; ++it) { const int idx = C.tid + 512 * it; const int rr = idx >> 6, v = idx & 63;
;             xs[it] = (v4u){0u, 0u, 0u, 0u};
;             if (idx < 47 * 64) {
;                 if (rr < 15 && t0 == 0) { if (hist) { const f32x4 a0 = *(const f32x4*)(hist + rr * 512 + v * 8), a1 = *(const f32x4*)(hist + rr * 512 + v * 8 + 4);
;                         xs[it] = (v4u){pk2(a0.x, a0.y), pk2(a0.z, a0.w), pk2(a1.x, a1.y), pk2(a1.z, a1.w)}; } }
;                 else xs[it] = *(const v4u*)(U + (size_t)(row0 - 15 + rr) * DIN + C_P + v * 8); } }
.LBB0_210:
	s_andn2_saveexec_b64 s[30:31], s[2:3]
	s_cbranch_execz .LBB0_214
	s_andn2_b64 vcc, exec, s[62:63]
	s_cbranch_vccnz .LBB0_213
	v_lshlrev_b32_e32 v4, 9, v32
	v_ashrrev_i32_e32 v5, 31, v4
	v_lshl_add_u64 v[4:5], v[4:5], 2, v[26:27]
	s_waitcnt lgkmcnt(0)
	global_load_dwordx4 v[10:13], v[4:5], off
	global_load_dwordx4 v[14:17], v[4:5], off offset:16
	s_waitcnt vmcnt(0)
	s_nop 0
	s_nop 0
	s_nop 0
	s_nop 0
	s_nop 0
	s_nop 0
	s_nop 0
	s_nop 0
	s_nop 0
	s_nop 0
	s_nop 0
	s_nop 0
	v_cvt_pk_bf16_f32 v10, v10, v11
	s_nop 0
	s_nop 0
	s_nop 0
	s_nop 0
	s_nop 0
	s_nop 0
	s_nop 0
	v_cvt_pk_bf16_f32 v11, v12, v13
	v_cvt_pk_bf16_f32 v12, v14, v15
	s_nop 0
	s_nop 0
	s_nop 0
	s_nop 0
	v_cvt_pk_bf16_f32 v13, v16, v17
	s_branch .LBB0_214

; __device__ __forceinline__ unsigned pk2(float lo, float hi) { return f2bf(lo) | (f2bf(hi) << 16); }
; __device__ __forceinline__ void pool_item(const Args& A, const Ctx& C0, int l, int row0, int t0, int pos0, const float* hist, float* outpool) {
;     ...
;         for (int it = 0; it < 6; ++it) { const int idx = C.tid + 512 * it; const int rr = idx >> 6, v = idx & 63;
;             xs[it] = (v4u){0u, 0u, 0u, 0u};
;             if (idx < 47 * 64) {
;                 if (rr < 15 && t0 == 0) { if (hist) { const f32x4 a0 = *(const f32x4*)(hist + rr * 512 + v * 8), a1 = *(const f32x4*)(hist + rr * 512 + v * 8 + 4);
;                         xs[it] = (v4u){pk2(a0.x, a0.y), pk2(a0.z, a0.w), pk2(a1.x, a1.y), pk2(a1.z, a1.w)}; } }
;                 else xs[it] = *(const v4u*)(U + (size_t)(row0 - 15 + rr) * DIN + C_P + v * 8); } }
.LBB0_218:
	s_andn2_saveexec_b64 s[30:31], s[2:3]
	s_cbranch_execz .LBB0_222
	s_andn2_b64 vcc, exec, s[62:63]
	s_cbranch_vccnz .LBB0_221
	s_waitcnt vmcnt(0) lgkmcnt(0)
	v_lshlrev_b32_e32 v2, 9, v33
	v_ashrrev_i32_e32 v3, 31, v2
	v_lshl_add_u64 v[14:15], v[2:3], 2, v[26:27]
	global_load_dwordx4 v[2:5], v[14:15], off
	s_nop 0
	global_load_dwordx4 v[14:17], v[14:15], off offset:16
	s_waitcnt vmcnt(1)
	s_nop 0
	s_nop 0
	s_nop 0
	s_nop 0
	s_waitcnt vmcnt(0)
	s_nop 0
	s_nop 0
	s_nop 0
	s_nop 0
	s_nop 0
	s_nop 0
	v_cvt_pk_bf16_f32 v2, v2, v3
	s_nop 0
	s_nop 0
	v_cvt_pk_bf16_f32 v3, v4, v5
	s_nop 0
	s_nop 0
	v_cvt_pk_bf16_f32 v4, v14, v15
	s_nop 0
	s_nop 0
	s_nop 0
	s_nop 0
	s_nop 0
	s_nop 0
	s_nop 0
	s_nop 0
	s_nop 0
	v_cvt_pk_bf16_f32 v5, v16, v17
	s_branch .LBB0_222

; __device__ __forceinline__ unsigned pk2(float lo, float hi) { return f2bf(lo) | (f2bf(hi) << 16); }
; __device__ __forceinline__ void pool_item(const Args& A, const Ctx& C0, int l, int row0, int t0, int pos0, const float* hist, float* outpool) {
;     ...
;         for (int it = 0; it < 6; ++it) { const int idx = C.tid + 512 * it; const int rr = idx >> 6, v = idx & 63;
;             xs[it] = (v4u){0u, 0u, 0u, 0u};
;             if (idx < 47 * 64) {
;                 if (rr < 15 && t0 == 0) { if (hist) { const f32x4 a0 = *(const f32x4*)(hist + rr * 512 + v * 8), a1 = *(const f32x4*)(hist + rr * 512 + v * 8 + 4);
;                         xs[it] = (v4u){pk2(a0.x, a0.y), pk2(a0.z, a0.w), pk2(a1.x, a1.y), pk2(a1.z, a1.w)}; } }
;                 else xs[it] = *(const v4u*)(U + (size_t)(row0 - 15 + rr) * DIN + C_P + v * 8); } }
.LBB0_226:
	s_andn2_saveexec_b64 s[36:37], s[2:3]
	s_cbranch_execz .LBB0_230
	s_andn2_b64 vcc, exec, s[62:63]
	s_cbranch_vccnz .LBB0_229
	v_lshlrev_b32_e32 v16, 9, v36
	v_ashrrev_i32_e32 v17, 31, v16
	s_waitcnt vmcnt(0) lgkmcnt(0)
	v_lshl_add_u64 v[20:21], v[16:17], 2, v[26:27]
	global_load_dwordx4 v[16:19], v[20:21], off
	s_nop 0
	global_load_dwordx4 v[20:23], v[20:21], off offset:16
	s_waitcnt vmcnt(1)
	s_nop 0
	s_nop 0
	s_nop 0
	s_nop 0
	s_waitcnt vmcnt(0)
	s_nop 0
	s_nop 0
	s_nop 0
	s_nop 0
	s_nop 0
	s_nop 0
	s_nop 0
	s_nop 0
	s_nop 0
	s_nop 0
	s_nop 0
	v_cvt_pk_bf16_f32 v20, v20, v21
	s_nop 0
	s_nop 0
	s_nop 0
	s_nop 0
	s_nop 0
	v_cvt_pk_bf16_f32 v19, v18, v19
	v_cvt_pk_bf16_f32 v18, v16, v17
	s_nop 0
	s_nop 0
	v_cvt_pk_bf16_f32 v21, v22, v23
	s_branch .LBB0_230

; __device__ __forceinline__ unsigned pk2(float lo, float hi) { return f2bf(lo) | (f2bf(hi) << 16); }
; __device__ __forceinline__ void pool_item(const Args& A, const Ctx& C0, int l, int row0, int t0, int pos0, const float* hist, float* outpool) {
;     ...
;         for (int it = 0; it < 6; ++it) { const int idx = C.tid + 512 * it; const int rr = idx >> 6, v = idx & 63;
;             xs[it] = (v4u){0u, 0u, 0u, 0u};
;             if (idx < 47 * 64) {
;                 if (rr < 15 && t0 == 0) { if (hist) { const f32x4 a0 = *(const f32x4*)(hist + rr * 512 + v * 8), a1 = *(const f32x4*)(hist + rr * 512 + v * 8 + 4);
;                         xs[it] = (v4u){pk2(a0.x, a0.y), pk2(a0.z, a0.w), pk2(a1.x, a1.y), pk2(a1.z, a1.w)}; } }
;                 else xs[it] = *(const v4u*)(U + (size_t)(row0 - 15 + rr) * DIN + C_P + v * 8); } }
.LBB0_234:
	s_andn2_saveexec_b64 s[36:37], s[2:3]
	s_cbranch_execz .LBB0_238
	s_andn2_b64 vcc, exec, s[62:63]
	s_cbranch_vccnz .LBB0_237
	s_waitcnt vmcnt(0) lgkmcnt(0)
	v_lshlrev_b32_e32 v14, 9, v37
	v_ashrrev_i32_e32 v15, 31, v14
	v_lshl_add_u64 v[22:23], v[14:15], 2, v[26:27]
	global_load_dwordx4 v[14:17], v[22:23], off
	s_nop 0
	global_load_dwordx4 v[22:25], v[22:23], off offset:16
	s_waitcnt vmcnt(1)
	s_nop 0
	s_nop 0
	s_nop 0
	s_nop 0
	s_waitcnt vmcnt(0)
	s_nop 0
	s_nop 0
	s_nop 0
	s_nop 0
	s_nop 0
	s_nop 0
	v_cvt_pk_bf16_f32 v14, v14, v15
	s_nop 0
	s_nop 0
	v_cvt_pk_bf16_f32 v15, v16, v17
	s_nop 0
	s_nop 0
	v_cvt_pk_bf16_f32 v16, v22, v23
	s_nop 0
	s_nop 0
	s_nop 0
	s_nop 0
	s_nop 0
	s_nop 0
	s_nop 0
	s_nop 0
	s_nop 0
	v_cvt_pk_bf16_f32 v17, v24, v25
	s_branch .LBB0_238

; __device__ __forceinline__ unsigned pk2(float lo, float hi) { return f2bf(lo) | (f2bf(hi) << 16); }
; __device__ __forceinline__ void pool_item(const Args& A, const Ctx& C0, int l, int row0, int t0, int pos0, const float* hist, float* outpool) {
;     ...
;         for (int it = 0; it < 6; ++it) { const int idx = C.tid + 512 * it; const int rr = idx >> 6, v = idx & 63;
;             xs[it] = (v4u){0u, 0u, 0u, 0u};
;             if (idx < 47 * 64) {
;                 if (rr < 15 && t0 == 0) { if (hist) { const f32x4 a0 = *(const f32x4*)(hist + rr * 512 + v * 8), a1 = *(const f32x4*)(hist + rr * 512 + v * 8 + 4);
;                         xs[it] = (v4u){pk2(a0.x, a0.y), pk2(a0.z, a0.w), pk2(a1.x, a1.y), pk2(a1.z, a1.w)}; } }
;                 else xs[it] = *(const v4u*)(U + (size_t)(row0 - 15 + rr) * DIN + C_P + v * 8); } }
.LBB0_295:
	s_andn2_saveexec_b64 s[64:65], s[2:3]
	s_cbranch_execz .LBB0_669
	s_andn2_b64 vcc, exec, s[62:63]
	s_cbranch_vccnz .LBB0_668
	s_waitcnt vmcnt(0) lgkmcnt(0)
	v_lshlrev_b32_e32 v22, 9, v38
	v_ashrrev_i32_e32 v23, 31, v22
	v_lshl_add_u64 v[22:23], v[22:23], 2, v[26:27]
	global_load_dwordx4 v[24:27], v[22:23], off offset:16
	global_load_dwordx4 v[40:43], v[22:23], off
	s_waitcnt vmcnt(0)
	s_nop 0
	s_nop 0
	s_nop 0
	s_nop 0
	s_nop 0
	v_cvt_pk_bf16_f32 v22, v40, v41
	s_nop 0
	s_nop 0
	s_nop 0
	s_nop 0
	s_nop 0
	v_cvt_pk_bf16_f32 v23, v42, v43
	s_nop 0
	s_nop 0
	s_nop 0
	s_nop 0
	s_nop 0
	v_cvt_pk_bf16_f32 v24, v24, v25
	s_nop 0
	s_nop 0
	s_nop 0
	s_nop 0
	s_nop 0
	v_cvt_pk_bf16_f32 v25, v26, v27
	s_branch .LBB0_669

; __device__ __forceinline__ unsigned pk2(float lo, float hi) { return f2bf(lo) | (f2bf(hi) << 16); }
; __device__ __forceinline__ void attn_unit(const Args& A, const Ctx& C0, int l, int u_qrow0, int u_nq, int u_krow0, int u_krow1, int u_krow2, int u_g, const float* u_ck, const float* u_cv, unsigned u_vmask) {
;     ...
;         for (int it = 0; it < 3; ++it) { const int idx = C.tid + 512 * it; const int j = idx >> 3, part = idx & 7;
;             kx[it] = (v4u){0u, 0u, 0u, 0u}; vx[it] = kx[it];
;             if ((u.vmask >> (j >> 5)) & 1u) {
;                 if (u.ck && j < 128) { const float* pk = u.ck + (size_t)j * 128 + part * 8; const float* pv = u.cv + (size_t)j * 128 + part * 8;
;                     const f32x4 a0 = *(const f32x4*)pk, a1 = *(const f32x4*)(pk + 4), b0 = *(const f32x4*)pv, b1 = *(const f32x4*)(pv + 4);
;                     kx[it] = (v4u){pk2(a0.x, a0.y), pk2(a0.z, a0.w), pk2(a1.x, a1.y), pk2(a1.z, a1.w)}; vx[it] = (v4u){pk2(b0.x, b0.y), pk2(b0.z, b0.w), pk2(b1.x, b1.y), pk2(b1.z, b1.w)}; }
;                 else { const int ch = j >> 6; const int kr = (ch == 0 ? u.krow0 : (ch == 1 ? u.krow1 : u.krow2)) + (j & 63);
;                     kx[it] = *(const v4u*)(U + (size_t)kr * DIN + C_K + u.g * 64 + part * 8); vx[it] = *(const v4u*)(U + (size_t)kr * DIN + C_V + u.g * 64 + part * 8); }
;             } }
.LBB0_304:
	s_andn2_saveexec_b64 s[42:43], s[30:31]
	s_cbranch_execz .LBB0_306
	v_ashrrev_i32_e32 v31, 31, v30
	s_waitcnt vmcnt(0) lgkmcnt(0)
	v_lshlrev_b64 v[2:3], 9, v[30:31]
	v_lshl_add_u64 v[4:5], v[34:35], 0, v[2:3]
	v_lshl_add_u64 v[16:17], v[32:33], 0, v[2:3]
	global_load_dwordx4 v[8:11], v[4:5], off offset:16
	s_nop 0
	global_load_dwordx4 v[2:5], v[4:5], off
	s_nop 0
	global_load_dwordx4 v[12:15], v[16:17], off offset:16
	global_load_dwordx4 v[22:25], v[16:17], off
	s_waitcnt vmcnt(2)
	s_nop 0
	s_nop 0
	s_nop 0
	s_nop 0
	s_nop 0
	v_cvt_pk_bf16_f32 v2, v2, v3
	s_nop 0
	s_nop 0
	s_nop 0
	s_nop 0
	s_nop 0
	v_cvt_pk_bf16_f32 v3, v4, v5
	s_nop 0
	s_nop 0
	s_nop 0
	s_nop 0
	s_nop 0
	v_cvt_pk_bf16_f32 v4, v8, v9
	s_nop 0
	s_nop 0
	s_nop 0
	s_nop 0
	s_nop 0
	v_cvt_pk_bf16_f32 v5, v10, v11
	s_waitcnt vmcnt(0)
	s_nop 0
	s_nop 0
	s_nop 0
	s_nop 0
	s_nop 0
	v_cvt_pk_bf16_f32 v10, v22, v23
	s_nop 0
	s_nop 0
	s_nop 0
	s_nop 0
	s_nop 0
	v_cvt_pk_bf16_f32 v11, v24, v25
	s_nop 0
	s_nop 0
	s_nop 0
	s_nop 0
	s_nop 0
	v_cvt_pk_bf16_f32 v12, v12, v13
	s_nop 0
	s_nop 0
	s_nop 0
	s_nop 0
	s_nop 0
	v_cvt_pk_bf16_f32 v13, v14, v15

; __device__ __forceinline__ unsigned pk2(float lo, float hi) { return f2bf(lo) | (f2bf(hi) << 16); }
; __device__ __forceinline__ void attn_unit(const Args& A, const Ctx& C0, int l, int u_qrow0, int u_nq, int u_krow0, int u_krow1, int u_krow2, int u_g, const float* u_ck, const float* u_cv, unsigned u_vmask) {
;     ...
;         for (int it = 0; it < 3; ++it) { const int idx = C.tid + 512 * it; const int j = idx >> 3, part = idx & 7;
;             kx[it] = (v4u){0u, 0u, 0u, 0u}; vx[it] = kx[it];
;             if ((u.vmask >> (j >> 5)) & 1u) {
;                 if (u.ck && j < 128) { const float* pk = u.ck + (size_t)j * 128 + part * 8; const float* pv = u.cv + (size_t)j * 128 + part * 8;
;                     const f32x4 a0 = *(const f32x4*)pk, a1 = *(const f32x4*)(pk + 4), b0 = *(const f32x4*)pv, b1 = *(const f32x4*)(pv + 4);
;                     kx[it] = (v4u){pk2(a0.x, a0.y), pk2(a0.z, a0.w), pk2(a1.x, a1.y), pk2(a1.z, a1.w)}; vx[it] = (v4u){pk2(b0.x, b0.y), pk2(b0.z, b0.w), pk2(b1.x, b1.y), pk2(b1.z, b1.w)}; }
;                 else { const int ch = j >> 6; const int kr = (ch == 0 ? u.krow0 : (ch == 1 ? u.krow1 : u.krow2)) + (j & 63);
;                     kx[it] = *(const v4u*)(U + (size_t)kr * DIN + C_K + u.g * 64 + part * 8); vx[it] = *(const v4u*)(U + (size_t)kr * DIN + C_V + u.g * 64 + part * 8); }
;             } }
.LBB0_310:
	s_andn2_saveexec_b64 s[30:31], s[30:31]
	s_cbranch_execz .LBB0_312
	v_ashrrev_i32_e32 v37, 31, v36
	v_lshlrev_b64 v[8:9], 9, v[36:37]
	s_waitcnt vmcnt(0) lgkmcnt(0)
	v_lshl_add_u64 v[22:23], v[34:35], 0, v[8:9]
	v_lshl_add_u64 v[8:9], v[32:33], 0, v[8:9]
	global_load_dwordx4 v[14:17], v[22:23], off
	s_nop 0
	global_load_dwordx4 v[22:25], v[22:23], off offset:16
	s_nop 0
	global_load_dwordx4 v[26:29], v[8:9], off
	global_load_dwordx4 v[42:45], v[8:9], off offset:16
	s_waitcnt vmcnt(3)
	s_nop 0
	s_nop 0
	s_nop 0
	s_nop 0
	s_waitcnt vmcnt(2)
	s_nop 0
	s_nop 0
	s_nop 0
	s_waitcnt vmcnt(1)
	s_nop 0
	s_nop 0
	s_waitcnt vmcnt(0)
	s_nop 0
	s_nop 0
	s_nop 0
	s_nop 0
	s_nop 0
	s_nop 0
	s_nop 0
	s_nop 0
	s_nop 0
	s_nop 0
	s_nop 0
	s_nop 0
	s_nop 0
	s_nop 0
	s_nop 0
	v_cvt_pk_bf16_f32 v25, v24, v25
	s_nop 0
	s_nop 0
	s_nop 0
	s_nop 0
	s_nop 0
	s_nop 0
	s_nop 0
	s_nop 0
	s_nop 0
	s_nop 0
	s_nop 0
	s_nop 0
	s_nop 0
	s_nop 0
	s_nop 0
	s_nop 0
	v_cvt_pk_bf16_f32 v24, v22, v23
	v_cvt_pk_bf16_f32 v22, v14, v15
	v_cvt_pk_bf16_f32 v23, v16, v17
	s_nop 0
	s_nop 0
	v_cvt_pk_bf16_f32 v14, v26, v27
	v_cvt_pk_bf16_f32 v15, v28, v29
	v_cvt_pk_bf16_f32 v16, v42, v43
	v_cvt_pk_bf16_f32 v17, v44, v45

; __device__ __forceinline__ unsigned pk2(float lo, float hi) { return f2bf(lo) | (f2bf(hi) << 16); }
; __device__ __forceinline__ void attn_unit(const Args& A, const Ctx& C0, int l, int u_qrow0, int u_nq, int u_krow0, int u_krow1, int u_krow2, int u_g, const float* u_ck, const float* u_cv, unsigned u_vmask) {
;     ...
;         for (int it = 0; it < 3; ++it) { const int idx = C.tid + 512 * it; const int j = idx >> 3, part = idx & 7;
;             kx[it] = (v4u){0u, 0u, 0u, 0u}; vx[it] = kx[it];
;             if ((u.vmask >> (j >> 5)) & 1u) {
;                 if (u.ck && j < 128) { const float* pk = u.ck + (size_t)j * 128 + part * 8; const float* pv = u.cv + (size_t)j * 128 + part * 8;
;                     const f32x4 a0 = *(const f32x4*)pk, a1 = *(const f32x4*)(pk + 4), b0 = *(const f32x4*)pv, b1 = *(const f32x4*)(pv + 4);
;                     kx[it] = (v4u){pk2(a0.x, a0.y), pk2(a0.z, a0.w), pk2(a1.x, a1.y), pk2(a1.z, a1.w)}; vx[it] = (v4u){pk2(b0.x, b0.y), pk2(b0.z, b0.w), pk2(b1.x, b1.y), pk2(b1.z, b1.w)}; }
;                 else { const int ch = j >> 6; const int kr = (ch == 0 ? u.krow0 : (ch == 1 ? u.krow1 : u.krow2)) + (j & 63);
;                     kx[it] = *(const v4u*)(U + (size_t)kr * DIN + C_K + u.g * 64 + part * 8); vx[it] = *(const v4u*)(U + (size_t)kr * DIN + C_V + u.g * 64 + part * 8); }
;             } }
.LBB0_316:
	s_andn2_saveexec_b64 s[24:25], s[30:31]
	s_cbranch_execz .LBB0_318
	v_ashrrev_i32_e32 v39, 31, v38
	v_lshlrev_b64 v[42:43], 9, v[38:39]
	s_waitcnt vmcnt(0) lgkmcnt(0)
	v_lshl_add_u64 v[26:27], v[34:35], 0, v[42:43]
	v_lshl_add_u64 v[42:43], v[32:33], 0, v[42:43]
	global_load_dwordx4 v[6:9], v[26:27], off
	s_nop 0
	global_load_dwordx4 v[26:29], v[26:27], off offset:16
	s_nop 0
	global_load_dwordx4 v[32:35], v[42:43], off
	s_nop 0
	global_load_dwordx4 v[42:45], v[42:43], off offset:16
	s_waitcnt vmcnt(3)
	s_nop 0
	s_nop 0
	s_waitcnt vmcnt(2)
	s_nop 0
	s_nop 0
	s_waitcnt vmcnt(1)
	s_nop 0
	s_nop 0
	s_nop 0
	s_nop 0
	s_waitcnt vmcnt(0)
	s_nop 0
	s_nop 0
	s_nop 0
	s_nop 0
	s_nop 0
	s_nop 0
	s_nop 0
	s_nop 0
	s_nop 0
	s_nop 0
	s_nop 0
	s_nop 0
	s_nop 0
	s_nop 0
	s_nop 0
	s_nop 0
	s_nop 0
	s_nop 0
	s_nop 0
	s_nop 0
	s_nop 0
	s_nop 0
	s_nop 0
	s_nop 0
	s_nop 0
	s_nop 0
	s_nop 0
	s_nop 0
	s_nop 0
	s_nop 0
	s_nop 0
	s_nop 0
	v_cvt_pk_bf16_f32 v6, v6, v7
	v_cvt_pk_bf16_f32 v7, v8, v9
	v_cvt_pk_bf16_f32 v8, v26, v27
	v_cvt_pk_bf16_f32 v9, v28, v29
	v_cvt_pk_bf16_f32 v26, v32, v33
	v_cvt_pk_bf16_f32 v27, v34, v35
	v_cvt_pk_bf16_f32 v28, v42, v43
	v_cvt_pk_bf16_f32 v29, v44, v45

; __device__ __forceinline__ float shflx(float v, int mask, int lane) { return __int_as_float(__builtin_amdgcn_ds_bpermute((lane ^ mask) << 2, __float_as_int(v))); }
; __device__ __forceinline__ void attn_unit(const Args& A, const Ctx& C0, int l, int u_qrow0, int u_nq, int u_krow0, int u_krow1, int u_krow2, int u_g, const float* u_ck, const float* u_cv, unsigned u_vmask) {
;     ...
;         float mx = sink;
; #pragma unroll
;         for (int kt = 0; kt < 6; ++kt) { const bool valid = (u.vmask >> kt) & 1u;
; #pragma unroll
;             for (int r = 0; r < 16; ++r) { const int j = kt * 32 + (r & 3) + 8 * (r >> 2) + 4 * h;
;                 const float lg = valid ? sacc[kt][r] * 0.125f + bL[j - qi + 63] : -1e30f; sacc[kt][r] = lg; mx = fmaxf(mx, lg); }
;             asm volatile("" ::: "memory"); }
;         mx = fmaxf(mx, shflx(mx, 32, C.lane));
;         float sum = 0.f;
; #pragma unroll
;         for (int kt = 0; kt < 6; ++kt)
; #pragma unroll
;             for (int r = 0; r < 16; ++r) { const float e = __expf(sacc[kt][r] - mx); sacc[kt][r] = e; sum += e; }
;         sum += shflx(sum, 32, C.lane); sum += __expf(sink - mx);
.LBB0_404:
	s_waitcnt vmcnt(0)
	v_max3_f32 v18, v186, v123, v122
	v_max3_f32 v18, v18, v83, v82
	v_max3_f32 v18, v18, v85, v84
	v_max3_f32 v18, v18, v87, v86
	v_max3_f32 v18, v18, v89, v88
	v_max3_f32 v18, v18, v91, v90
	v_max3_f32 v18, v18, v93, v92
	v_max3_f32 v18, v18, v95, v94
	v_max3_f32 v18, v18, v97, v96
	v_max3_f32 v18, v18, v67, v66
	v_max3_f32 v18, v18, v69, v68
	v_max3_f32 v18, v18, v71, v70
	v_max3_f32 v18, v18, v73, v72
	v_max3_f32 v18, v18, v75, v74
	v_max3_f32 v18, v18, v77, v76
	v_max3_f32 v18, v18, v79, v78
	v_max3_f32 v18, v18, v81, v80
	v_max3_f32 v18, v18, v119, v118
	v_max3_f32 v18, v18, v53, v52
	v_max3_f32 v18, v18, v55, v54
	v_max3_f32 v18, v18, v57, v56
	v_max3_f32 v18, v18, v59, v58
	v_max3_f32 v18, v18, v61, v60
	v_max3_f32 v18, v18, v63, v62
	v_max3_f32 v18, v18, v65, v64
	v_max3_f32 v18, v18, v121, v120
	v_max3_f32 v18, v18, v125, v124
	v_max3_f32 v18, v18, v127, v126
	v_max3_f32 v18, v18, v194, v192
	v_max3_f32 v18, v18, v197, v196
	v_max3_f32 v18, v18, v201, v199
	v_max3_f32 v18, v18, v205, v204
	s_waitcnt lgkmcnt(7)
	v_fmamk_f32 v48, v2, 0x3e000000, v48
	v_fmac_f32_e32 v49, 0x3e000000, v3
	v_max3_f32 v2, v18, v48, v49
	s_waitcnt lgkmcnt(6)
	v_fmamk_f32 v46, v4, 0x3e000000, v46
	v_fmac_f32_e32 v47, 0x3e000000, v5
	v_max3_f32 v2, v2, v46, v47
	s_waitcnt lgkmcnt(5)
	v_fmamk_f32 v44, v6, 0x3e000000, v44
	v_fmac_f32_e32 v45, 0x3e000000, v7
	v_max3_f32 v2, v2, v44, v45
	s_waitcnt lgkmcnt(4)
	v_fmamk_f32 v42, v8, 0x3e000000, v42
	v_fmac_f32_e32 v43, 0x3e000000, v9
	v_max3_f32 v2, v2, v42, v43
	s_waitcnt lgkmcnt(3)
	v_fmamk_f32 v40, v10, 0x3e000000, v40
	v_fmac_f32_e32 v41, 0x3e000000, v11
	v_max3_f32 v2, v2, v40, v41
	s_waitcnt lgkmcnt(2)
	v_fmamk_f32 v38, v12, 0x3e000000, v38
	v_fmac_f32_e32 v39, 0x3e000000, v13
	v_max3_f32 v2, v2, v38, v39
	s_waitcnt lgkmcnt(1)
	v_fmamk_f32 v36, v14, 0x3e000000, v36
	v_fmac_f32_e32 v37, 0x3e000000, v15
	v_max3_f32 v2, v2, v36, v37
	s_waitcnt lgkmcnt(0)
	v_fmamk_f32 v34, v16, 0x3e000000, v34
	v_fmac_f32_e32 v35, 0x3e000000, v17
	v_max3_f32 v2, v2, v34, v35
	v_max3_f32 v2, v2, v195, v193
	v_max3_f32 v2, v2, v200, v198
	v_max3_f32 v2, v2, v203, v202
	v_max3_f32 v2, v2, v208, v206
	v_max3_f32 v2, v2, v210, v209
	v_max3_f32 v2, v2, v212, v211
	v_max3_f32 v2, v2, v214, v213
	v_xor_b32_e32 v189, 0x80, v164
	v_max3_f32 v2, v2, v216, v215
	ds_bpermute_b32 v3, v189, v2
	s_waitcnt lgkmcnt(0)
	v_max_f32_e32 v3, v3, v3
	v_max_f32_e32 v217, v2, v3
	v_sub_f32_e32 v17, v97, v217
	v_mul_f32_e32 v17, 0x3fb8aa3b, v17
	v_sub_f32_e32 v2, v123, v217
	v_exp_f32_e32 v176, v17
	v_sub_f32_e32 v17, v96, v217
	v_mul_f32_e32 v2, 0x3fb8aa3b, v2
	v_mul_f32_e32 v17, 0x3fb8aa3b, v17
	v_exp_f32_e32 v10, v2
	v_sub_f32_e32 v2, v122, v217
	v_exp_f32_e32 v178, v17
	v_sub_f32_e32 v17, v67, v217
	v_mul_f32_e32 v2, 0x3fb8aa3b, v2
	v_mul_f32_e32 v17, 0x3fb8aa3b, v17
	v_exp_f32_e32 v12, v2
	v_sub_f32_e32 v2, v83, v217
	v_sub_f32_e32 v3, v85, v217
	v_exp_f32_e32 v177, v17
	v_sub_f32_e32 v17, v66, v217
	v_mul_f32_e32 v2, 0x3fb8aa3b, v2
	v_mul_f32_e32 v3, 0x3fb8aa3b, v3
	v_mul_f32_e32 v17, 0x3fb8aa3b, v17
	v_exp_f32_e32 v11, v2
	v_sub_f32_e32 v2, v82, v217
	v_exp_f32_e32 v14, v3
	v_sub_f32_e32 v3, v84, v217
	v_exp_f32_e32 v179, v17
	v_sub_f32_e32 v17, v69, v217
	v_mul_f32_e32 v2, 0x3fb8aa3b, v2
	v_mul_f32_e32 v3, 0x3fb8aa3b, v3
	v_mul_f32_e32 v17, 0x3fb8aa3b, v17
	v_exp_f32_e32 v13, v2
	v_exp_f32_e32 v50, v3
	v_sub_f32_e32 v3, v87, v217
	v_exp_f32_e32 v180, v17
	v_sub_f32_e32 v17, v68, v217
	v_add_f32_e32 v2, 0, v10
	v_mul_f32_e32 v3, 0x3fb8aa3b, v3
	v_mul_f32_e32 v17, 0x3fb8aa3b, v17
	v_add_f32_e32 v2, v12, v2
	v_exp_f32_e32 v15, v3
	v_sub_f32_e32 v3, v86, v217
	v_exp_f32_e32 v182, v17
	v_sub_f32_e32 v17, v71, v217
	v_add_f32_e32 v2, v11, v2
	v_mul_f32_e32 v3, 0x3fb8aa3b, v3
	v_mul_f32_e32 v17, 0x3fb8aa3b, v17
	v_add_f32_e32 v2, v13, v2
	v_exp_f32_e32 v51, v3
	v_exp_f32_e32 v181, v17
	v_sub_f32_e32 v17, v70, v217
	v_add_f32_e32 v2, v14, v2
	v_mul_f32_e32 v17, 0x3fb8aa3b, v17
	v_add_f32_e32 v2, v50, v2
	v_exp_f32_e32 v183, v17
	v_sub_f32_e32 v17, v73, v217
	v_add_f32_e32 v2, v15, v2
	v_mul_f32_e32 v17, 0x3fb8aa3b, v17
	v_add_f32_e32 v6, v51, v2
	v_sub_f32_e32 v2, v89, v217
	v_sub_f32_e32 v3, v88, v217
	v_exp_f32_e32 v168, v17
	v_sub_f32_e32 v17, v72, v217
	v_mul_f32_e32 v2, 0x3fb8aa3b, v2
	v_mul_f32_e32 v3, 0x3fb8aa3b, v3
	v_mul_f32_e32 v17, 0x3fb8aa3b, v17
	v_exp_f32_e32 v2, v2
	v_exp_f32_e32 v4, v3
	v_sub_f32_e32 v3, v91, v217
	v_exp_f32_e32 v170, v17
	v_sub_f32_e32 v17, v75, v217
	v_mul_f32_e32 v3, 0x3fb8aa3b, v3
	v_sub_f32_e32 v5, v90, v217
	v_mul_f32_e32 v17, 0x3fb8aa3b, v17
	v_exp_f32_e32 v3, v3
	v_mul_f32_e32 v5, 0x3fb8aa3b, v5
	v_exp_f32_e32 v169, v17
	v_sub_f32_e32 v17, v74, v217
	v_exp_f32_e32 v5, v5
	v_mul_f32_e32 v17, 0x3fb8aa3b, v17
	v_add_f32_e32 v6, v2, v6
	v_exp_f32_e32 v171, v17
	v_sub_f32_e32 v17, v77, v217
	v_add_f32_e32 v6, v4, v6
	v_mul_f32_e32 v17, 0x3fb8aa3b, v17
	v_add_f32_e32 v6, v3, v6
	v_exp_f32_e32 v172, v17
	v_sub_f32_e32 v17, v76, v217
	v_add_f32_e32 v16, v5, v6
	v_sub_f32_e32 v6, v93, v217
	v_sub_f32_e32 v7, v92, v217
	v_mul_f32_e32 v17, 0x3fb8aa3b, v17
	v_mul_f32_e32 v6, 0x3fb8aa3b, v6
	v_mul_f32_e32 v7, 0x3fb8aa3b, v7
	v_exp_f32_e32 v174, v17
	v_sub_f32_e32 v17, v79, v217
	v_exp_f32_e32 v6, v6
	v_exp_f32_e32 v8, v7
	v_sub_f32_e32 v7, v95, v217
	v_mul_f32_e32 v17, 0x3fb8aa3b, v17
	v_mul_f32_e32 v7, 0x3fb8aa3b, v7
	v_sub_f32_e32 v9, v94, v217
	v_exp_f32_e32 v173, v17
	v_sub_f32_e32 v17, v78, v217
	v_exp_f32_e32 v7, v7
	v_mul_f32_e32 v9, 0x3fb8aa3b, v9
	v_mul_f32_e32 v17, 0x3fb8aa3b, v17
	v_exp_f32_e32 v9, v9
	v_exp_f32_e32 v175, v17
	v_sub_f32_e32 v17, v81, v217
	v_add_f32_e32 v16, v6, v16
; __device__ __forceinline__ float shflx(float v, int mask, int lane) { return __int_as_float(__builtin_amdgcn_ds_bpermute((lane ^ mask) << 2, __float_as_int(v))); }
; __device__ __forceinline__ void attn_unit(const Args& A, const Ctx& C0, int l, int u_qrow0, int u_nq, int u_krow0, int u_krow1, int u_krow2, int u_g, const float* u_ck, const float* u_cv, unsigned u_vmask) {
;     ...
;         float sum = 0.f;
; #pragma unroll
;         for (int kt = 0; kt < 6; ++kt)
; #pragma unroll
;             for (int r = 0; r < 16; ++r) { const float e = __expf(sacc[kt][r] - mx); sacc[kt][r] = e; sum += e; }
;         sum += shflx(sum, 32, C.lane); sum += __expf(sink - mx);
	v_mul_f32_e32 v17, 0x3fb8aa3b, v17
	v_add_f32_e32 v16, v8, v16
	v_exp_f32_e32 v32, v17
	v_sub_f32_e32 v17, v80, v217
	v_add_f32_e32 v16, v7, v16
	v_mul_f32_e32 v17, 0x3fb8aa3b, v17
	v_add_f32_e32 v16, v9, v16
	v_exp_f32_e32 v128, v17
	v_sub_f32_e32 v17, v119, v217
	v_add_f32_e32 v16, v176, v16
	v_mul_f32_e32 v17, 0x3fb8aa3b, v17
	v_add_f32_e32 v16, v178, v16
	v_exp_f32_e32 v33, v17
	v_sub_f32_e32 v17, v118, v217
	v_add_f32_e32 v16, v177, v16
	v_mul_f32_e32 v17, 0x3fb8aa3b, v17
	v_add_f32_e32 v16, v179, v16
	v_exp_f32_e32 v129, v17
	v_sub_f32_e32 v17, v53, v217
	v_add_f32_e32 v16, v180, v16
	v_mul_f32_e32 v17, 0x3fb8aa3b, v17
	v_add_f32_e32 v16, v182, v16
	v_exp_f32_e32 v164, v17
	v_sub_f32_e32 v17, v52, v217
	v_add_f32_e32 v16, v181, v16
	v_mul_f32_e32 v17, 0x3fb8aa3b, v17
	v_add_f32_e32 v16, v183, v16
	v_exp_f32_e32 v166, v17
	v_sub_f32_e32 v17, v55, v217
	v_add_f32_e32 v16, v168, v16
	v_mul_f32_e32 v17, 0x3fb8aa3b, v17
	v_add_f32_e32 v16, v170, v16
	v_exp_f32_e32 v165, v17
	v_sub_f32_e32 v17, v54, v217
	v_add_f32_e32 v16, v169, v16
	v_mul_f32_e32 v17, 0x3fb8aa3b, v17
	v_add_f32_e32 v16, v171, v16
	v_exp_f32_e32 v167, v17
	v_sub_f32_e32 v17, v57, v217
	v_add_f32_e32 v16, v172, v16
	v_mul_f32_e32 v17, 0x3fb8aa3b, v17
	v_add_f32_e32 v16, v174, v16
	v_exp_f32_e32 v24, v17
	v_sub_f32_e32 v17, v56, v217
	v_add_f32_e32 v16, v173, v16
	v_mul_f32_e32 v17, 0x3fb8aa3b, v17
	v_add_f32_e32 v16, v175, v16
	v_exp_f32_e32 v26, v17
	v_sub_f32_e32 v17, v59, v217
	v_add_f32_e32 v16, v32, v16
	v_mul_f32_e32 v17, 0x3fb8aa3b, v17
	v_add_f32_e32 v16, v128, v16
	v_exp_f32_e32 v25, v17
	v_sub_f32_e32 v17, v58, v217
	v_add_f32_e32 v16, v33, v16
	v_mul_f32_e32 v17, 0x3fb8aa3b, v17
	v_add_f32_e32 v16, v129, v16
	v_exp_f32_e32 v27, v17
	v_sub_f32_e32 v17, v61, v217
	v_add_f32_e32 v16, v164, v16
	v_mul_f32_e32 v17, 0x3fb8aa3b, v17
	v_add_f32_e32 v16, v166, v16
	v_exp_f32_e32 v28, v17
	v_sub_f32_e32 v17, v60, v217
	v_add_f32_e32 v16, v165, v16
	v_mul_f32_e32 v17, 0x3fb8aa3b, v17
	v_add_f32_e32 v16, v167, v16
	v_exp_f32_e32 v30, v17
	v_sub_f32_e32 v17, v63, v217
	v_add_f32_e32 v16, v24, v16
	v_mul_f32_e32 v17, 0x3fb8aa3b, v17
	v_add_f32_e32 v16, v26, v16
	v_exp_f32_e32 v29, v17
	v_sub_f32_e32 v17, v62, v217
	v_add_f32_e32 v16, v25, v16
	v_mul_f32_e32 v17, 0x3fb8aa3b, v17
	v_add_f32_e32 v16, v27, v16
	v_exp_f32_e32 v31, v17
	v_add_f32_e32 v16, v28, v16
	v_add_f32_e32 v16, v30, v16
	v_add_f32_e32 v16, v29, v16
	v_add_f32_e32 v20, v31, v16
	v_sub_f32_e32 v16, v65, v217
	v_sub_f32_e32 v17, v64, v217
	v_mul_f32_e32 v16, 0x3fb8aa3b, v16
	v_mul_f32_e32 v17, 0x3fb8aa3b, v17
	v_exp_f32_e32 v16, v16
	v_exp_f32_e32 v18, v17
	v_sub_f32_e32 v17, v121, v217
	v_mul_f32_e32 v17, 0x3fb8aa3b, v17
	v_sub_f32_e32 v19, v120, v217
	v_exp_f32_e32 v17, v17
	v_mul_f32_e32 v19, 0x3fb8aa3b, v19
	v_exp_f32_e32 v19, v19
	v_add_f32_e32 v20, v16, v20
	v_sub_f32_e32 v53, v194, v217
	v_add_f32_e32 v20, v18, v20
	v_mul_f32_e32 v53, 0x3fb8aa3b, v53
	v_add_f32_e32 v20, v17, v20
	v_exp_f32_e32 v120, v53
	v_sub_f32_e32 v53, v192, v217
	v_add_f32_e32 v52, v19, v20
	v_sub_f32_e32 v20, v125, v217
	v_sub_f32_e32 v21, v124, v217
	v_mul_f32_e32 v53, 0x3fb8aa3b, v53
	v_mul_f32_e32 v20, 0x3fb8aa3b, v20
	v_mul_f32_e32 v21, 0x3fb8aa3b, v21
	v_exp_f32_e32 v122, v53
	v_sub_f32_e32 v53, v197, v217
	v_exp_f32_e32 v20, v20
	v_exp_f32_e32 v22, v21
	v_sub_f32_e32 v21, v127, v217
	v_mul_f32_e32 v53, 0x3fb8aa3b, v53
	v_mul_f32_e32 v21, 0x3fb8aa3b, v21
	v_sub_f32_e32 v23, v126, v217
	v_exp_f32_e32 v121, v53
	v_sub_f32_e32 v53, v196, v217
	v_exp_f32_e32 v21, v21
	v_mul_f32_e32 v23, 0x3fb8aa3b, v23
	v_mul_f32_e32 v53, 0x3fb8aa3b, v53
	v_exp_f32_e32 v23, v23
	v_exp_f32_e32 v123, v53
	v_sub_f32_e32 v53, v201, v217
	v_add_f32_e32 v52, v20, v52
	v_mul_f32_e32 v53, 0x3fb8aa3b, v53
	v_add_f32_e32 v52, v22, v52
	v_exp_f32_e32 v124, v53
	v_sub_f32_e32 v53, v199, v217
	v_add_f32_e32 v52, v21, v52
	v_mul_f32_e32 v53, 0x3fb8aa3b, v53
	v_add_f32_e32 v52, v23, v52
	v_exp_f32_e32 v126, v53
	v_sub_f32_e32 v53, v205, v217
	v_add_f32_e32 v52, v120, v52
	v_mul_f32_e32 v53, 0x3fb8aa3b, v53
	v_add_f32_e32 v52, v122, v52
	v_exp_f32_e32 v125, v53
	v_sub_f32_e32 v53, v204, v217
	v_sub_f32_e32 v48, v48, v217
	v_sub_f32_e32 v34, v34, v217
	v_add_f32_e32 v52, v121, v52
	v_mul_f32_e32 v53, 0x3fb8aa3b, v53
	v_mul_f32_e32 v48, 0x3fb8aa3b, v48
	v_mul_f32_e32 v34, 0x3fb8aa3b, v34
	v_add_f32_e32 v52, v123, v52
	v_exp_f32_e32 v127, v53
	v_exp_f32_e32 v92, v48
	v_sub_f32_e32 v48, v49, v217
	v_sub_f32_e32 v46, v46, v217
	v_exp_f32_e32 v89, v34
	v_sub_f32_e32 v34, v35, v217
	v_sub_f32_e32 v35, v195, v217
	v_add_f32_e32 v52, v124, v52
	v_mul_f32_e32 v48, 0x3fb8aa3b, v48
	v_mul_f32_e32 v46, 0x3fb8aa3b, v46
	v_mul_f32_e32 v35, 0x3fb8aa3b, v35
	v_add_f32_e32 v52, v126, v52
	v_exp_f32_e32 v94, v48
	v_exp_f32_e32 v93, v46
	v_sub_f32_e32 v46, v47, v217
	v_sub_f32_e32 v44, v44, v217
	v_exp_f32_e32 v74, v35
	v_sub_f32_e32 v35, v193, v217
	v_add_f32_e32 v52, v125, v52
	v_mul_f32_e32 v46, 0x3fb8aa3b, v46
	v_mul_f32_e32 v44, 0x3fb8aa3b, v44
	v_mul_f32_e32 v35, 0x3fb8aa3b, v35
	v_add_f32_e32 v52, v127, v52
	v_exp_f32_e32 v95, v46
	v_exp_f32_e32 v96, v44
	v_sub_f32_e32 v44, v45, v217
	v_sub_f32_e32 v42, v42, v217
	v_exp_f32_e32 v76, v35
	v_sub_f32_e32 v35, v200, v217
	v_add_f32_e32 v46, v92, v52
	v_mul_f32_e32 v44, 0x3fb8aa3b, v44
	v_mul_f32_e32 v42, 0x3fb8aa3b, v42
; #define LAS __attribute__((address_space(3)))
; __device__ __forceinline__ unsigned pk2(float lo, float hi) { return f2bf(lo) | (f2bf(hi) << 16); }
; __device__ __forceinline__ float shflx(float v, int mask, int lane) { return __int_as_float(__builtin_amdgcn_ds_bpermute((lane ^ mask) << 2, __float_as_int(v))); }
; __device__ __forceinline__ void attn_unit(const Args& A, const Ctx& C0, int l, int u_qrow0, int u_nq, int u_krow0, int u_krow1, int u_krow2, int u_g, const float* u_ck, const float* u_cv, unsigned u_vmask) {
;     ...
;         for (int kt = 0; kt < 6; ++kt)
; #pragma unroll
;             for (int r = 0; r < 16; ++r) { const float e = __expf(sacc[kt][r] - mx); sacc[kt][r] = e; sum += e; }
;         sum += shflx(sum, 32, C.lane); sum += __expf(sink - mx);
;         const float inv = 1.f / sum;
;         f32x16 oacc[2];
; #pragma unroll
;         for (int dt = 0; dt < 2; ++dt)
; #pragma unroll
;             for (int r = 0; r < 16; ++r) oacc[dt][r] = 0.f;
; #pragma unroll
;         for (int kt = 0; kt < 6; ++kt) {
;             if ((u.vmask >> kt) & 1u) {
; #pragma unroll
;                 for (int s = 0; s < 2; ++s) {
;                     union { bf16x8 v; unsigned w[4]; } pf;
; #pragma unroll
;                     for (int e = 0; e < 4; ++e) pf.w[e] = pk2(sacc[kt][8 * s + 2 * e] * inv, sacc[kt][8 * s + 2 * e + 1] * inv);
; #pragma unroll
;                     for (int dt = 0; dt < 2; ++dt) { const LAS bf16* vp = Vt + (dt * 32 + li) * VP + kt * 32 + 16 * s + 4 * h;
;                         union { bf16x8 v; v2u w[2]; } vf; vf.w[0] = *(const LAS v2u*)vp; vf.w[1] = *(const LAS v2u*)(vp + 8);
;                         oacc[dt] = __builtin_amdgcn_mfma_f32_32x32x16_bf16(vf.v, pf.v, oacc[dt], 0, 0, 0); }
	v_mul_f32_e32 v35, 0x3fb8aa3b, v35
	v_add_f32_e32 v46, v94, v46
	v_exp_f32_e32 v118, v44
	v_exp_f32_e32 v97, v42
	v_sub_f32_e32 v42, v43, v217
	v_sub_f32_e32 v40, v40, v217
	v_exp_f32_e32 v75, v35
	v_sub_f32_e32 v35, v198, v217
	v_add_f32_e32 v46, v93, v46
	v_mul_f32_e32 v42, 0x3fb8aa3b, v42
	v_mul_f32_e32 v40, 0x3fb8aa3b, v40
	v_mul_f32_e32 v35, 0x3fb8aa3b, v35
	v_add_f32_e32 v46, v95, v46
	v_exp_f32_e32 v119, v42
	v_exp_f32_e32 v84, v40
	v_sub_f32_e32 v40, v41, v217
	v_sub_f32_e32 v38, v38, v217
	v_exp_f32_e32 v77, v35
	v_sub_f32_e32 v35, v203, v217
	v_add_f32_e32 v42, v96, v46
	v_mul_f32_e32 v40, 0x3fb8aa3b, v40
	v_mul_f32_e32 v38, 0x3fb8aa3b, v38
	v_mul_f32_e32 v35, 0x3fb8aa3b, v35
	v_add_f32_e32 v42, v118, v42
	v_exp_f32_e32 v86, v40
	v_exp_f32_e32 v85, v38
	v_sub_f32_e32 v38, v39, v217
	v_sub_f32_e32 v36, v36, v217
	v_exp_f32_e32 v78, v35
	v_sub_f32_e32 v35, v202, v217
	v_add_f32_e32 v42, v97, v42
	v_mul_f32_e32 v38, 0x3fb8aa3b, v38
	v_mul_f32_e32 v36, 0x3fb8aa3b, v36
	v_mul_f32_e32 v35, 0x3fb8aa3b, v35
	v_add_f32_e32 v42, v119, v42
	v_exp_f32_e32 v87, v38
	v_exp_f32_e32 v88, v36
	v_sub_f32_e32 v36, v37, v217
	v_exp_f32_e32 v80, v35
	v_sub_f32_e32 v35, v208, v217
	v_add_f32_e32 v38, v84, v42
	v_mul_f32_e32 v36, 0x3fb8aa3b, v36
	v_mul_f32_e32 v35, 0x3fb8aa3b, v35
	v_add_f32_e32 v38, v86, v38
	v_exp_f32_e32 v90, v36
	v_exp_f32_e32 v79, v35
	v_sub_f32_e32 v35, v206, v217
	v_add_f32_e32 v38, v85, v38
	v_mul_f32_e32 v34, 0x3fb8aa3b, v34
	v_mul_f32_e32 v35, 0x3fb8aa3b, v35
	v_add_f32_e32 v38, v87, v38
	v_exp_f32_e32 v91, v34
	v_exp_f32_e32 v81, v35
	v_sub_f32_e32 v35, v210, v217
	v_add_f32_e32 v34, v88, v38
	v_mul_f32_e32 v35, 0x3fb8aa3b, v35
	v_add_f32_e32 v34, v90, v34
	v_exp_f32_e32 v66, v35
	v_sub_f32_e32 v35, v209, v217
	v_add_f32_e32 v34, v89, v34
	v_mul_f32_e32 v35, 0x3fb8aa3b, v35
	v_add_f32_e32 v34, v91, v34
	v_exp_f32_e32 v68, v35
	v_sub_f32_e32 v35, v212, v217
	v_add_f32_e32 v34, v74, v34
	v_mul_f32_e32 v35, 0x3fb8aa3b, v35
	v_add_f32_e32 v34, v76, v34
	v_exp_f32_e32 v67, v35
	v_sub_f32_e32 v35, v211, v217
	v_add_f32_e32 v34, v75, v34
	v_mul_f32_e32 v35, 0x3fb8aa3b, v35
	v_add_f32_e32 v34, v77, v34
	v_exp_f32_e32 v69, v35
	v_sub_f32_e32 v35, v214, v217
	v_add_f32_e32 v34, v78, v34
	v_mul_f32_e32 v35, 0x3fb8aa3b, v35
	v_add_f32_e32 v34, v80, v34
	v_exp_f32_e32 v70, v35
	v_sub_f32_e32 v35, v213, v217
	v_add_f32_e32 v34, v79, v34
	v_mul_f32_e32 v35, 0x3fb8aa3b, v35
	v_add_f32_e32 v34, v81, v34
	v_exp_f32_e32 v72, v35
	v_sub_f32_e32 v35, v216, v217
	v_add_f32_e32 v34, v66, v34
	v_mul_f32_e32 v35, 0x3fb8aa3b, v35
	v_add_f32_e32 v34, v68, v34
	v_exp_f32_e32 v71, v35
	v_sub_f32_e32 v35, v215, v217
	v_add_f32_e32 v34, v67, v34
	v_mul_f32_e32 v35, 0x3fb8aa3b, v35
	v_add_f32_e32 v34, v69, v34
	v_exp_f32_e32 v73, v35
	v_add_f32_e32 v34, v70, v34
	v_add_f32_e32 v34, v72, v34
	v_add_f32_e32 v34, v71, v34
	v_add_f32_e32 v34, v73, v34
	ds_bpermute_b32 v35, v189, v34
	v_sub_f32_e32 v36, v186, v217
	v_mul_f32_e32 v36, 0x3fb8aa3b, v36
	v_exp_f32_e32 v36, v36
	v_sub_u32_e32 v192, v190, v0
	s_waitcnt lgkmcnt(0)
	v_add_f32_e32 v34, v34, v35
	v_add_f32_e32 v34, v36, v34
	v_div_scale_f32 v35, s[2:3], v34, v34, 1.0
	v_rcp_f32_e32 v36, v35
	s_movk_i32 s2, 0x188
	v_fma_f32 v0, -v35, v36, 1.0
	v_fmac_f32_e32 v36, v0, v36
	v_div_scale_f32 v0, vcc, 1.0, v34, 1.0
	v_mul_f32_e32 v37, v0, v36
	v_fma_f32 v38, -v35, v37, v0
	v_fmac_f32_e32 v37, v38, v36
	v_fma_f32 v0, -v35, v37, v0
	v_div_fmas_f32 v0, v0, v36, v37
	v_div_fixup_f32 v82, v0, v34, 1.0
	v_mad_u32_u24 v0, v187, s2, v192
	s_and_b64 vcc, exec, s[38:39]
	v_add_u32_e32 v83, 0x6800, v0
	v_add_u32_e32 v193, 0x9800, v0
	s_cbranch_vccnz .LBB0_481
	v_pk_mul_f32 v[12:13], v[12:13], v[82:83] op_sel_hi:[1,0]
	v_pk_mul_f32 v[34:35], v[50:51], v[82:83] op_sel_hi:[1,0]
	v_pk_mul_f32 v[10:11], v[10:11], v[82:83] op_sel_hi:[1,0]
	v_pk_mul_f32 v[14:15], v[14:15], v[82:83] op_sel_hi:[1,0]
	s_nop 0
	s_nop 0
	s_nop 0
	s_nop 0
	s_nop 0
	s_nop 0
	s_nop 0
	s_nop 0
	s_nop 0
	s_nop 0
	s_nop 0
	s_nop 0
	s_nop 0
	s_nop 0
	v_cvt_pk_bf16_f32 v53, v15, v35
	s_nop 0
	s_nop 0
	v_cvt_pk_bf16_f32 v51, v11, v13
	v_cvt_pk_bf16_f32 v50, v10, v12
	ds_read2_b64 v[10:13], v83 offset0:128 offset1:130
	s_nop 0
	s_nop 0
	s_nop 0
	s_nop 0
	s_nop 0
	v_cvt_pk_bf16_f32 v52, v14, v34
	s_nop 0
	s_nop 0
	v_pk_mul_f32 v[8:9], v[8:9], v[82:83] op_sel_hi:[1,0]
	v_pk_mul_f32 v[4:5], v[4:5], v[82:83] op_sel_hi:[1,0]
	s_waitcnt lgkmcnt(0)
	v_mfma_f32_32x32x16_bf16 v[34:49], v[10:13], v[50:53], 0
	ds_read2_b64 v[10:13], v193 offset0:160 offset1:162
	ds_read2_b64 v[194:197], v83 offset0:132 offset1:134
	v_mul_f32_e64 v6, v6, v82
	v_mul_f32_e64 v7, v7, v82
	s_nop 0
	s_nop 0
	s_nop 0
	v_pk_mul_f32 v[2:3], v[2:3], v[82:83] op_sel_hi:[1,0]
	s_nop 0
	s_waitcnt lgkmcnt(1)
	v_mfma_f32_32x32x16_bf16 v[50:65], v[10:13], v[50:53], 0
	s_nop 0
	s_nop 0
	s_nop 0
	s_nop 0
	s_nop 0
	s_nop 0
	s_nop 0
	s_nop 0
	v_cvt_pk_bf16_f32 v2, v2, v4
	v_cvt_pk_bf16_f32 v4, v6, v8
	s_nop 0
	s_nop 0
	s_nop 0
	s_nop 0
	s_nop 0
	s_nop 0
	s_nop 0
	v_cvt_pk_bf16_f32 v3, v3, v5
	v_cvt_pk_bf16_f32 v5, v7, v9
	ds_read2_b64 v[6:9], v193 offset0:164 offset1:166
	s_nop 0
	s_nop 0
	s_nop 0
	s_nop 0
	s_nop 0
	s_waitcnt lgkmcnt(1)
	s_nop 0
	v_mfma_f32_32x32x16_bf16 v[34:49], v[194:197], v[2:5], v[34:49]
	s_waitcnt lgkmcnt(0)
	v_mfma_f32_32x32x16_bf16 v[50:65], v[6:9], v[2:5], v[50:65]
	s_branch .LBB0_482

; #define LAS __attribute__((address_space(3)))
; __device__ __forceinline__ unsigned pk2(float lo, float hi) { return f2bf(lo) | (f2bf(hi) << 16); }
; __device__ __forceinline__ void attn_unit(const Args& A, const Ctx& C0, int l, int u_qrow0, int u_nq, int u_krow0, int u_krow1, int u_krow2, int u_g, const float* u_ck, const float* u_cv, unsigned u_vmask) {
;     ...
;         for (int kt = 0; kt < 6; ++kt) {
;             if ((u.vmask >> kt) & 1u) {
; #pragma unroll
;                 for (int s = 0; s < 2; ++s) {
;                     union { bf16x8 v; unsigned w[4]; } pf;
; #pragma unroll
;                     for (int e = 0; e < 4; ++e) pf.w[e] = pk2(sacc[kt][8 * s + 2 * e] * inv, sacc[kt][8 * s + 2 * e + 1] * inv);
; #pragma unroll
;                     for (int dt = 0; dt < 2; ++dt) { const LAS bf16* vp = Vt + (dt * 32 + li) * VP + kt * 32 + 16 * s + 4 * h;
;                         union { bf16x8 v; v2u w[2]; } vf; vf.w[0] = *(const LAS v2u*)vp; vf.w[1] = *(const LAS v2u*)(vp + 8);
;                         oacc[dt] = __builtin_amdgcn_mfma_f32_32x32x16_bf16(vf.v, pf.v, oacc[dt], 0, 0, 0); }
.LBB0_482:
	s_and_b64 vcc, exec, s[40:41]
	s_cbranch_vccnz .LBB0_484
	v_pk_mul_f32 v[4:5], v[178:179], v[82:83] op_sel_hi:[1,0]
	v_pk_mul_f32 v[8:9], v[182:183], v[82:83] op_sel_hi:[1,0]
	v_pk_mul_f32 v[2:3], v[176:177], v[82:83] op_sel_hi:[1,0]
	v_pk_mul_f32 v[6:7], v[180:181], v[82:83] op_sel_hi:[1,0]
	v_bfe_u32 v0, v9, 16, 1
	s_nop 0
	v_bfe_u32 v11, v5, 16, 1
	v_bfe_u32 v12, v4, 16, 1
	v_add3_u32 v12, v4, v12, s33
	v_add3_u32 v11, v5, v11, s33
	s_nop 0
	v_add3_u32 v0, v9, v0, s33
	v_bfe_u32 v4, v2, 16, 1
	v_bfe_u32 v5, v3, 16, 1
	s_nop 0
	v_bfe_u32 v10, v7, 16, 1
	v_add3_u32 v7, v7, v10, s33
	s_nop 0
	v_add3_u32 v9, v3, v5, s33
	v_add3_u32 v10, v2, v4, s33
	ds_read2_b64 v[2:5], v83 offset0:136 offset1:138
	v_lshrrev_b32_e32 v10, 16, v10
	v_lshrrev_b32_e32 v13, 16, v9
	s_nop 0
	v_lshrrev_b32_e32 v7, 16, v7
	v_and_or_b32 v9, v0, s96, v7
	v_cvt_pk_bf16_f32 v8, v6, v8
	v_and_or_b32 v7, v11, s96, v13
	v_and_or_b32 v6, v12, s96, v10
	s_waitcnt lgkmcnt(0)
	s_nop 0
	v_mfma_f32_32x32x16_bf16 v[34:49], v[2:5], v[6:9], v[34:49]
	ds_read2_b64 v[2:5], v193 offset0:168 offset1:170
	ds_read2_b64 v[10:13], v83 offset0:140 offset1:142
	s_waitcnt lgkmcnt(1)
	v_mfma_f32_32x32x16_bf16 v[50:65], v[2:5], v[6:9], v[50:65]
	v_mul_f32_e64 v8, v174, v82
	v_mul_f32_e64 v9, v175, v82
	v_mul_f32_e64 v4, v170, v82
	v_mul_f32_e64 v5, v171, v82
	v_mul_f32_e64 v6, v172, v82
	v_mul_f32_e64 v7, v173, v82
	s_nop 0
	v_pk_mul_f32 v[2:3], v[168:169], v[82:83] op_sel_hi:[1,0]
	s_nop 0
	s_nop 0
	s_nop 0
	s_nop 0
	s_nop 0
	s_nop 0
	s_nop 0
	s_nop 0
	s_nop 0
	s_nop 0
	s_nop 0
	v_cvt_pk_bf16_f32 v2, v2, v4
	v_cvt_pk_bf16_f32 v4, v6, v8
	s_nop 0
	s_nop 0
	s_nop 0
	s_nop 0
	s_nop 0
	s_nop 0
	s_nop 0
	v_cvt_pk_bf16_f32 v3, v3, v5
	v_cvt_pk_bf16_f32 v5, v7, v9
	ds_read2_b64 v[6:9], v193 offset0:172 offset1:174
	s_nop 0
	s_nop 0
	s_nop 0
	s_nop 0
	s_nop 0
	s_waitcnt lgkmcnt(1)
	s_nop 0
	v_mfma_f32_32x32x16_bf16 v[34:49], v[10:13], v[2:5], v[34:49]
	s_waitcnt lgkmcnt(0)
	v_mfma_f32_32x32x16_bf16 v[50:65], v[6:9], v[2:5], v[50:65]
.LBB0_484:
	s_and_b64 vcc, exec, s[44:45]
	s_cbranch_vccnz .LBB0_486
	v_pk_mul_f32 v[4:5], v[128:129], v[82:83] op_sel_hi:[1,0]
	v_pk_mul_f32 v[8:9], v[166:167], v[82:83] op_sel_hi:[1,0]
	v_pk_mul_f32 v[2:3], v[32:33], v[82:83] op_sel_hi:[1,0]
	v_pk_mul_f32 v[6:7], v[164:165], v[82:83] op_sel_hi:[1,0]
	v_bfe_u32 v0, v9, 16, 1
	s_nop 0
	v_bfe_u32 v11, v5, 16, 1
	v_bfe_u32 v12, v4, 16, 1
	v_add3_u32 v12, v4, v12, s33
	v_add3_u32 v11, v5, v11, s33
	s_nop 0
	v_add3_u32 v0, v9, v0, s33
	v_bfe_u32 v4, v2, 16, 1
	v_bfe_u32 v5, v3, 16, 1
	s_nop 0
	v_bfe_u32 v10, v7, 16, 1
	v_add3_u32 v7, v7, v10, s33
	s_nop 0
	v_add3_u32 v9, v3, v5, s33
	v_add3_u32 v10, v2, v4, s33
	ds_read2_b64 v[2:5], v83 offset0:144 offset1:146
	v_lshrrev_b32_e32 v10, 16, v10
	v_lshrrev_b32_e32 v13, 16, v9
	s_nop 0
	v_lshrrev_b32_e32 v7, 16, v7
	v_and_or_b32 v9, v0, s96, v7
	v_cvt_pk_bf16_f32 v8, v6, v8
	v_and_or_b32 v7, v11, s96, v13
	v_and_or_b32 v6, v12, s96, v10
	s_waitcnt lgkmcnt(0)
	s_nop 0
	v_mfma_f32_32x32x16_bf16 v[34:49], v[2:5], v[6:9], v[34:49]
	ds_read2_b64 v[2:5], v193 offset0:176 offset1:178
	ds_read2_b64 v[10:13], v83 offset0:148 offset1:150
	s_waitcnt lgkmcnt(1)
	v_mfma_f32_32x32x16_bf16 v[50:65], v[2:5], v[6:9], v[50:65]
	v_mul_f32_e64 v8, v30, v82
	v_mul_f32_e64 v9, v31, v82
	v_mul_f32_e64 v4, v26, v82
	v_mul_f32_e64 v5, v27, v82
	v_mul_f32_e64 v6, v28, v82
	v_mul_f32_e64 v7, v29, v82
	s_nop 0
	v_pk_mul_f32 v[2:3], v[24:25], v[82:83] op_sel_hi:[1,0]
	s_nop 0
	s_nop 0
	s_nop 0
	s_nop 0
	s_nop 0
	s_nop 0
	s_nop 0
	s_nop 0
	s_nop 0
	s_nop 0
	s_nop 0
	v_cvt_pk_bf16_f32 v2, v2, v4
	v_cvt_pk_bf16_f32 v4, v6, v8
	s_nop 0
	s_nop 0
	s_nop 0
	s_nop 0
	s_nop 0
	s_nop 0
	s_nop 0
	v_cvt_pk_bf16_f32 v3, v3, v5
	v_cvt_pk_bf16_f32 v5, v7, v9
	ds_read2_b64 v[6:9], v193 offset0:180 offset1:182
	s_nop 0
	s_nop 0
	s_nop 0
	s_nop 0
	s_nop 0
	s_waitcnt lgkmcnt(1)
	s_nop 0
	v_mfma_f32_32x32x16_bf16 v[34:49], v[10:13], v[2:5], v[34:49]
	s_waitcnt lgkmcnt(0)
	v_mfma_f32_32x32x16_bf16 v[50:65], v[6:9], v[2:5], v[50:65]
.LBB0_486:
	v_mov_b32_e32 v14, 0x3100
	s_and_b64 vcc, exec, s[60:61]
	v_mul_u32_u24_e32 v0, 0x188, v187
	v_mad_u32_u24 v128, v187, s2, v14
	s_cbranch_vccz .LBB0_488
	v_pk_mul_f32 v[4:5], v[18:19], v[82:83] op_sel_hi:[1,0]
	v_pk_mul_f32 v[8:9], v[22:23], v[82:83] op_sel_hi:[1,0]
	v_pk_mul_f32 v[2:3], v[16:17], v[82:83] op_sel_hi:[1,0]
	v_pk_mul_f32 v[6:7], v[20:21], v[82:83] op_sel_hi:[1,0]
	s_nop 0
	s_nop 0
	s_nop 0
	s_nop 0
	s_nop 0
	s_nop 0
	s_nop 0
	s_nop 0
	s_nop 0
	s_nop 0
	s_nop 0
	s_nop 0
	s_nop 0
	s_nop 0
	s_nop 0
	s_nop 0
	v_cvt_pk_bf16_f32 v167, v3, v5
	v_cvt_pk_bf16_f32 v166, v2, v4
	ds_read2_b64 v[2:5], v83 offset0:152 offset1:154
	s_nop 0
	s_nop 0
	s_nop 0
	s_nop 0
	v_cvt_pk_bf16_f32 v169, v7, v9
	v_cvt_pk_bf16_f32 v168, v6, v8
	s_nop 0
	s_nop 0
	v_mad_u32_u24 v164, v187, s2, v14
	v_pk_mul_f32 v[122:123], v[122:123], v[82:83] op_sel_hi:[1,0]
	s_waitcnt lgkmcnt(0)
	v_mfma_f32_32x32x16_bf16 v[18:33], v[2:5], v[166:169], v[34:49]
	v_add_u32_e32 v2, v192, v164
	v_add_u32_e32 v129, 0x6800, v2
	ds_read2_b64 v[170:173], v129 offset0:152 offset1:154
	ds_read2_b64 v[174:177], v83 offset0:156 offset1:158
	v_mul_f32_e64 v124, v124, v82
	v_mul_f32_e64 v125, v125, v82
	v_pk_mul_f32 v[126:127], v[126:127], v[82:83] op_sel_hi:[1,0]
	v_pk_mul_f32 v[120:121], v[120:121], v[82:83] op_sel_hi:[1,0]
	s_nop 0
	s_waitcnt lgkmcnt(1)
	v_mfma_f32_32x32x16_bf16 v[2:17], v[170:173], v[166:169], v[50:65]
	s_nop 0
	s_nop 0
	s_nop 0
	s_nop 0
	s_nop 0
	s_nop 0
	s_nop 0
	s_nop 0
	ds_read2_b64 v[166:169], v129 offset0:156 offset1:158
	s_nop 0
	s_nop 0
	s_nop 0
	v_cvt_pk_bf16_f32 v125, v125, v127
	s_nop 0
	s_nop 0
	s_nop 0
	s_nop 0
	s_nop 0
	s_nop 0
	s_nop 0
	s_nop 0
	s_nop 0
	v_cvt_pk_bf16_f32 v124, v124, v126
	v_cvt_pk_bf16_f32 v123, v121, v123
	v_cvt_pk_bf16_f32 v122, v120, v122
	v_mul_u32_u24_e32 v120, 0x188, v187
	s_waitcnt lgkmcnt(1)
	v_mfma_f32_32x32x16_bf16 v[18:33], v[174:177], v[122:125], v[18:33]
	s_waitcnt lgkmcnt(0)
	v_mfma_f32_32x32x16_bf16 v[2:17], v[166:169], v[122:125], v[2:17]
	s_cbranch_execz .LBB0_489
	s_branch .LBB0_490

; #define LAS __attribute__((address_space(3)))
; __device__ __forceinline__ unsigned pk2(float lo, float hi) { return f2bf(lo) | (f2bf(hi) << 16); }
; __device__ __forceinline__ void attn_unit(const Args& A, const Ctx& C0, int l, int u_qrow0, int u_nq, int u_krow0, int u_krow1, int u_krow2, int u_g, const float* u_ck, const float* u_cv, unsigned u_vmask) {
;     ...
;         for (int kt = 0; kt < 6; ++kt) {
;             if ((u.vmask >> kt) & 1u) {
; #pragma unroll
;                 for (int s = 0; s < 2; ++s) {
;                     union { bf16x8 v; unsigned w[4]; } pf;
; #pragma unroll
;                     for (int e = 0; e < 4; ++e) pf.w[e] = pk2(sacc[kt][8 * s + 2 * e] * inv, sacc[kt][8 * s + 2 * e + 1] * inv);
; #pragma unroll
;                     for (int dt = 0; dt < 2; ++dt) { const LAS bf16* vp = Vt + (dt * 32 + li) * VP + kt * 32 + 16 * s + 4 * h;
;                         union { bf16x8 v; v2u w[2]; } vf; vf.w[0] = *(const LAS v2u*)vp; vf.w[1] = *(const LAS v2u*)(vp + 8);
;                         oacc[dt] = __builtin_amdgcn_mfma_f32_32x32x16_bf16(vf.v, pf.v, oacc[dt], 0, 0, 0); }
.LBB0_490:
	v_mov_b32_e32 v83, v82
	v_pk_mul_f32 v[36:37], v[94:95], v[82:83]
	v_pk_mul_f32 v[40:41], v[118:119], v[82:83]
	v_pk_mul_f32 v[34:35], v[92:93], v[82:83]
	v_pk_mul_f32 v[38:39], v[96:97], v[82:83]
	s_nop 0
	v_bfe_u32 v44, v36, 16, 1
	v_add3_u32 v44, v36, v44, s33
	s_nop 0
	v_bfe_u32 v36, v34, 16, 1
	v_bfe_u32 v42, v39, 16, 1
	v_bfe_u32 v0, v41, 16, 1
	v_bfe_u32 v43, v37, 16, 1
	v_add3_u32 v39, v39, v42, s33
	v_add3_u32 v42, v34, v36, s33
	v_add_u32_e32 v34, v192, v120
	v_add3_u32 v43, v37, v43, s33
	v_add3_u32 v0, v41, v0, s33
	v_bfe_u32 v37, v35, 16, 1
	s_nop 0
	v_add_u32_e32 v129, 0x6800, v34
	s_nop 0
	v_add3_u32 v41, v35, v37, s33
	ds_read2_b64 v[34:37], v129 offset0:160 offset1:162
	v_lshrrev_b32_e32 v39, 16, v39
	v_lshrrev_b32_e32 v42, 16, v42
	v_lshrrev_b32_e32 v45, 16, v41
	s_nop 0
	v_and_or_b32 v41, v0, s96, v39
	v_add_u32_e32 v0, v192, v164
	v_cvt_pk_bf16_f32 v40, v38, v40
	v_and_or_b32 v39, v43, s96, v45
	v_and_or_b32 v38, v44, s96, v42
	v_add_u32_e32 v128, 0x6800, v0
	s_and_b64 vcc, exec, s[42:43]
	s_waitcnt lgkmcnt(0)
	v_mfma_f32_32x32x16_bf16 v[18:33], v[34:37], v[38:41], v[18:33]
	ds_read2_b64 v[34:37], v128 offset0:160 offset1:162
	ds_read2_b64 v[42:45], v129 offset0:164 offset1:166
	s_waitcnt lgkmcnt(1)
	v_mfma_f32_32x32x16_bf16 v[2:17], v[34:37], v[38:41], v[2:17]
	v_mul_f32_e64 v40, v90, v82
	v_mul_f32_e64 v41, v91, v83
	v_mul_f32_e64 v36, v86, v82
	v_mul_f32_e64 v37, v87, v83
	v_mul_f32_e64 v38, v88, v82
	v_mul_f32_e64 v39, v89, v83
	s_nop 0
	s_nop 0
	s_nop 0
	s_nop 0
	s_nop 0
	v_pk_mul_f32 v[34:35], v[84:85], v[82:83]
	s_nop 0
	s_nop 0
	s_nop 0
	s_nop 0
	s_nop 0
	s_nop 0
	s_nop 0
	v_cvt_pk_bf16_f32 v34, v34, v36
	v_cvt_pk_bf16_f32 v36, v38, v40
	s_nop 0
	s_nop 0
	s_nop 0
	s_nop 0
	s_nop 0
	s_nop 0
	s_nop 0
	v_cvt_pk_bf16_f32 v35, v35, v37
	v_cvt_pk_bf16_f32 v37, v39, v41
	ds_read2_b64 v[38:41], v128 offset0:164 offset1:166
	s_nop 0
	s_nop 0
	s_nop 0
	s_nop 0
	s_nop 0
	s_waitcnt lgkmcnt(1)
	s_nop 0
	v_mfma_f32_32x32x16_bf16 v[18:33], v[42:45], v[34:37], v[18:33]
	s_waitcnt lgkmcnt(0)
	v_mfma_f32_32x32x16_bf16 v[2:17], v[38:41], v[34:37], v[2:17]
	s_cbranch_vccnz .LBB0_492
	v_pk_mul_f32 v[36:37], v[76:77], v[82:83]
	v_pk_mul_f32 v[40:41], v[80:81], v[82:83]
	v_pk_mul_f32 v[34:35], v[74:75], v[82:83]
	v_pk_mul_f32 v[38:39], v[78:79], v[82:83]
	v_bfe_u32 v0, v41, 16, 1
	s_nop 0
	v_bfe_u32 v43, v37, 16, 1
	v_bfe_u32 v44, v36, 16, 1
	v_add3_u32 v44, v36, v44, s33
	v_add3_u32 v43, v37, v43, s33
	s_nop 0
	v_add3_u32 v0, v41, v0, s33
	v_bfe_u32 v36, v34, 16, 1
	v_bfe_u32 v37, v35, 16, 1
	s_nop 0
	v_bfe_u32 v42, v39, 16, 1
	v_add3_u32 v39, v39, v42, s33
	s_nop 0
	v_add3_u32 v41, v35, v37, s33
	v_add3_u32 v42, v34, v36, s33
	ds_read2_b64 v[34:37], v129 offset0:168 offset1:170
	v_lshrrev_b32_e32 v42, 16, v42
	v_lshrrev_b32_e32 v45, 16, v41
	s_nop 0
	v_lshrrev_b32_e32 v39, 16, v39
	v_and_or_b32 v41, v0, s96, v39
	v_cvt_pk_bf16_f32 v40, v38, v40
	v_and_or_b32 v39, v43, s96, v45
	v_and_or_b32 v38, v44, s96, v42
	s_waitcnt lgkmcnt(0)
	s_nop 0
	v_mfma_f32_32x32x16_bf16 v[18:33], v[34:37], v[38:41], v[18:33]
	ds_read2_b64 v[34:37], v128 offset0:168 offset1:170
	ds_read2_b64 v[42:45], v129 offset0:172 offset1:174
	s_waitcnt lgkmcnt(1)
	v_mfma_f32_32x32x16_bf16 v[2:17], v[34:37], v[38:41], v[2:17]
	v_mul_f32_e64 v40, v72, v82
	v_mul_f32_e64 v41, v73, v83
	v_mul_f32_e64 v36, v68, v82
	v_mul_f32_e64 v37, v69, v83
	v_mul_f32_e64 v38, v70, v82
	v_mul_f32_e64 v39, v71, v83
	s_nop 0
	s_nop 0
	s_nop 0
	s_nop 0
	s_nop 0
	v_pk_mul_f32 v[34:35], v[66:67], v[82:83]
	s_nop 0
	s_nop 0
	s_nop 0
	s_nop 0
	s_nop 0
	s_nop 0
	s_nop 0
	v_cvt_pk_bf16_f32 v34, v34, v36
	v_cvt_pk_bf16_f32 v36, v38, v40
	s_nop 0
	s_nop 0
	s_nop 0
	s_nop 0
	s_nop 0
	s_nop 0
	s_nop 0
	v_cvt_pk_bf16_f32 v35, v35, v37
	v_cvt_pk_bf16_f32 v37, v39, v41
	ds_read2_b64 v[38:41], v128 offset0:172 offset1:174
	s_nop 0
	s_nop 0
	s_nop 0
	s_nop 0
	s_nop 0
	s_waitcnt lgkmcnt(1)
	s_nop 0
	v_mfma_f32_32x32x16_bf16 v[18:33], v[42:45], v[34:37], v[18:33]
	s_waitcnt lgkmcnt(0)
	v_mfma_f32_32x32x16_bf16 v[2:17], v[38:41], v[34:37], v[2:17]

; __device__ __forceinline__ float shflx(float v, int mask, int lane) { return __int_as_float(__builtin_amdgcn_ds_bpermute((lane ^ mask) << 2, __float_as_int(v))); }
; __device__ __forceinline__ void attn_unit(const Args& A, const Ctx& C0, int l, int u_qrow0, int u_nq, int u_krow0, int u_krow1, int u_krow2, int u_g, const float* u_ck, const float* u_cv, unsigned u_vmask) {
;     ...
;         float mx = sink;
; #pragma unroll
;         for (int kt = 0; kt < 6; ++kt) { const bool valid = (u.vmask >> kt) & 1u;
; #pragma unroll
;             for (int r = 0; r < 16; ++r) { const int j = kt * 32 + (r & 3) + 8 * (r >> 2) + 4 * h;
;                 const float lg = valid ? sacc[kt][r] * 0.125f + bL[j - qi + 63] : -1e30f; sacc[kt][r] = lg; mx = fmaxf(mx, lg); }
;             asm volatile("" ::: "memory"); }
;         mx = fmaxf(mx, shflx(mx, 32, C.lane));
;         float sum = 0.f;
; #pragma unroll
;         for (int kt = 0; kt < 6; ++kt)
; #pragma unroll
;             for (int r = 0; r < 16; ++r) { const float e = __expf(sacc[kt][r] - mx); sacc[kt][r] = e; sum += e; }
.LBB0_578:
	v_max3_f32 v18, v186, v107, v106
	v_max3_f32 v18, v18, v83, v82
	v_max3_f32 v18, v18, v85, v84
	v_max3_f32 v18, v18, v87, v86
	v_max3_f32 v18, v18, v89, v88
	v_max3_f32 v18, v18, v91, v90
	v_max3_f32 v18, v18, v93, v92
	v_max3_f32 v18, v18, v95, v94
	v_max3_f32 v18, v18, v97, v96
	v_max3_f32 v18, v18, v67, v66
	v_max3_f32 v18, v18, v69, v68
	v_max3_f32 v18, v18, v71, v70
	v_max3_f32 v18, v18, v73, v72
	v_max3_f32 v18, v18, v75, v74
	v_max3_f32 v18, v18, v77, v76
	v_max3_f32 v18, v18, v79, v78
	v_max3_f32 v18, v18, v81, v80
	v_max3_f32 v18, v18, v103, v102
	v_max3_f32 v18, v18, v105, v104
	v_max3_f32 v18, v18, v109, v108
	v_max3_f32 v18, v18, v111, v110
	v_max3_f32 v18, v18, v59, v58
	v_max3_f32 v18, v18, v61, v60
	v_max3_f32 v18, v18, v63, v62
	v_max3_f32 v18, v18, v65, v64
	v_max3_f32 v18, v18, v149, v148
	v_max3_f32 v18, v18, v151, v150
	v_max3_f32 v18, v18, v153, v152
	v_max3_f32 v18, v18, v156, v154
	v_max3_f32 v18, v18, v160, v158
	v_max3_f32 v18, v18, v164, v162
	v_max3_f32 v18, v18, v168, v166
	s_waitcnt lgkmcnt(0)
	v_fmamk_f32 v48, v2, 0x3e000000, v48
	v_fmac_f32_e32 v49, 0x3e000000, v3
	v_max3_f32 v2, v18, v48, v49
	v_fmamk_f32 v46, v4, 0x3e000000, v46
	v_fmac_f32_e32 v47, 0x3e000000, v5
	v_max3_f32 v2, v2, v46, v47
	v_fmamk_f32 v44, v6, 0x3e000000, v44
	v_fmac_f32_e32 v45, 0x3e000000, v7
	v_max3_f32 v2, v2, v44, v45
	v_fmamk_f32 v42, v8, 0x3e000000, v42
	v_fmac_f32_e32 v43, 0x3e000000, v9
	v_max3_f32 v2, v2, v42, v43
	v_fmamk_f32 v40, v10, 0x3e000000, v40
	v_fmac_f32_e32 v41, 0x3e000000, v11
	v_max3_f32 v2, v2, v40, v41
	v_fmamk_f32 v38, v12, 0x3e000000, v38
	v_fmac_f32_e32 v39, 0x3e000000, v13
	v_max3_f32 v2, v2, v38, v39
	v_fmamk_f32 v36, v14, 0x3e000000, v36
	v_fmac_f32_e32 v37, 0x3e000000, v15
	v_max3_f32 v2, v2, v36, v37
	v_fmamk_f32 v34, v16, 0x3e000000, v34
	v_fmac_f32_e32 v35, 0x3e000000, v17
	v_max3_f32 v2, v2, v34, v35
	v_max3_f32 v2, v2, v157, v155
	v_max3_f32 v2, v2, v161, v159
	v_max3_f32 v2, v2, v165, v163
	v_max3_f32 v2, v2, v169, v167
	v_max3_f32 v2, v2, v171, v170
	v_max3_f32 v2, v2, v173, v172
	v_max3_f32 v2, v2, v175, v174
	v_max3_f32 v2, v2, v177, v176
	ds_bpermute_b32 v3, v189, v2
	s_waitcnt lgkmcnt(0)
	v_max_f32_e32 v3, v3, v3
	v_max_f32_e32 v178, v2, v3
	v_sub_f32_e32 v3, v85, v178
	v_mul_f32_e32 v3, 0x3fb8aa3b, v3
	v_exp_f32_e32 v54, v3
	v_sub_f32_e32 v3, v84, v178
	v_mul_f32_e32 v3, 0x3fb8aa3b, v3
	v_exp_f32_e32 v56, v3
	v_sub_f32_e32 v3, v87, v178
	v_mul_f32_e32 v3, 0x3fb8aa3b, v3
	v_exp_f32_e32 v55, v3
	v_sub_f32_e32 v3, v86, v178
	v_mul_f32_e32 v3, 0x3fb8aa3b, v3
	v_exp_f32_e32 v57, v3
	v_sub_f32_e32 v3, v89, v178
	v_mul_f32_e32 v3, 0x3fb8aa3b, v3
	v_exp_f32_e32 v120, v3
	v_sub_f32_e32 v3, v88, v178
	v_mul_f32_e32 v3, 0x3fb8aa3b, v3
	v_exp_f32_e32 v122, v3
	v_sub_f32_e32 v3, v91, v178
	v_mul_f32_e32 v3, 0x3fb8aa3b, v3
	v_exp_f32_e32 v121, v3
	v_sub_f32_e32 v3, v90, v178
	v_mul_f32_e32 v3, 0x3fb8aa3b, v3
	v_exp_f32_e32 v123, v3
	v_sub_f32_e32 v3, v93, v178
	v_mul_f32_e32 v3, 0x3fb8aa3b, v3
	v_exp_f32_e32 v124, v3
	v_sub_f32_e32 v3, v92, v178
	v_mul_f32_e32 v3, 0x3fb8aa3b, v3
	v_exp_f32_e32 v126, v3
	v_sub_f32_e32 v3, v95, v178
	v_mul_f32_e32 v3, 0x3fb8aa3b, v3
	v_exp_f32_e32 v125, v3
	v_sub_f32_e32 v3, v94, v178
	v_mul_f32_e32 v3, 0x3fb8aa3b, v3
	v_exp_f32_e32 v127, v3
	v_sub_f32_e32 v3, v97, v178
	v_mul_f32_e32 v3, 0x3fb8aa3b, v3
	v_exp_f32_e32 v112, v3
	v_sub_f32_e32 v3, v96, v178
	v_mul_f32_e32 v3, 0x3fb8aa3b, v3
	v_exp_f32_e32 v114, v3
	v_sub_f32_e32 v3, v67, v178
	v_mul_f32_e32 v3, 0x3fb8aa3b, v3
	v_exp_f32_e32 v113, v3
	v_sub_f32_e32 v3, v66, v178
	v_mul_f32_e32 v3, 0x3fb8aa3b, v3
	v_exp_f32_e32 v115, v3
	v_sub_f32_e32 v3, v69, v178
	v_mul_f32_e32 v3, 0x3fb8aa3b, v3
	v_exp_f32_e32 v116, v3
	v_sub_f32_e32 v3, v68, v178
	v_mul_f32_e32 v3, 0x3fb8aa3b, v3
	v_sub_f32_e32 v2, v107, v178
	v_exp_f32_e32 v118, v3
	v_sub_f32_e32 v3, v71, v178
	v_mul_f32_e32 v2, 0x3fb8aa3b, v2
	v_mul_f32_e32 v3, 0x3fb8aa3b, v3
	v_exp_f32_e32 v50, v2
	v_sub_f32_e32 v2, v106, v178
	v_exp_f32_e32 v117, v3
	v_sub_f32_e32 v3, v70, v178
	v_mul_f32_e32 v2, 0x3fb8aa3b, v2
	v_mul_f32_e32 v3, 0x3fb8aa3b, v3
	v_exp_f32_e32 v52, v2
	v_sub_f32_e32 v2, v83, v178
	v_exp_f32_e32 v119, v3
	v_sub_f32_e32 v3, v73, v178
	v_mul_f32_e32 v2, 0x3fb8aa3b, v2
	v_mul_f32_e32 v3, 0x3fb8aa3b, v3
	v_exp_f32_e32 v51, v2
	v_sub_f32_e32 v2, v82, v178
	v_exp_f32_e32 v26, v3
	v_sub_f32_e32 v3, v72, v178
	v_mul_f32_e32 v2, 0x3fb8aa3b, v2
	v_mul_f32_e32 v3, 0x3fb8aa3b, v3
	v_exp_f32_e32 v53, v2
	v_exp_f32_e32 v28, v3
	v_sub_f32_e32 v3, v75, v178
	v_add_f32_e32 v2, 0, v50
	v_mul_f32_e32 v3, 0x3fb8aa3b, v3
	v_add_f32_e32 v2, v52, v2
	v_exp_f32_e32 v27, v3
	v_sub_f32_e32 v3, v74, v178
	v_add_f32_e32 v2, v51, v2
	v_mul_f32_e32 v3, 0x3fb8aa3b, v3
	v_add_f32_e32 v2, v53, v2
	v_exp_f32_e32 v29, v3
	v_sub_f32_e32 v3, v77, v178
	v_add_f32_e32 v2, v54, v2
	v_mul_f32_e32 v3, 0x3fb8aa3b, v3
	v_add_f32_e32 v2, v56, v2
	v_exp_f32_e32 v30, v3
	v_sub_f32_e32 v3, v76, v178
	v_add_f32_e32 v2, v55, v2
	v_mul_f32_e32 v3, 0x3fb8aa3b, v3
	v_add_f32_e32 v2, v57, v2
	v_exp_f32_e32 v32, v3
	v_sub_f32_e32 v3, v79, v178
	v_add_f32_e32 v2, v120, v2
	v_mul_f32_e32 v3, 0x3fb8aa3b, v3
	v_add_f32_e32 v2, v122, v2
	v_exp_f32_e32 v31, v3
	v_sub_f32_e32 v3, v78, v178
	v_add_f32_e32 v2, v121, v2
	v_mul_f32_e32 v3, 0x3fb8aa3b, v3
	v_add_f32_e32 v2, v123, v2
	v_exp_f32_e32 v33, v3
	v_sub_f32_e32 v3, v81, v178
	v_add_f32_e32 v2, v124, v2
	v_mul_f32_e32 v3, 0x3fb8aa3b, v3
	v_add_f32_e32 v2, v126, v2
	v_exp_f32_e32 v18, v3
	v_sub_f32_e32 v3, v80, v178
	v_add_f32_e32 v2, v125, v2
	v_mul_f32_e32 v3, 0x3fb8aa3b, v3
	v_add_f32_e32 v2, v127, v2
	v_exp_f32_e32 v20, v3
	v_sub_f32_e32 v3, v103, v178
; __device__ __forceinline__ float shflx(float v, int mask, int lane) { return __int_as_float(__builtin_amdgcn_ds_bpermute((lane ^ mask) << 2, __float_as_int(v))); }
; __device__ __forceinline__ void attn_unit(const Args& A, const Ctx& C0, int l, int u_qrow0, int u_nq, int u_krow0, int u_krow1, int u_krow2, int u_g, const float* u_ck, const float* u_cv, unsigned u_vmask) {
;     ...
; #pragma unroll
;         for (int kt = 0; kt < 6; ++kt)
; #pragma unroll
;             for (int r = 0; r < 16; ++r) { const float e = __expf(sacc[kt][r] - mx); sacc[kt][r] = e; sum += e; }
;         sum += shflx(sum, 32, C.lane); sum += __expf(sink - mx);
	v_add_f32_e32 v2, v112, v2
	v_mul_f32_e32 v3, 0x3fb8aa3b, v3
	v_add_f32_e32 v2, v114, v2
	v_exp_f32_e32 v19, v3
	v_sub_f32_e32 v3, v102, v178
	v_add_f32_e32 v2, v113, v2
	v_mul_f32_e32 v3, 0x3fb8aa3b, v3
	v_add_f32_e32 v2, v115, v2
	v_exp_f32_e32 v21, v3
	v_sub_f32_e32 v3, v105, v178
	v_add_f32_e32 v2, v116, v2
	v_mul_f32_e32 v3, 0x3fb8aa3b, v3
	v_add_f32_e32 v2, v118, v2
	v_exp_f32_e32 v22, v3
	v_sub_f32_e32 v3, v104, v178
	v_add_f32_e32 v2, v117, v2
	v_mul_f32_e32 v3, 0x3fb8aa3b, v3
	v_add_f32_e32 v2, v119, v2
	v_exp_f32_e32 v24, v3
	v_sub_f32_e32 v3, v109, v178
	v_add_f32_e32 v2, v26, v2
	v_mul_f32_e32 v3, 0x3fb8aa3b, v3
	v_add_f32_e32 v2, v28, v2
	v_exp_f32_e32 v23, v3
	v_sub_f32_e32 v3, v108, v178
	v_add_f32_e32 v2, v27, v2
	v_mul_f32_e32 v3, 0x3fb8aa3b, v3
	v_add_f32_e32 v2, v29, v2
	v_exp_f32_e32 v25, v3
	v_sub_f32_e32 v3, v111, v178
	v_add_f32_e32 v2, v30, v2
	v_mul_f32_e32 v3, 0x3fb8aa3b, v3
	v_add_f32_e32 v2, v32, v2
	v_exp_f32_e32 v10, v3
	v_sub_f32_e32 v3, v110, v178
	v_add_f32_e32 v2, v31, v2
	v_mul_f32_e32 v3, 0x3fb8aa3b, v3
	v_add_f32_e32 v2, v33, v2
	v_exp_f32_e32 v12, v3
	v_sub_f32_e32 v3, v59, v178
	v_add_f32_e32 v2, v18, v2
	v_mul_f32_e32 v3, 0x3fb8aa3b, v3
	v_add_f32_e32 v2, v20, v2
	v_exp_f32_e32 v11, v3
	v_sub_f32_e32 v3, v58, v178
	v_add_f32_e32 v2, v19, v2
	v_mul_f32_e32 v3, 0x3fb8aa3b, v3
	v_add_f32_e32 v2, v21, v2
	v_exp_f32_e32 v13, v3
	v_sub_f32_e32 v3, v61, v178
	v_add_f32_e32 v2, v22, v2
	v_mul_f32_e32 v3, 0x3fb8aa3b, v3
	v_add_f32_e32 v2, v24, v2
	v_exp_f32_e32 v14, v3
	v_sub_f32_e32 v3, v60, v178
	v_add_f32_e32 v2, v23, v2
	v_mul_f32_e32 v3, 0x3fb8aa3b, v3
	v_add_f32_e32 v2, v25, v2
	v_exp_f32_e32 v16, v3
	v_sub_f32_e32 v3, v63, v178
	v_add_f32_e32 v2, v10, v2
	v_mul_f32_e32 v3, 0x3fb8aa3b, v3
	v_add_f32_e32 v2, v12, v2
	v_exp_f32_e32 v15, v3
	v_sub_f32_e32 v3, v62, v178
	v_add_f32_e32 v2, v11, v2
	v_mul_f32_e32 v3, 0x3fb8aa3b, v3
	v_add_f32_e32 v2, v13, v2
	v_exp_f32_e32 v17, v3
	v_add_f32_e32 v2, v14, v2
	v_add_f32_e32 v2, v16, v2
	v_add_f32_e32 v2, v15, v2
	v_add_f32_e32 v6, v17, v2
	v_sub_f32_e32 v2, v65, v178
	v_sub_f32_e32 v3, v64, v178
	v_mul_f32_e32 v2, 0x3fb8aa3b, v2
	v_mul_f32_e32 v3, 0x3fb8aa3b, v3
	v_exp_f32_e32 v2, v2
	v_exp_f32_e32 v4, v3
	v_sub_f32_e32 v3, v149, v178
	v_mul_f32_e32 v3, 0x3fb8aa3b, v3
	v_sub_f32_e32 v5, v148, v178
	v_exp_f32_e32 v3, v3
	v_mul_f32_e32 v5, 0x3fb8aa3b, v5
	v_exp_f32_e32 v5, v5
	v_add_f32_e32 v6, v2, v6
	v_sub_f32_e32 v59, v156, v178
	v_add_f32_e32 v6, v4, v6
	v_mul_f32_e32 v59, 0x3fb8aa3b, v59
	v_add_f32_e32 v6, v3, v6
	v_exp_f32_e32 v104, v59
	v_sub_f32_e32 v59, v154, v178
	v_add_f32_e32 v58, v5, v6
	v_sub_f32_e32 v6, v151, v178
	v_sub_f32_e32 v7, v150, v178
	v_mul_f32_e32 v59, 0x3fb8aa3b, v59
	v_mul_f32_e32 v6, 0x3fb8aa3b, v6
	v_mul_f32_e32 v7, 0x3fb8aa3b, v7
	v_exp_f32_e32 v106, v59
	v_sub_f32_e32 v59, v160, v178
	v_exp_f32_e32 v6, v6
	v_exp_f32_e32 v8, v7
	v_sub_f32_e32 v7, v153, v178
	v_mul_f32_e32 v59, 0x3fb8aa3b, v59
	v_mul_f32_e32 v7, 0x3fb8aa3b, v7
	v_sub_f32_e32 v9, v152, v178
	v_exp_f32_e32 v105, v59
	v_sub_f32_e32 v59, v158, v178
	v_exp_f32_e32 v7, v7
	v_mul_f32_e32 v9, 0x3fb8aa3b, v9
	v_mul_f32_e32 v59, 0x3fb8aa3b, v59
	v_exp_f32_e32 v9, v9
	v_exp_f32_e32 v107, v59
	v_sub_f32_e32 v59, v164, v178
	v_add_f32_e32 v58, v6, v58
	v_mul_f32_e32 v59, 0x3fb8aa3b, v59
	v_add_f32_e32 v58, v8, v58
	v_exp_f32_e32 v108, v59
	v_sub_f32_e32 v59, v162, v178
	v_add_f32_e32 v58, v7, v58
	v_mul_f32_e32 v59, 0x3fb8aa3b, v59
	v_add_f32_e32 v58, v9, v58
	v_exp_f32_e32 v110, v59
	v_sub_f32_e32 v59, v168, v178
	v_add_f32_e32 v58, v104, v58
	v_mul_f32_e32 v59, 0x3fb8aa3b, v59
	v_add_f32_e32 v58, v106, v58
	v_exp_f32_e32 v109, v59
	v_sub_f32_e32 v59, v166, v178
	v_sub_f32_e32 v48, v48, v178
	v_sub_f32_e32 v34, v34, v178
	v_add_f32_e32 v58, v105, v58
	v_mul_f32_e32 v59, 0x3fb8aa3b, v59
	v_mul_f32_e32 v48, 0x3fb8aa3b, v48
	v_mul_f32_e32 v34, 0x3fb8aa3b, v34
	v_add_f32_e32 v58, v107, v58
	v_exp_f32_e32 v111, v59
	v_exp_f32_e32 v92, v48
	v_sub_f32_e32 v48, v49, v178
	v_sub_f32_e32 v46, v46, v178
	v_exp_f32_e32 v89, v34
	v_sub_f32_e32 v34, v35, v178
	v_sub_f32_e32 v35, v157, v178
	v_add_f32_e32 v58, v108, v58
	v_mul_f32_e32 v48, 0x3fb8aa3b, v48
	v_mul_f32_e32 v46, 0x3fb8aa3b, v46
	v_mul_f32_e32 v35, 0x3fb8aa3b, v35
	v_add_f32_e32 v58, v110, v58
	v_exp_f32_e32 v94, v48
	v_exp_f32_e32 v93, v46
	v_sub_f32_e32 v46, v47, v178
	v_sub_f32_e32 v44, v44, v178
	v_exp_f32_e32 v74, v35
	v_sub_f32_e32 v35, v155, v178
	v_add_f32_e32 v58, v109, v58
	v_mul_f32_e32 v46, 0x3fb8aa3b, v46
	v_mul_f32_e32 v44, 0x3fb8aa3b, v44
	v_mul_f32_e32 v35, 0x3fb8aa3b, v35
	v_add_f32_e32 v58, v111, v58
	v_exp_f32_e32 v95, v46
	v_exp_f32_e32 v96, v44
	v_sub_f32_e32 v44, v45, v178
	v_sub_f32_e32 v42, v42, v178
	v_exp_f32_e32 v76, v35
	v_sub_f32_e32 v35, v161, v178
	v_add_f32_e32 v46, v92, v58
	v_mul_f32_e32 v44, 0x3fb8aa3b, v44
	v_mul_f32_e32 v42, 0x3fb8aa3b, v42
	v_mul_f32_e32 v35, 0x3fb8aa3b, v35
	v_add_f32_e32 v46, v94, v46
	v_exp_f32_e32 v102, v44
	v_exp_f32_e32 v97, v42
	v_sub_f32_e32 v42, v43, v178
	v_sub_f32_e32 v40, v40, v178
	v_exp_f32_e32 v75, v35
	v_sub_f32_e32 v35, v159, v178
	v_add_f32_e32 v46, v93, v46
; #define LAS __attribute__((address_space(3)))
; __device__ __forceinline__ unsigned pk2(float lo, float hi) { return f2bf(lo) | (f2bf(hi) << 16); }
; __device__ __forceinline__ float shflx(float v, int mask, int lane) { return __int_as_float(__builtin_amdgcn_ds_bpermute((lane ^ mask) << 2, __float_as_int(v))); }
; __device__ __forceinline__ void attn_unit(const Args& A, const Ctx& C0, int l, int u_qrow0, int u_nq, int u_krow0, int u_krow1, int u_krow2, int u_g, const float* u_ck, const float* u_cv, unsigned u_vmask) {
;     ...
; #pragma unroll
;         for (int kt = 0; kt < 6; ++kt)
; #pragma unroll
;             for (int r = 0; r < 16; ++r) { const float e = __expf(sacc[kt][r] - mx); sacc[kt][r] = e; sum += e; }
;         sum += shflx(sum, 32, C.lane); sum += __expf(sink - mx);
;         const float inv = 1.f / sum;
;     ...
;         for (int kt = 0; kt < 6; ++kt) {
;             if ((u.vmask >> kt) & 1u) {
; #pragma unroll
;                 for (int s = 0; s < 2; ++s) {
;                     union { bf16x8 v; unsigned w[4]; } pf;
; #pragma unroll
;                     for (int e = 0; e < 4; ++e) pf.w[e] = pk2(sacc[kt][8 * s + 2 * e] * inv, sacc[kt][8 * s + 2 * e + 1] * inv);
; #pragma unroll
;                     for (int dt = 0; dt < 2; ++dt) { const LAS bf16* vp = Vt + (dt * 32 + li) * VP + kt * 32 + 16 * s + 4 * h;
;                         union { bf16x8 v; v2u w[2]; } vf; vf.w[0] = *(const LAS v2u*)vp; vf.w[1] = *(const LAS v2u*)(vp + 8);
;                         oacc[dt] = __builtin_amdgcn_mfma_f32_32x32x16_bf16(vf.v, pf.v, oacc[dt], 0, 0, 0); }
	v_mul_f32_e32 v42, 0x3fb8aa3b, v42
	v_mul_f32_e32 v40, 0x3fb8aa3b, v40
	v_mul_f32_e32 v35, 0x3fb8aa3b, v35
	v_add_f32_e32 v46, v95, v46
	v_exp_f32_e32 v103, v42
	v_exp_f32_e32 v84, v40
	v_sub_f32_e32 v40, v41, v178
	v_sub_f32_e32 v38, v38, v178
	v_exp_f32_e32 v77, v35
	v_sub_f32_e32 v35, v165, v178
	v_add_f32_e32 v42, v96, v46
	v_mul_f32_e32 v40, 0x3fb8aa3b, v40
	v_mul_f32_e32 v38, 0x3fb8aa3b, v38
	v_mul_f32_e32 v35, 0x3fb8aa3b, v35
	v_add_f32_e32 v42, v102, v42
	v_exp_f32_e32 v86, v40
	v_exp_f32_e32 v85, v38
	v_sub_f32_e32 v38, v39, v178
	v_sub_f32_e32 v36, v36, v178
	v_exp_f32_e32 v78, v35
	v_sub_f32_e32 v35, v163, v178
	v_add_f32_e32 v42, v97, v42
	v_mul_f32_e32 v38, 0x3fb8aa3b, v38
	v_mul_f32_e32 v36, 0x3fb8aa3b, v36
	v_mul_f32_e32 v35, 0x3fb8aa3b, v35
	v_add_f32_e32 v42, v103, v42
	v_exp_f32_e32 v87, v38
	v_exp_f32_e32 v88, v36
	v_sub_f32_e32 v36, v37, v178
	v_exp_f32_e32 v80, v35
	v_sub_f32_e32 v35, v169, v178
	v_add_f32_e32 v38, v84, v42
	v_mul_f32_e32 v36, 0x3fb8aa3b, v36
	v_mul_f32_e32 v35, 0x3fb8aa3b, v35
	v_add_f32_e32 v38, v86, v38
	v_exp_f32_e32 v90, v36
	v_exp_f32_e32 v79, v35
	v_sub_f32_e32 v35, v167, v178
	v_add_f32_e32 v38, v85, v38
	v_mul_f32_e32 v34, 0x3fb8aa3b, v34
	v_mul_f32_e32 v35, 0x3fb8aa3b, v35
	v_add_f32_e32 v38, v87, v38
	v_exp_f32_e32 v91, v34
	v_exp_f32_e32 v81, v35
	v_sub_f32_e32 v35, v171, v178
	v_add_f32_e32 v34, v88, v38
	v_mul_f32_e32 v35, 0x3fb8aa3b, v35
	v_add_f32_e32 v34, v90, v34
	v_exp_f32_e32 v66, v35
	v_sub_f32_e32 v35, v170, v178
	v_add_f32_e32 v34, v89, v34
	v_mul_f32_e32 v35, 0x3fb8aa3b, v35
	v_add_f32_e32 v34, v91, v34
	v_exp_f32_e32 v68, v35
	v_sub_f32_e32 v35, v173, v178
	v_add_f32_e32 v34, v74, v34
	v_mul_f32_e32 v35, 0x3fb8aa3b, v35
	v_add_f32_e32 v34, v76, v34
	v_exp_f32_e32 v67, v35
	v_sub_f32_e32 v35, v172, v178
	v_add_f32_e32 v34, v75, v34
	v_mul_f32_e32 v35, 0x3fb8aa3b, v35
	v_add_f32_e32 v34, v77, v34
	v_exp_f32_e32 v69, v35
	v_sub_f32_e32 v35, v175, v178
	v_add_f32_e32 v34, v78, v34
	v_mul_f32_e32 v35, 0x3fb8aa3b, v35
	v_add_f32_e32 v34, v80, v34
	v_exp_f32_e32 v70, v35
	v_sub_f32_e32 v35, v174, v178
	v_add_f32_e32 v34, v79, v34
	v_mul_f32_e32 v35, 0x3fb8aa3b, v35
	v_add_f32_e32 v34, v81, v34
	v_exp_f32_e32 v72, v35
	v_sub_f32_e32 v35, v177, v178
	v_add_f32_e32 v34, v66, v34
	v_mul_f32_e32 v35, 0x3fb8aa3b, v35
	v_add_f32_e32 v34, v68, v34
	v_exp_f32_e32 v71, v35
	v_sub_f32_e32 v35, v176, v178
	v_add_f32_e32 v34, v67, v34
	v_mul_f32_e32 v35, 0x3fb8aa3b, v35
	v_add_f32_e32 v34, v69, v34
	v_exp_f32_e32 v73, v35
	v_add_f32_e32 v34, v70, v34
	v_add_f32_e32 v34, v72, v34
	v_add_f32_e32 v34, v71, v34
	v_add_f32_e32 v34, v73, v34
	ds_bpermute_b32 v35, v189, v34
	v_sub_f32_e32 v36, v186, v178
	v_mul_f32_e32 v36, 0x3fb8aa3b, v36
	v_exp_f32_e32 v36, v36
	s_waitcnt lgkmcnt(0)
	v_add_f32_e32 v34, v34, v35
	v_add_f32_e32 v34, v36, v34
	v_div_scale_f32 v35, s[2:3], v34, v34, 1.0
	v_rcp_f32_e32 v36, v35
	s_nop 0
	v_fma_f32 v37, -v35, v36, 1.0
	v_fmac_f32_e32 v36, v37, v36
	v_div_scale_f32 v37, vcc, 1.0, v34, 1.0
	v_mul_f32_e32 v38, v37, v36
	v_fma_f32 v39, -v35, v38, v37
	v_fmac_f32_e32 v38, v39, v36
	v_fma_f32 v35, -v35, v38, v37
	v_div_fmas_f32 v35, v35, v36, v38
	s_and_b64 vcc, exec, s[38:39]
	v_div_fixup_f32 v82, v35, v34, 1.0
	s_cbranch_vccnz .LBB0_655
	v_pk_mul_f32 v[36:37], v[52:53], v[82:83] op_sel_hi:[1,0]
	v_pk_mul_f32 v[40:41], v[56:57], v[82:83] op_sel_hi:[1,0]
	v_pk_mul_f32 v[34:35], v[50:51], v[82:83] op_sel_hi:[1,0]
	v_pk_mul_f32 v[38:39], v[54:55], v[82:83] op_sel_hi:[1,0]
	s_nop 0
	s_nop 0
	v_bfe_u32 v44, v37, 16, 1
	v_bfe_u32 v45, v36, 16, 1
	v_add3_u32 v45, v36, v45, s33
	v_add3_u32 v44, v37, v44, s33
	s_nop 0
	s_nop 0
	v_bfe_u32 v36, v34, 16, 1
	v_bfe_u32 v37, v35, 16, 1
	s_nop 0
	s_nop 0
	s_nop 0
	s_nop 0
	v_add3_u32 v42, v35, v37, s33
	v_add3_u32 v43, v34, v36, s33
	ds_read2_b64 v[34:37], v129 offset0:128 offset1:130
	v_lshrrev_b32_e32 v43, 16, v43
	v_lshrrev_b32_e32 v42, 16, v42
	s_nop 0
	s_nop 0
	v_pk_mul_f32 v[126:127], v[126:127], v[82:83] op_sel_hi:[1,0]
	v_cvt_pk_bf16_f32 v41, v39, v41
	v_cvt_pk_bf16_f32 v40, v38, v40
	v_and_or_b32 v39, v44, s96, v42
	v_and_or_b32 v38, v45, s96, v43
	v_pk_mul_f32 v[120:121], v[120:121], v[82:83] op_sel_hi:[1,0]
	v_pk_mul_f32 v[122:123], v[122:123], v[82:83] op_sel_hi:[1,0]
	v_pk_mul_f32 v[124:125], v[124:125], v[82:83] op_sel_hi:[1,0]
	s_nop 0
	s_waitcnt lgkmcnt(0)
	v_mfma_f32_32x32x16_bf16 v[50:65], v[34:37], v[38:41], 0
	ds_read2_b64 v[34:37], v128 offset0:128 offset1:130
	ds_read2_b64 v[148:151], v129 offset0:132 offset1:134
	s_nop 0
	s_nop 0
	s_nop 0
	s_nop 0
	s_nop 0
	s_nop 0
	s_nop 0
	s_nop 0
	s_nop 0
	s_nop 0
	s_nop 0
	v_cvt_pk_bf16_f32 v120, v120, v122
	v_cvt_pk_bf16_f32 v122, v124, v126
	s_nop 0
	s_nop 0
	s_nop 0
	s_nop 0
	s_nop 0
	s_nop 0
	s_nop 0
	v_cvt_pk_bf16_f32 v121, v121, v123
	v_cvt_pk_bf16_f32 v123, v125, v127
	ds_read2_b64 v[124:127], v128 offset0:132 offset1:134
	s_waitcnt lgkmcnt(0)
	v_mfma_f32_32x32x16_bf16 v[34:49], v[34:37], v[38:41], 0
	s_nop 0
	s_nop 0
	s_nop 0
	s_nop 0
	s_nop 0
	s_nop 1
	v_mfma_f32_32x32x16_bf16 v[50:65], v[148:151], v[120:123], v[50:65]
	v_mfma_f32_32x32x16_bf16 v[34:49], v[124:127], v[120:123], v[34:49]
	s_branch .LBB0_656

; #define LAS __attribute__((address_space(3)))
; __device__ __forceinline__ unsigned pk2(float lo, float hi) { return f2bf(lo) | (f2bf(hi) << 16); }
; __device__ __forceinline__ void attn_unit(const Args& A, const Ctx& C0, int l, int u_qrow0, int u_nq, int u_krow0, int u_krow1, int u_krow2, int u_g, const float* u_ck, const float* u_cv, unsigned u_vmask) {
;     ...
;         for (int kt = 0; kt < 6; ++kt) {
;             if ((u.vmask >> kt) & 1u) {
; #pragma unroll
;                 for (int s = 0; s < 2; ++s) {
;                     union { bf16x8 v; unsigned w[4]; } pf;
; #pragma unroll
;                     for (int e = 0; e < 4; ++e) pf.w[e] = pk2(sacc[kt][8 * s + 2 * e] * inv, sacc[kt][8 * s + 2 * e + 1] * inv);
; #pragma unroll
;                     for (int dt = 0; dt < 2; ++dt) { const LAS bf16* vp = Vt + (dt * 32 + li) * VP + kt * 32 + 16 * s + 4 * h;
;                         union { bf16x8 v; v2u w[2]; } vf; vf.w[0] = *(const LAS v2u*)vp; vf.w[1] = *(const LAS v2u*)(vp + 8);
;                         oacc[dt] = __builtin_amdgcn_mfma_f32_32x32x16_bf16(vf.v, pf.v, oacc[dt], 0, 0, 0); }
.LBB0_656:
	s_and_b64 vcc, exec, s[40:41]
	s_cbranch_vccnz .LBB0_658
	v_pk_mul_f32 v[114:115], v[114:115], v[82:83] op_sel_hi:[1,0]
	v_pk_mul_f32 v[118:119], v[118:119], v[82:83] op_sel_hi:[1,0]
	v_pk_mul_f32 v[112:113], v[112:113], v[82:83] op_sel_hi:[1,0]
	v_pk_mul_f32 v[116:117], v[116:117], v[82:83] op_sel_hi:[1,0]
	v_bfe_u32 v83, v119, 16, 1
	s_nop 0
	v_bfe_u32 v121, v115, 16, 1
	v_bfe_u32 v122, v114, 16, 1
	v_add3_u32 v122, v114, v122, s33
	v_add3_u32 v121, v115, v121, s33
	s_nop 0
	v_add3_u32 v83, v119, v83, s33
	v_bfe_u32 v114, v112, 16, 1
	v_bfe_u32 v115, v113, 16, 1
	s_nop 0
	v_bfe_u32 v120, v117, 16, 1
	v_add3_u32 v117, v117, v120, s33
	s_nop 0
	v_add3_u32 v119, v113, v115, s33
	v_add3_u32 v120, v112, v114, s33
	ds_read2_b64 v[112:115], v129 offset0:136 offset1:138
	v_lshrrev_b32_e32 v120, 16, v120
	v_lshrrev_b32_e32 v123, 16, v119
	s_nop 0
	v_lshrrev_b32_e32 v117, 16, v117
	v_and_or_b32 v119, v83, s96, v117
	v_cvt_pk_bf16_f32 v118, v116, v118
	v_and_or_b32 v117, v121, s96, v123
	v_and_or_b32 v116, v122, s96, v120
	v_pk_mul_f32 v[28:29], v[28:29], v[82:83] op_sel_hi:[1,0]
	v_pk_mul_f32 v[32:33], v[32:33], v[82:83] op_sel_hi:[1,0]
	s_waitcnt lgkmcnt(0)
	v_mfma_f32_32x32x16_bf16 v[50:65], v[112:115], v[116:119], v[50:65]
	ds_read2_b64 v[112:115], v128 offset0:136 offset1:138
	ds_read2_b64 v[120:123], v129 offset0:140 offset1:142
	v_mul_f32_e64 v26, v26, v82
	v_mul_f32_e64 v27, v27, v82
	v_mul_f32_e64 v30, v30, v82
	v_mul_f32_e64 v31, v31, v82
	s_nop 0
	s_waitcnt lgkmcnt(0)
	v_mfma_f32_32x32x16_bf16 v[34:49], v[112:115], v[116:119], v[34:49]
	s_nop 0
	v_bfe_u32 v113, v29, 16, 1
	v_bfe_u32 v114, v28, 16, 1
	v_add3_u32 v114, v28, v114, s33
	v_add3_u32 v113, v29, v113, s33
	s_nop 0
	s_nop 0
	s_nop 0
	s_nop 0
	s_nop 0
	s_nop 0
	v_cvt_pk_bf16_f32 v28, v30, v32
	v_bfe_u32 v32, v26, 16, 1
	v_cvt_pk_bf16_f32 v29, v31, v33
	v_bfe_u32 v33, v27, 16, 1
	s_nop 0
	s_nop 0
	v_add3_u32 v27, v27, v33, s33
	v_add3_u32 v26, v26, v32, s33
	s_nop 0
	s_nop 0
	ds_read2_b64 v[30:33], v128 offset0:140 offset1:142
	v_lshrrev_b32_e32 v26, 16, v26
	v_lshrrev_b32_e32 v27, 16, v27
	v_and_or_b32 v27, v113, s96, v27
	v_and_or_b32 v26, v114, s96, v26
	s_nop 1
	v_mfma_f32_32x32x16_bf16 v[50:65], v[120:123], v[26:29], v[50:65]
	s_waitcnt lgkmcnt(0)
	v_mfma_f32_32x32x16_bf16 v[34:49], v[30:33], v[26:29], v[34:49]
.LBB0_658:
	s_and_b64 vcc, exec, s[44:45]
	s_cbranch_vccnz .LBB0_660
	v_pk_mul_f32 v[20:21], v[20:21], v[82:83] op_sel_hi:[1,0]
	v_pk_mul_f32 v[24:25], v[24:25], v[82:83] op_sel_hi:[1,0]
	v_pk_mul_f32 v[18:19], v[18:19], v[82:83] op_sel_hi:[1,0]
	v_pk_mul_f32 v[22:23], v[22:23], v[82:83] op_sel_hi:[1,0]
	s_nop 0
	s_nop 0
	v_bfe_u32 v28, v21, 16, 1
	v_bfe_u32 v29, v20, 16, 1
	v_add3_u32 v29, v20, v29, s33
	v_add3_u32 v28, v21, v28, s33
	s_nop 0
	s_nop 0
	v_bfe_u32 v20, v18, 16, 1
	v_bfe_u32 v21, v19, 16, 1
	s_nop 0
	s_nop 0
	s_nop 0
	s_nop 0
	v_add3_u32 v26, v19, v21, s33
	v_add3_u32 v27, v18, v20, s33
	ds_read2_b64 v[18:21], v129 offset0:144 offset1:146
	v_lshrrev_b32_e32 v27, 16, v27
	v_lshrrev_b32_e32 v26, 16, v26
	s_nop 0
	s_nop 0
	v_cvt_pk_bf16_f32 v25, v23, v25
	v_cvt_pk_bf16_f32 v24, v22, v24
	v_and_or_b32 v23, v28, s96, v26
	v_and_or_b32 v22, v29, s96, v27
	v_pk_mul_f32 v[12:13], v[12:13], v[82:83] op_sel_hi:[1,0]
	v_pk_mul_f32 v[16:17], v[16:17], v[82:83] op_sel_hi:[1,0]
	s_waitcnt lgkmcnt(0)
	v_mfma_f32_32x32x16_bf16 v[50:65], v[18:21], v[22:25], v[50:65]
	ds_read2_b64 v[18:21], v128 offset0:144 offset1:146
	ds_read2_b64 v[26:29], v129 offset0:148 offset1:150
	v_mul_f32_e64 v14, v14, v82
	v_mul_f32_e64 v15, v15, v82
	v_mul_f32_e64 v10, v10, v82
	v_mul_f32_e64 v11, v11, v82
	s_waitcnt lgkmcnt(0)
	v_mfma_f32_32x32x16_bf16 v[34:49], v[18:21], v[22:25], v[34:49]
	s_nop 0
	s_nop 0
	v_bfe_u32 v20, v13, 16, 1
	v_bfe_u32 v21, v12, 16, 1
	v_add3_u32 v21, v12, v21, s33
	v_add3_u32 v20, v13, v20, s33
	s_nop 0
	s_nop 0
	s_nop 0
	s_nop 0
	s_nop 0
	s_nop 0
	v_cvt_pk_bf16_f32 v12, v14, v16
	v_bfe_u32 v16, v10, 16, 1
	v_cvt_pk_bf16_f32 v13, v15, v17
	v_bfe_u32 v17, v11, 16, 1
	s_nop 0
	s_nop 0
	v_add3_u32 v11, v11, v17, s33
	v_add3_u32 v10, v10, v16, s33
	s_nop 0
	s_nop 0
	ds_read2_b64 v[14:17], v128 offset0:148 offset1:150
	v_lshrrev_b32_e32 v10, 16, v10
	v_lshrrev_b32_e32 v11, 16, v11
	v_and_or_b32 v11, v20, s96, v11
	v_and_or_b32 v10, v21, s96, v10
	s_nop 1
	v_mfma_f32_32x32x16_bf16 v[50:65], v[26:29], v[10:13], v[50:65]
	s_waitcnt lgkmcnt(0)
	v_mfma_f32_32x32x16_bf16 v[34:49], v[14:17], v[10:13], v[34:49]
.LBB0_660:
	s_and_b64 vcc, exec, s[60:61]
	s_cbranch_vccz .LBB0_662
	v_pk_mul_f32 v[4:5], v[4:5], v[82:83] op_sel_hi:[1,0]
	v_pk_mul_f32 v[8:9], v[8:9], v[82:83] op_sel_hi:[1,0]
	v_pk_mul_f32 v[2:3], v[2:3], v[82:83] op_sel_hi:[1,0]
	v_pk_mul_f32 v[6:7], v[6:7], v[82:83] op_sel_hi:[1,0]
	s_nop 0
	s_nop 0
	s_nop 0
	s_nop 0
	s_nop 0
	s_nop 0
	s_nop 0
	s_nop 0
	s_nop 0
	s_nop 0
	s_nop 0
	s_nop 0
	s_nop 0
	s_nop 0
	s_nop 0
	s_nop 0
	v_cvt_pk_bf16_f32 v113, v3, v5
	v_cvt_pk_bf16_f32 v112, v2, v4
	ds_read2_b64 v[2:5], v129 offset0:152 offset1:154
	ds_read2_b64 v[116:119], v128 offset0:152 offset1:154
	ds_read2_b64 v[120:123], v129 offset0:156 offset1:158
	s_nop 0
	s_nop 0
	s_nop 0
	s_nop 0
	v_pk_mul_f32 v[110:111], v[110:111], v[82:83] op_sel_hi:[1,0]
	v_cvt_pk_bf16_f32 v115, v7, v9
	v_cvt_pk_bf16_f32 v114, v6, v8
	s_nop 0
	s_nop 0
	v_pk_mul_f32 v[104:105], v[104:105], v[82:83] op_sel_hi:[1,0]
	v_pk_mul_f32 v[106:107], v[106:107], v[82:83] op_sel_hi:[1,0]
	v_pk_mul_f32 v[108:109], v[108:109], v[82:83] op_sel_hi:[1,0]
	s_nop 0
	s_waitcnt lgkmcnt(0)
	v_mfma_f32_32x32x16_bf16 v[18:33], v[2:5], v[112:115], v[50:65]
	s_nop 0
	s_nop 0
	s_nop 0
	s_nop 0
	v_mfma_f32_32x32x16_bf16 v[2:17], v[116:119], v[112:115], v[34:49]
	s_nop 0
	s_nop 0
	s_nop 0
	s_nop 0
	s_nop 0
	s_nop 0
	s_nop 0
	s_nop 0
	v_cvt_pk_bf16_f32 v104, v104, v106
	v_cvt_pk_bf16_f32 v106, v108, v110
	s_nop 0
	s_nop 0
	s_nop 0
	s_nop 0
	s_nop 0
	s_nop 0
	v_cvt_pk_bf16_f32 v105, v105, v107
	v_cvt_pk_bf16_f32 v107, v109, v111
	ds_read2_b64 v[108:111], v128 offset0:156 offset1:158
	s_nop 0
	s_nop 0
	s_nop 0
	s_nop 0
	s_nop 0
	s_nop 1
	v_mfma_f32_32x32x16_bf16 v[18:33], v[120:123], v[104:107], v[18:33]
	s_waitcnt lgkmcnt(0)
	v_mfma_f32_32x32x16_bf16 v[2:17], v[108:111], v[104:107], v[2:17]
	s_cbranch_execz .LBB0_663
	s_branch .LBB0_664

; #define LAS __attribute__((address_space(3)))
; __device__ __forceinline__ unsigned pk2(float lo, float hi) { return f2bf(lo) | (f2bf(hi) << 16); }
; __device__ __forceinline__ void attn_unit(const Args& A, const Ctx& C0, int l, int u_qrow0, int u_nq, int u_krow0, int u_krow1, int u_krow2, int u_g, const float* u_ck, const float* u_cv, unsigned u_vmask) {
;     ...
;         for (int kt = 0; kt < 6; ++kt) {
;             if ((u.vmask >> kt) & 1u) {
; #pragma unroll
;                 for (int s = 0; s < 2; ++s) {
;                     union { bf16x8 v; unsigned w[4]; } pf;
; #pragma unroll
;                     for (int e = 0; e < 4; ++e) pf.w[e] = pk2(sacc[kt][8 * s + 2 * e] * inv, sacc[kt][8 * s + 2 * e + 1] * inv);
; #pragma unroll
;                     for (int dt = 0; dt < 2; ++dt) { const LAS bf16* vp = Vt + (dt * 32 + li) * VP + kt * 32 + 16 * s + 4 * h;
;                         union { bf16x8 v; v2u w[2]; } vf; vf.w[0] = *(const LAS v2u*)vp; vf.w[1] = *(const LAS v2u*)(vp + 8);
;                         oacc[dt] = __builtin_amdgcn_mfma_f32_32x32x16_bf16(vf.v, pf.v, oacc[dt], 0, 0, 0); }
.LBB0_664:
	v_mov_b32_e32 v83, v82
	v_pk_mul_f32 v[36:37], v[94:95], v[82:83]
	v_pk_mul_f32 v[40:41], v[102:103], v[82:83]
	v_pk_mul_f32 v[34:35], v[92:93], v[82:83]
	v_pk_mul_f32 v[38:39], v[96:97], v[82:83]
	s_nop 0
	s_nop 0
	v_bfe_u32 v44, v37, 16, 1
	v_bfe_u32 v45, v36, 16, 1
	v_add3_u32 v45, v36, v45, s33
	v_add3_u32 v44, v37, v44, s33
	s_nop 0
	s_nop 0
	v_bfe_u32 v36, v34, 16, 1
	v_bfe_u32 v37, v35, 16, 1
	s_nop 0
	s_nop 0
	s_nop 0
	s_nop 0
	v_add3_u32 v42, v35, v37, s33
	v_add3_u32 v43, v34, v36, s33
	ds_read2_b64 v[34:37], v129 offset0:160 offset1:162
	v_lshrrev_b32_e32 v43, 16, v43
	v_lshrrev_b32_e32 v42, 16, v42
	s_nop 0
	s_nop 0
	v_cvt_pk_bf16_f32 v41, v39, v41
	v_cvt_pk_bf16_f32 v40, v38, v40
	v_and_or_b32 v39, v44, s96, v42
	v_and_or_b32 v38, v45, s96, v43
	s_and_b64 vcc, exec, s[42:43]
	s_waitcnt lgkmcnt(0)
	v_mfma_f32_32x32x16_bf16 v[18:33], v[34:37], v[38:41], v[18:33]
	ds_read2_b64 v[34:37], v128 offset0:160 offset1:162
	ds_read2_b64 v[42:45], v129 offset0:164 offset1:166
	s_waitcnt lgkmcnt(0)
	v_mfma_f32_32x32x16_bf16 v[2:17], v[34:37], v[38:41], v[2:17]
	v_mul_f32_e64 v36, v86, v82
	v_mul_f32_e64 v37, v87, v83
	v_mul_f32_e64 v40, v90, v82
	v_mul_f32_e64 v41, v91, v83
	v_mul_f32_e64 v38, v88, v82
	v_mul_f32_e64 v39, v89, v83
	s_nop 0
	s_nop 0
	v_bfe_u32 v48, v37, 16, 1
	v_bfe_u32 v49, v36, 16, 1
	v_add3_u32 v49, v36, v49, s33
	v_add3_u32 v48, v37, v48, s33
	s_nop 0
	s_nop 0
	s_nop 0
	s_nop 0
	v_pk_mul_f32 v[34:35], v[84:85], v[82:83]
	s_nop 0
	s_nop 0
	v_cvt_pk_bf16_f32 v36, v38, v40
	v_bfe_u32 v40, v34, 16, 1
	v_cvt_pk_bf16_f32 v37, v39, v41
	v_bfe_u32 v41, v35, 16, 1
	s_nop 0
	s_nop 0
	v_add3_u32 v35, v35, v41, s33
	v_add3_u32 v34, v34, v40, s33
	s_nop 0
	s_nop 0
	ds_read2_b64 v[38:41], v128 offset0:164 offset1:166
	v_lshrrev_b32_e32 v34, 16, v34
	v_lshrrev_b32_e32 v35, 16, v35
	v_and_or_b32 v35, v48, s96, v35
	v_and_or_b32 v34, v49, s96, v34
	s_nop 1
	v_mfma_f32_32x32x16_bf16 v[18:33], v[42:45], v[34:37], v[18:33]
	s_waitcnt lgkmcnt(0)
	v_mfma_f32_32x32x16_bf16 v[2:17], v[38:41], v[34:37], v[2:17]
	s_cbranch_vccnz .LBB0_666
	v_pk_mul_f32 v[36:37], v[76:77], v[82:83]
	v_pk_mul_f32 v[40:41], v[80:81], v[82:83]
	v_pk_mul_f32 v[34:35], v[74:75], v[82:83]
	v_pk_mul_f32 v[38:39], v[78:79], v[82:83]
	s_nop 0
	s_nop 0
	v_bfe_u32 v44, v37, 16, 1
	v_bfe_u32 v45, v36, 16, 1
	v_add3_u32 v45, v36, v45, s33
	v_add3_u32 v44, v37, v44, s33
	s_nop 0
	s_nop 0
	v_bfe_u32 v36, v34, 16, 1
	v_bfe_u32 v37, v35, 16, 1
	s_nop 0
	s_nop 0
	s_nop 0
	s_nop 0
	v_add3_u32 v42, v35, v37, s33
	v_add3_u32 v43, v34, v36, s33
	ds_read2_b64 v[34:37], v129 offset0:168 offset1:170
	v_lshrrev_b32_e32 v43, 16, v43
	v_lshrrev_b32_e32 v42, 16, v42
	s_nop 0
	s_nop 0
	v_cvt_pk_bf16_f32 v41, v39, v41
	v_cvt_pk_bf16_f32 v40, v38, v40
	v_and_or_b32 v39, v44, s96, v42
	v_and_or_b32 v38, v45, s96, v43
	s_waitcnt lgkmcnt(0)
	s_nop 0
	v_mfma_f32_32x32x16_bf16 v[18:33], v[34:37], v[38:41], v[18:33]
	ds_read2_b64 v[34:37], v128 offset0:168 offset1:170
	ds_read2_b64 v[42:45], v129 offset0:172 offset1:174
	s_waitcnt lgkmcnt(0)
	v_mfma_f32_32x32x16_bf16 v[2:17], v[34:37], v[38:41], v[2:17]
	v_mul_f32_e64 v36, v68, v82
	v_mul_f32_e64 v37, v69, v83
	v_mul_f32_e64 v40, v72, v82
	v_mul_f32_e64 v41, v73, v83
	v_mul_f32_e64 v38, v70, v82
	v_mul_f32_e64 v39, v71, v83
	s_nop 0
	s_nop 0
	v_bfe_u32 v48, v37, 16, 1
	v_bfe_u32 v49, v36, 16, 1
	v_add3_u32 v49, v36, v49, s33
	v_add3_u32 v48, v37, v48, s33
	s_nop 0
	s_nop 0
	s_nop 0
	s_nop 0
	v_pk_mul_f32 v[34:35], v[66:67], v[82:83]
	s_nop 0
	s_nop 0
	v_cvt_pk_bf16_f32 v36, v38, v40
	v_bfe_u32 v40, v34, 16, 1
	v_cvt_pk_bf16_f32 v37, v39, v41
	v_bfe_u32 v41, v35, 16, 1
	s_nop 0
	s_nop 0
	v_add3_u32 v35, v35, v41, s33
	v_add3_u32 v34, v34, v40, s33
	s_nop 0
	s_nop 0
	ds_read2_b64 v[38:41], v128 offset0:172 offset1:174
	v_lshrrev_b32_e32 v34, 16, v34
	v_lshrrev_b32_e32 v35, 16, v35
	v_and_or_b32 v35, v48, s96, v35
	v_and_or_b32 v34, v49, s96, v34
	s_nop 1
	v_mfma_f32_32x32x16_bf16 v[18:33], v[42:45], v[34:37], v[18:33]
	s_waitcnt lgkmcnt(0)
	v_mfma_f32_32x32x16_bf16 v[2:17], v[38:41], v[34:37], v[2:17]

; __device__ __forceinline__ unsigned pk2(float lo, float hi) { return f2bf(lo) | (f2bf(hi) << 16); }
; __device__ __forceinline__ void attn_unit(const Args& A, const Ctx& C0, int l, int u_qrow0, int u_nq, int u_krow0, int u_krow1, int u_krow2, int u_g, const float* u_ck, const float* u_cv, unsigned u_vmask) {
;     ...
;         for (int it = 0; it < 3; ++it) { const int idx = C.tid + 512 * it; const int j = idx >> 3, part = idx & 7;
;             kx[it] = (v4u){0u, 0u, 0u, 0u}; vx[it] = kx[it];
;             if ((u.vmask >> (j >> 5)) & 1u) {
;                 if (u.ck && j < 128) { const float* pk = u.ck + (size_t)j * 128 + part * 8; const float* pv = u.cv + (size_t)j * 128 + part * 8;
;                     const f32x4 a0 = *(const f32x4*)pk, a1 = *(const f32x4*)(pk + 4), b0 = *(const f32x4*)pv, b1 = *(const f32x4*)(pv + 4);
;                     kx[it] = (v4u){pk2(a0.x, a0.y), pk2(a0.z, a0.w), pk2(a1.x, a1.y), pk2(a1.z, a1.w)}; vx[it] = (v4u){pk2(b0.x, b0.y), pk2(b0.z, b0.w), pk2(b1.x, b1.y), pk2(b1.z, b1.w)}; }
;                 else { const int ch = j >> 6; const int kr = (ch == 0 ? u.krow0 : (ch == 1 ? u.krow1 : u.krow2)) + (j & 63);
;                     kx[it] = *(const v4u*)(U + (size_t)kr * DIN + C_K + u.g * 64 + part * 8); vx[it] = *(const v4u*)(U + (size_t)kr * DIN + C_V + u.g * 64 + part * 8); }
;             } }
.LBB0_705:
	s_andn2_saveexec_b64 s[30:31], s[2:3]
	s_cbranch_execz .LBB0_709
	s_andn2_b64 vcc, exec, s[64:65]
	s_cbranch_vccnz .LBB0_708
	v_lshlrev_b32_e32 v4, 9, v30
	v_ashrrev_i32_e32 v5, 31, v4
	s_waitcnt vmcnt(0) lgkmcnt(0)
	v_lshl_add_u64 v[8:9], v[4:5], 2, v[26:27]
	global_load_dwordx4 v[4:7], v[8:9], off
	s_nop 0
	global_load_dwordx4 v[8:11], v[8:9], off offset:16
	s_waitcnt vmcnt(1)
	s_nop 0
	s_nop 0
	s_nop 0
	s_nop 0
	s_waitcnt vmcnt(0)
	s_nop 0
	s_nop 0
	s_nop 0
	s_nop 0
	s_nop 0
	s_nop 0
	v_cvt_pk_bf16_f32 v241, v4, v5
	s_nop 0
	s_nop 0
	v_cvt_pk_bf16_f32 v242, v6, v7
	s_nop 0
	s_nop 0
	s_nop 0
	v_cvt_pk_bf16_f32 v8, v8, v9
	s_nop 0
	s_nop 0
	s_nop 0
	s_nop 0
	s_nop 0
	v_mov_b32_e32 v6, v241
	v_mov_b32_e32 v7, v242
	s_nop 0
	v_cvt_pk_bf16_f32 v9, v10, v11
	s_branch .LBB0_709

; __device__ __forceinline__ unsigned pk2(float lo, float hi) { return f2bf(lo) | (f2bf(hi) << 16); }
; __device__ __forceinline__ void attn_unit(const Args& A, const Ctx& C0, int l, int u_qrow0, int u_nq, int u_krow0, int u_krow1, int u_krow2, int u_g, const float* u_ck, const float* u_cv, unsigned u_vmask) {
;     ...
;         for (int it = 0; it < 3; ++it) { const int idx = C.tid + 512 * it; const int j = idx >> 3, part = idx & 7;
;             kx[it] = (v4u){0u, 0u, 0u, 0u}; vx[it] = kx[it];
;             if ((u.vmask >> (j >> 5)) & 1u) {
;                 if (u.ck && j < 128) { const float* pk = u.ck + (size_t)j * 128 + part * 8; const float* pv = u.cv + (size_t)j * 128 + part * 8;
;                     const f32x4 a0 = *(const f32x4*)pk, a1 = *(const f32x4*)(pk + 4), b0 = *(const f32x4*)pv, b1 = *(const f32x4*)(pv + 4);
;                     kx[it] = (v4u){pk2(a0.x, a0.y), pk2(a0.z, a0.w), pk2(a1.x, a1.y), pk2(a1.z, a1.w)}; vx[it] = (v4u){pk2(b0.x, b0.y), pk2(b0.z, b0.w), pk2(b1.x, b1.y), pk2(b1.z, b1.w)}; }
;                 else { const int ch = j >> 6; const int kr = (ch == 0 ? u.krow0 : (ch == 1 ? u.krow1 : u.krow2)) + (j & 63);
;                     kx[it] = *(const v4u*)(U + (size_t)kr * DIN + C_K + u.g * 64 + part * 8); vx[it] = *(const v4u*)(U + (size_t)kr * DIN + C_V + u.g * 64 + part * 8); }
;             } }
.LBB0_713:
	s_andn2_saveexec_b64 s[30:31], s[2:3]
	s_cbranch_execz .LBB0_717
	s_andn2_b64 vcc, exec, s[64:65]
	s_cbranch_vccnz .LBB0_716
	v_lshlrev_b32_e32 v4, 9, v32
	v_ashrrev_i32_e32 v5, 31, v4
	v_lshl_add_u64 v[4:5], v[4:5], 2, v[26:27]
	s_waitcnt lgkmcnt(0)
	global_load_dwordx4 v[10:13], v[4:5], off
	global_load_dwordx4 v[14:17], v[4:5], off offset:16
	s_waitcnt vmcnt(0)
	s_nop 0
	s_nop 0
	s_nop 0
	s_nop 0
	s_nop 0
	s_nop 0
	s_nop 0
	s_nop 0
	s_nop 0
	s_nop 0
	s_nop 0
	v_cvt_pk_bf16_f32 v241, v10, v11
	s_nop 0
	s_nop 0
	s_nop 0
	v_cvt_pk_bf16_f32 v242, v12, v13
	s_nop 0
	s_nop 0
	s_nop 0
	s_nop 0
	s_nop 0
	v_cvt_pk_bf16_f32 v12, v14, v15
	s_nop 0
	v_mov_b32_e32 v10, v241
	v_mov_b32_e32 v11, v242
	s_nop 0
	v_cvt_pk_bf16_f32 v13, v16, v17
	s_branch .LBB0_717

; __device__ __forceinline__ unsigned pk2(float lo, float hi) { return f2bf(lo) | (f2bf(hi) << 16); }
; __device__ __forceinline__ void attn_unit(const Args& A, const Ctx& C0, int l, int u_qrow0, int u_nq, int u_krow0, int u_krow1, int u_krow2, int u_g, const float* u_ck, const float* u_cv, unsigned u_vmask) {
;     ...
;         for (int it = 0; it < 3; ++it) { const int idx = C.tid + 512 * it; const int j = idx >> 3, part = idx & 7;
;             kx[it] = (v4u){0u, 0u, 0u, 0u}; vx[it] = kx[it];
;             if ((u.vmask >> (j >> 5)) & 1u) {
;                 if (u.ck && j < 128) { const float* pk = u.ck + (size_t)j * 128 + part * 8; const float* pv = u.cv + (size_t)j * 128 + part * 8;
;                     const f32x4 a0 = *(const f32x4*)pk, a1 = *(const f32x4*)(pk + 4), b0 = *(const f32x4*)pv, b1 = *(const f32x4*)(pv + 4);
;                     kx[it] = (v4u){pk2(a0.x, a0.y), pk2(a0.z, a0.w), pk2(a1.x, a1.y), pk2(a1.z, a1.w)}; vx[it] = (v4u){pk2(b0.x, b0.y), pk2(b0.z, b0.w), pk2(b1.x, b1.y), pk2(b1.z, b1.w)}; }
;                 else { const int ch = j >> 6; const int kr = (ch == 0 ? u.krow0 : (ch == 1 ? u.krow1 : u.krow2)) + (j & 63);
;                     kx[it] = *(const v4u*)(U + (size_t)kr * DIN + C_K + u.g * 64 + part * 8); vx[it] = *(const v4u*)(U + (size_t)kr * DIN + C_V + u.g * 64 + part * 8); }
;             } }
.LBB0_721:
	s_andn2_saveexec_b64 s[30:31], s[2:3]
	s_cbranch_execz .LBB0_725
	s_andn2_b64 vcc, exec, s[64:65]
	s_cbranch_vccnz .LBB0_724
	s_waitcnt vmcnt(0) lgkmcnt(0)
	v_lshlrev_b32_e32 v2, 9, v33
	v_ashrrev_i32_e32 v3, 31, v2
	v_lshl_add_u64 v[14:15], v[2:3], 2, v[26:27]
	global_load_dwordx4 v[2:5], v[14:15], off
	s_nop 0
	global_load_dwordx4 v[14:17], v[14:15], off offset:16
	s_waitcnt vmcnt(1)
	s_nop 0
	s_nop 0
	s_nop 0
	s_nop 0
	s_waitcnt vmcnt(0)
	s_nop 0
	s_nop 0
	s_nop 0
	s_nop 0
	s_nop 0
	s_nop 0
	v_cvt_pk_bf16_f32 v2, v2, v3
	s_nop 0
	s_nop 0
	v_cvt_pk_bf16_f32 v3, v4, v5
	s_nop 0
	s_nop 0
	v_cvt_pk_bf16_f32 v4, v14, v15
	s_nop 0
	s_nop 0
	s_nop 0
	s_nop 0
	s_nop 0
	s_nop 0
	s_nop 0
	s_nop 0
	s_nop 0
	v_cvt_pk_bf16_f32 v5, v16, v17
	s_branch .LBB0_725

; __device__ __forceinline__ unsigned pk2(float lo, float hi) { return f2bf(lo) | (f2bf(hi) << 16); }
; __device__ __forceinline__ void attn_unit(const Args& A, const Ctx& C0, int l, int u_qrow0, int u_nq, int u_krow0, int u_krow1, int u_krow2, int u_g, const float* u_ck, const float* u_cv, unsigned u_vmask) {
;     ...
;         for (int it = 0; it < 3; ++it) { const int idx = C.tid + 512 * it; const int j = idx >> 3, part = idx & 7;
;             kx[it] = (v4u){0u, 0u, 0u, 0u}; vx[it] = kx[it];
;             if ((u.vmask >> (j >> 5)) & 1u) {
;                 if (u.ck && j < 128) { const float* pk = u.ck + (size_t)j * 128 + part * 8; const float* pv = u.cv + (size_t)j * 128 + part * 8;
;                     const f32x4 a0 = *(const f32x4*)pk, a1 = *(const f32x4*)(pk + 4), b0 = *(const f32x4*)pv, b1 = *(const f32x4*)(pv + 4);
;                     kx[it] = (v4u){pk2(a0.x, a0.y), pk2(a0.z, a0.w), pk2(a1.x, a1.y), pk2(a1.z, a1.w)}; vx[it] = (v4u){pk2(b0.x, b0.y), pk2(b0.z, b0.w), pk2(b1.x, b1.y), pk2(b1.z, b1.w)}; }
;                 else { const int ch = j >> 6; const int kr = (ch == 0 ? u.krow0 : (ch == 1 ? u.krow1 : u.krow2)) + (j & 63);
;                     kx[it] = *(const v4u*)(U + (size_t)kr * DIN + C_K + u.g * 64 + part * 8); vx[it] = *(const v4u*)(U + (size_t)kr * DIN + C_V + u.g * 64 + part * 8); }
;             } }
.LBB0_729:
	s_andn2_saveexec_b64 s[36:37], s[2:3]
	s_cbranch_execz .LBB0_733
	s_andn2_b64 vcc, exec, s[64:65]
	s_cbranch_vccnz .LBB0_732
	v_lshlrev_b32_e32 v16, 9, v36
	v_ashrrev_i32_e32 v17, 31, v16
	s_waitcnt vmcnt(0) lgkmcnt(0)
	v_lshl_add_u64 v[20:21], v[16:17], 2, v[26:27]
	global_load_dwordx4 v[16:19], v[20:21], off
	s_nop 0
	global_load_dwordx4 v[20:23], v[20:21], off offset:16
	s_waitcnt vmcnt(1)
	s_nop 0
	s_nop 0
	s_nop 0
	s_nop 0
	s_waitcnt vmcnt(0)
	s_nop 0
	s_nop 0
	s_nop 0
	s_nop 0
	s_nop 0
	s_nop 0
	v_cvt_pk_bf16_f32 v241, v16, v17
	s_nop 0
	s_nop 0
	v_cvt_pk_bf16_f32 v242, v18, v19
	s_nop 0
	s_nop 0
	s_nop 0
	v_cvt_pk_bf16_f32 v20, v20, v21
	s_nop 0
	s_nop 0
	s_nop 0
	s_nop 0
	s_nop 0
	v_mov_b32_e32 v18, v241
	v_mov_b32_e32 v19, v242
	s_nop 0
	v_cvt_pk_bf16_f32 v21, v22, v23
	s_branch .LBB0_733

; __device__ __forceinline__ unsigned pk2(float lo, float hi) { return f2bf(lo) | (f2bf(hi) << 16); }
; __device__ __forceinline__ void attn_unit(const Args& A, const Ctx& C0, int l, int u_qrow0, int u_nq, int u_krow0, int u_krow1, int u_krow2, int u_g, const float* u_ck, const float* u_cv, unsigned u_vmask) {
;     ...
;         for (int it = 0; it < 3; ++it) { const int idx = C.tid + 512 * it; const int j = idx >> 3, part = idx & 7;
;             kx[it] = (v4u){0u, 0u, 0u, 0u}; vx[it] = kx[it];
;             if ((u.vmask >> (j >> 5)) & 1u) {
;                 if (u.ck && j < 128) { const float* pk = u.ck + (size_t)j * 128 + part * 8; const float* pv = u.cv + (size_t)j * 128 + part * 8;
;                     const f32x4 a0 = *(const f32x4*)pk, a1 = *(const f32x4*)(pk + 4), b0 = *(const f32x4*)pv, b1 = *(const f32x4*)(pv + 4);
;                     kx[it] = (v4u){pk2(a0.x, a0.y), pk2(a0.z, a0.w), pk2(a1.x, a1.y), pk2(a1.z, a1.w)}; vx[it] = (v4u){pk2(b0.x, b0.y), pk2(b0.z, b0.w), pk2(b1.x, b1.y), pk2(b1.z, b1.w)}; }
;                 else { const int ch = j >> 6; const int kr = (ch == 0 ? u.krow0 : (ch == 1 ? u.krow1 : u.krow2)) + (j & 63);
;                     kx[it] = *(const v4u*)(U + (size_t)kr * DIN + C_K + u.g * 64 + part * 8); vx[it] = *(const v4u*)(U + (size_t)kr * DIN + C_V + u.g * 64 + part * 8); }
;             } }
.LBB0_737:
	s_andn2_saveexec_b64 s[36:37], s[2:3]
	s_cbranch_execz .LBB0_741
	s_andn2_b64 vcc, exec, s[64:65]
	s_cbranch_vccnz .LBB0_740
	s_waitcnt vmcnt(0) lgkmcnt(0)
	v_lshlrev_b32_e32 v14, 9, v37
	v_ashrrev_i32_e32 v15, 31, v14
	v_lshl_add_u64 v[22:23], v[14:15], 2, v[26:27]
	global_load_dwordx4 v[14:17], v[22:23], off
	s_nop 0
	global_load_dwordx4 v[22:25], v[22:23], off offset:16
	s_waitcnt vmcnt(1)
	s_nop 0
	s_nop 0
	s_nop 0
	s_nop 0
	s_waitcnt vmcnt(0)
	s_nop 0
	s_nop 0
	s_nop 0
	s_nop 0
	s_nop 0
	s_nop 0
	v_cvt_pk_bf16_f32 v14, v14, v15
	s_nop 0
	s_nop 0
	v_cvt_pk_bf16_f32 v15, v16, v17
	s_nop 0
	s_nop 0
	v_cvt_pk_bf16_f32 v16, v22, v23
	s_nop 0
	s_nop 0
	s_nop 0
	s_nop 0
	s_nop 0
	s_nop 0
	s_nop 0
	s_nop 0
	s_nop 0
	v_cvt_pk_bf16_f32 v17, v24, v25
	s_branch .LBB0_741

; __device__ __forceinline__ unsigned pk2(float lo, float hi) { return f2bf(lo) | (f2bf(hi) << 16); }
; __device__ __forceinline__ void attn_unit(const Args& A, const Ctx& C0, int l, int u_qrow0, int u_nq, int u_krow0, int u_krow1, int u_krow2, int u_g, const float* u_ck, const float* u_cv, unsigned u_vmask) {
;     ...
;         for (int it = 0; it < 3; ++it) { const int idx = C.tid + 512 * it; const int j = idx >> 3, part = idx & 7;
;             kx[it] = (v4u){0u, 0u, 0u, 0u}; vx[it] = kx[it];
;             if ((u.vmask >> (j >> 5)) & 1u) {
;                 if (u.ck && j < 128) { const float* pk = u.ck + (size_t)j * 128 + part * 8; const float* pv = u.cv + (size_t)j * 128 + part * 8;
;                     const f32x4 a0 = *(const f32x4*)pk, a1 = *(const f32x4*)(pk + 4), b0 = *(const f32x4*)pv, b1 = *(const f32x4*)(pv + 4);
;                     kx[it] = (v4u){pk2(a0.x, a0.y), pk2(a0.z, a0.w), pk2(a1.x, a1.y), pk2(a1.z, a1.w)}; vx[it] = (v4u){pk2(b0.x, b0.y), pk2(b0.z, b0.w), pk2(b1.x, b1.y), pk2(b1.z, b1.w)}; }
;                 else { const int ch = j >> 6; const int kr = (ch == 0 ? u.krow0 : (ch == 1 ? u.krow1 : u.krow2)) + (j & 63);
;                     kx[it] = *(const v4u*)(U + (size_t)kr * DIN + C_K + u.g * 64 + part * 8); vx[it] = *(const v4u*)(U + (size_t)kr * DIN + C_V + u.g * 64 + part * 8); }
;             } }
.LBB0_783:
	s_andn2_saveexec_b64 s[66:67], s[2:3]
	s_cbranch_execz .LBB0_1157
	s_andn2_b64 vcc, exec, s[64:65]
	s_cbranch_vccnz .LBB0_1156
	s_waitcnt vmcnt(0) lgkmcnt(0)
	v_lshlrev_b32_e32 v22, 9, v38
	v_ashrrev_i32_e32 v23, 31, v22
	v_lshl_add_u64 v[22:23], v[22:23], 2, v[26:27]
	global_load_dwordx4 v[24:27], v[22:23], off offset:16
	global_load_dwordx4 v[40:43], v[22:23], off
	s_waitcnt vmcnt(0)
	s_nop 0
	s_nop 0
	s_nop 0
	s_nop 0
	s_nop 0
	v_cvt_pk_bf16_f32 v22, v40, v41
	s_nop 0
	s_nop 0
	s_nop 0
	s_nop 0
	s_nop 0
	v_cvt_pk_bf16_f32 v23, v42, v43
	s_nop 0
	s_nop 0
	s_nop 0
	s_nop 0
	s_nop 0
	v_cvt_pk_bf16_f32 v24, v24, v25
	s_nop 0
	s_nop 0
	s_nop 0
	s_nop 0
	s_nop 0
	v_cvt_pk_bf16_f32 v25, v26, v27
	s_branch .LBB0_1157

; __device__ __forceinline__ unsigned pk2(float lo, float hi) { return f2bf(lo) | (f2bf(hi) << 16); }
; __device__ __forceinline__ void attn_unit(const Args& A, const Ctx& C0, int l, int u_qrow0, int u_nq, int u_krow0, int u_krow1, int u_krow2, int u_g, const float* u_ck, const float* u_cv, unsigned u_vmask) {
;     ...
;         for (int it = 0; it < 3; ++it) { const int idx = C.tid + 512 * it; const int j = idx >> 3, part = idx & 7;
;             kx[it] = (v4u){0u, 0u, 0u, 0u}; vx[it] = kx[it];
;             if ((u.vmask >> (j >> 5)) & 1u) {
;                 if (u.ck && j < 128) { const float* pk = u.ck + (size_t)j * 128 + part * 8; const float* pv = u.cv + (size_t)j * 128 + part * 8;
;                     const f32x4 a0 = *(const f32x4*)pk, a1 = *(const f32x4*)(pk + 4), b0 = *(const f32x4*)pv, b1 = *(const f32x4*)(pv + 4);
;                     kx[it] = (v4u){pk2(a0.x, a0.y), pk2(a0.z, a0.w), pk2(a1.x, a1.y), pk2(a1.z, a1.w)}; vx[it] = (v4u){pk2(b0.x, b0.y), pk2(b0.z, b0.w), pk2(b1.x, b1.y), pk2(b1.z, b1.w)}; }
;                 else { const int ch = j >> 6; const int kr = (ch == 0 ? u.krow0 : (ch == 1 ? u.krow1 : u.krow2)) + (j & 63);
;                     kx[it] = *(const v4u*)(U + (size_t)kr * DIN + C_K + u.g * 64 + part * 8); vx[it] = *(const v4u*)(U + (size_t)kr * DIN + C_V + u.g * 64 + part * 8); }
;             } }
.LBB0_798:
	s_andn2_saveexec_b64 s[30:31], s[30:31]
	s_cbranch_execz .LBB0_800
	v_ashrrev_i32_e32 v37, 31, v36
	v_lshlrev_b64 v[8:9], 9, v[36:37]
	s_waitcnt vmcnt(0) lgkmcnt(0)
	v_lshl_add_u64 v[22:23], v[34:35], 0, v[8:9]
	v_lshl_add_u64 v[8:9], v[32:33], 0, v[8:9]
	global_load_dwordx4 v[14:17], v[22:23], off
	s_nop 0
	global_load_dwordx4 v[22:25], v[22:23], off offset:16
	s_nop 0
	global_load_dwordx4 v[26:29], v[8:9], off
	global_load_dwordx4 v[42:45], v[8:9], off offset:16
	s_waitcnt vmcnt(3)
	s_nop 0
	s_nop 0
	s_nop 0
	s_nop 0
	s_waitcnt vmcnt(2)
	s_nop 0
	s_nop 0
	s_nop 0
	s_waitcnt vmcnt(1)
	s_nop 0
	s_nop 0
	s_waitcnt vmcnt(0)
	s_nop 0
	s_nop 0
	s_nop 0
	s_nop 0
	s_nop 0
	s_nop 0
	s_nop 0
	s_nop 0
	s_nop 0
	v_cvt_pk_bf16_f32 v241, v14, v15
	s_nop 0
	s_nop 0
	v_cvt_pk_bf16_f32 v242, v16, v17
	s_nop 0
	s_nop 0
	v_cvt_pk_bf16_f32 v243, v22, v23
	s_nop 0
	s_nop 0
	v_cvt_pk_bf16_f32 v25, v24, v25
	s_nop 0
	v_cvt_pk_bf16_f32 v15, v28, v29
	s_nop 0
	s_nop 0
	s_nop 0
	s_nop 0
	v_cvt_pk_bf16_f32 v14, v26, v27
	s_nop 0
	s_nop 0
	s_nop 0
	s_nop 0
	s_nop 0
	s_nop 0
	s_nop 0
	s_nop 0
	s_nop 0
	s_nop 0
	s_nop 0
	v_mov_b32_e32 v22, v241
	v_mov_b32_e32 v23, v242
	v_mov_b32_e32 v24, v243
	s_nop 0
	s_nop 0
	s_nop 0
	v_cvt_pk_bf16_f32 v16, v42, v43
	v_cvt_pk_bf16_f32 v17, v44, v45

; __device__ __forceinline__ unsigned pk2(float lo, float hi) { return f2bf(lo) | (f2bf(hi) << 16); }
; __device__ __forceinline__ void attn_unit(const Args& A, const Ctx& C0, int l, int u_qrow0, int u_nq, int u_krow0, int u_krow1, int u_krow2, int u_g, const float* u_ck, const float* u_cv, unsigned u_vmask) {
;     ...
;         for (int it = 0; it < 3; ++it) { const int idx = C.tid + 512 * it; const int j = idx >> 3, part = idx & 7;
;             kx[it] = (v4u){0u, 0u, 0u, 0u}; vx[it] = kx[it];
;             if ((u.vmask >> (j >> 5)) & 1u) {
;                 if (u.ck && j < 128) { const float* pk = u.ck + (size_t)j * 128 + part * 8; const float* pv = u.cv + (size_t)j * 128 + part * 8;
;                     const f32x4 a0 = *(const f32x4*)pk, a1 = *(const f32x4*)(pk + 4), b0 = *(const f32x4*)pv, b1 = *(const f32x4*)(pv + 4);
;                     kx[it] = (v4u){pk2(a0.x, a0.y), pk2(a0.z, a0.w), pk2(a1.x, a1.y), pk2(a1.z, a1.w)}; vx[it] = (v4u){pk2(b0.x, b0.y), pk2(b0.z, b0.w), pk2(b1.x, b1.y), pk2(b1.z, b1.w)}; }
;                 else { const int ch = j >> 6; const int kr = (ch == 0 ? u.krow0 : (ch == 1 ? u.krow1 : u.krow2)) + (j & 63);
;                     kx[it] = *(const v4u*)(U + (size_t)kr * DIN + C_K + u.g * 64 + part * 8); vx[it] = *(const v4u*)(U + (size_t)kr * DIN + C_V + u.g * 64 + part * 8); }
;             } }
.LBB0_804:
	s_andn2_saveexec_b64 s[24:25], s[30:31]
	s_cbranch_execz .LBB0_806
	v_ashrrev_i32_e32 v39, 31, v38
	v_lshlrev_b64 v[42:43], 9, v[38:39]
	s_waitcnt vmcnt(0) lgkmcnt(0)
	v_lshl_add_u64 v[26:27], v[34:35], 0, v[42:43]
	v_lshl_add_u64 v[42:43], v[32:33], 0, v[42:43]
	global_load_dwordx4 v[6:9], v[26:27], off
	s_nop 0
	global_load_dwordx4 v[26:29], v[26:27], off offset:16
	s_nop 0
	global_load_dwordx4 v[32:35], v[42:43], off
	s_nop 0
	global_load_dwordx4 v[42:45], v[42:43], off offset:16
	s_waitcnt vmcnt(3)
	s_nop 0
	s_nop 0
	s_waitcnt vmcnt(2)
	s_nop 0
	s_nop 0
	s_waitcnt vmcnt(1)
	s_nop 0
	s_nop 0
	s_nop 0
	s_nop 0
	s_waitcnt vmcnt(0)
	s_nop 0
	s_nop 0
	s_nop 0
	s_nop 0
	s_nop 0
	s_nop 0
	s_nop 0
	s_nop 0
	s_nop 0
	s_nop 0
	s_nop 0
	s_nop 0
	s_nop 0
	s_nop 0
	v_cvt_pk_bf16_f32 v241, v32, v33
	s_nop 0
	s_nop 0
	v_cvt_pk_bf16_f32 v242, v34, v35
	s_nop 0
	s_nop 0
	s_nop 0
	s_nop 0
	s_nop 0
	s_nop 0
	s_nop 0
	s_nop 0
	s_nop 0
	s_nop 0
	s_nop 0
	s_nop 0
	s_nop 0
	s_nop 0
	s_nop 0
	s_nop 0
	v_cvt_pk_bf16_f32 v6, v6, v7
	v_cvt_pk_bf16_f32 v7, v8, v9
	v_cvt_pk_bf16_f32 v8, v26, v27
	v_cvt_pk_bf16_f32 v9, v28, v29
	v_mov_b32_e32 v26, v241
	v_mov_b32_e32 v27, v242
	v_cvt_pk_bf16_f32 v28, v42, v43
	v_cvt_pk_bf16_f32 v29, v44, v45

; #define LAS __attribute__((address_space(3)))
; __device__ __forceinline__ unsigned pk2(float lo, float hi) { return f2bf(lo) | (f2bf(hi) << 16); }
; __device__ __forceinline__ void attn_unit(const Args& A, const Ctx& C0, int l, int u_qrow0, int u_nq, int u_krow0, int u_krow1, int u_krow2, int u_g, const float* u_ck, const float* u_cv, unsigned u_vmask) {
;     ...
;         for (int kt = 0; kt < 6; ++kt) {
;             if ((u.vmask >> kt) & 1u) {
; #pragma unroll
;                 for (int s = 0; s < 2; ++s) {
;                     union { bf16x8 v; unsigned w[4]; } pf;
; #pragma unroll
;                     for (int e = 0; e < 4; ++e) pf.w[e] = pk2(sacc[kt][8 * s + 2 * e] * inv, sacc[kt][8 * s + 2 * e + 1] * inv);
; #pragma unroll
;                     for (int dt = 0; dt < 2; ++dt) { const LAS bf16* vp = Vt + (dt * 32 + li) * VP + kt * 32 + 16 * s + 4 * h;
;                         union { bf16x8 v; v2u w[2]; } vf; vf.w[0] = *(const LAS v2u*)vp; vf.w[1] = *(const LAS v2u*)(vp + 8);
;                         oacc[dt] = __builtin_amdgcn_mfma_f32_32x32x16_bf16(vf.v, pf.v, oacc[dt], 0, 0, 0); }
.LBB0_970:
	s_and_b64 vcc, exec, s[40:41]
	s_cbranch_vccnz .LBB0_972
	v_pk_mul_f32 v[4:5], v[178:179], v[82:83] op_sel_hi:[1,0]
	v_pk_mul_f32 v[8:9], v[182:183], v[82:83] op_sel_hi:[1,0]
	v_pk_mul_f32 v[2:3], v[176:177], v[82:83] op_sel_hi:[1,0]
	v_pk_mul_f32 v[6:7], v[180:181], v[82:83] op_sel_hi:[1,0]
	s_nop 0
	s_nop 0
	s_nop 0
	s_nop 0
	s_nop 0
	s_nop 0
	s_nop 0
	s_nop 0
	s_nop 0
	s_nop 0
	s_nop 0
	s_nop 0
	s_nop 0
	s_nop 0
	v_cvt_pk_bf16_f32 v241, v7, v9
	s_nop 0
	s_nop 0
	v_cvt_pk_bf16_f32 v7, v3, v5
	v_cvt_pk_bf16_f32 v242, v2, v4
	ds_read2_b64 v[2:5], v83 offset0:136 offset1:138
	s_nop 0
	s_nop 0
	s_nop 0
	s_nop 0
	v_mov_b32_e32 v9, v241
	v_cvt_pk_bf16_f32 v8, v6, v8
	s_nop 0
	v_mov_b32_e32 v6, v242
	s_waitcnt lgkmcnt(0)
	s_nop 0
	v_mfma_f32_32x32x16_bf16 v[34:49], v[2:5], v[6:9], v[34:49]
	ds_read2_b64 v[2:5], v193 offset0:168 offset1:170
	ds_read2_b64 v[10:13], v83 offset0:140 offset1:142
	s_waitcnt lgkmcnt(1)
	v_mfma_f32_32x32x16_bf16 v[50:65], v[2:5], v[6:9], v[50:65]
	v_mul_f32_e64 v8, v174, v82
	v_mul_f32_e64 v9, v175, v82
	v_mul_f32_e64 v4, v170, v82
	v_mul_f32_e64 v5, v171, v82
	v_mul_f32_e64 v6, v172, v82
	v_mul_f32_e64 v7, v173, v82
	s_nop 0
	v_pk_mul_f32 v[2:3], v[168:169], v[82:83] op_sel_hi:[1,0]
	s_nop 0
	s_nop 0
	s_nop 0
	s_nop 0
	s_nop 0
	s_nop 0
	s_nop 0
	s_nop 0
	s_nop 0
	s_nop 0
	s_nop 0
	v_cvt_pk_bf16_f32 v2, v2, v4
	v_cvt_pk_bf16_f32 v4, v6, v8
	s_nop 0
	s_nop 0
	s_nop 0
	s_nop 0
	s_nop 0
	s_nop 0
	s_nop 0
	v_cvt_pk_bf16_f32 v3, v3, v5
	v_cvt_pk_bf16_f32 v5, v7, v9
	ds_read2_b64 v[6:9], v193 offset0:172 offset1:174
	s_nop 0
	s_nop 0
	s_nop 0
	s_nop 0
	s_nop 0
	s_waitcnt lgkmcnt(1)
	s_nop 0
	v_mfma_f32_32x32x16_bf16 v[34:49], v[10:13], v[2:5], v[34:49]
	s_waitcnt lgkmcnt(0)
	v_mfma_f32_32x32x16_bf16 v[50:65], v[6:9], v[2:5], v[50:65]
.LBB0_972:
	s_and_b64 vcc, exec, s[44:45]
	s_cbranch_vccnz .LBB0_974
	v_pk_mul_f32 v[4:5], v[128:129], v[82:83] op_sel_hi:[1,0]
	v_pk_mul_f32 v[8:9], v[166:167], v[82:83] op_sel_hi:[1,0]
	v_pk_mul_f32 v[2:3], v[32:33], v[82:83] op_sel_hi:[1,0]
	v_pk_mul_f32 v[6:7], v[164:165], v[82:83] op_sel_hi:[1,0]
	s_nop 0
	s_nop 0
	s_nop 0
	s_nop 0
	s_nop 0
	s_nop 0
	s_nop 0
	s_nop 0
	s_nop 0
	s_nop 0
	s_nop 0
	s_nop 0
	s_nop 0
	s_nop 0
	v_cvt_pk_bf16_f32 v241, v7, v9
	s_nop 0
	s_nop 0
	v_cvt_pk_bf16_f32 v7, v3, v5
	v_cvt_pk_bf16_f32 v242, v2, v4
	ds_read2_b64 v[2:5], v83 offset0:144 offset1:146
	s_nop 0
	s_nop 0
	s_nop 0
	s_nop 0
	v_mov_b32_e32 v9, v241
	v_cvt_pk_bf16_f32 v8, v6, v8
	s_nop 0
	v_mov_b32_e32 v6, v242
	s_waitcnt lgkmcnt(0)
	s_nop 0
	v_mfma_f32_32x32x16_bf16 v[34:49], v[2:5], v[6:9], v[34:49]
	ds_read2_b64 v[2:5], v193 offset0:176 offset1:178
	ds_read2_b64 v[10:13], v83 offset0:148 offset1:150
	s_waitcnt lgkmcnt(1)
	v_mfma_f32_32x32x16_bf16 v[50:65], v[2:5], v[6:9], v[50:65]
	v_mul_f32_e64 v8, v30, v82
	v_mul_f32_e64 v9, v31, v82
	v_mul_f32_e64 v4, v26, v82
	v_mul_f32_e64 v5, v27, v82
	v_mul_f32_e64 v6, v28, v82
	v_mul_f32_e64 v7, v29, v82
	s_nop 0
	v_pk_mul_f32 v[2:3], v[24:25], v[82:83] op_sel_hi:[1,0]
	s_nop 0
	s_nop 0
	s_nop 0
	s_nop 0
	s_nop 0
	s_nop 0
	s_nop 0
	s_nop 0
	s_nop 0
	s_nop 0
	s_nop 0
	v_cvt_pk_bf16_f32 v2, v2, v4
	v_cvt_pk_bf16_f32 v4, v6, v8
	s_nop 0
	s_nop 0
	s_nop 0
	s_nop 0
	s_nop 0
	s_nop 0
	s_nop 0
	v_cvt_pk_bf16_f32 v3, v3, v5
	v_cvt_pk_bf16_f32 v5, v7, v9
	ds_read2_b64 v[6:9], v193 offset0:180 offset1:182
	s_nop 0
	s_nop 0
	s_nop 0
	s_nop 0
	s_nop 0
	s_waitcnt lgkmcnt(1)
	s_nop 0
	v_mfma_f32_32x32x16_bf16 v[34:49], v[10:13], v[2:5], v[34:49]
	s_waitcnt lgkmcnt(0)
	v_mfma_f32_32x32x16_bf16 v[50:65], v[6:9], v[2:5], v[50:65]
.LBB0_974:
	v_mov_b32_e32 v14, 0x3100
	s_and_b64 vcc, exec, s[62:63]
	v_mul_u32_u24_e32 v0, 0x188, v187
	v_mad_u32_u24 v128, v187, s2, v14
	s_cbranch_vccz .LBB0_976
	v_pk_mul_f32 v[4:5], v[18:19], v[82:83] op_sel_hi:[1,0]
	v_pk_mul_f32 v[8:9], v[22:23], v[82:83] op_sel_hi:[1,0]
	v_pk_mul_f32 v[2:3], v[16:17], v[82:83] op_sel_hi:[1,0]
	v_pk_mul_f32 v[6:7], v[20:21], v[82:83] op_sel_hi:[1,0]
	s_nop 0
	s_nop 0
	s_nop 0
	s_nop 0
	s_nop 0
	s_nop 0
	s_nop 0
	s_nop 0
	s_nop 0
	s_nop 0
	s_nop 0
	s_nop 0
	s_nop 0
	s_nop 0
	s_nop 0
	s_nop 0
	v_cvt_pk_bf16_f32 v167, v3, v5
	v_cvt_pk_bf16_f32 v166, v2, v4
	ds_read2_b64 v[2:5], v83 offset0:152 offset1:154
	s_nop 0
	s_nop 0
	s_nop 0
	s_nop 0
	v_cvt_pk_bf16_f32 v169, v7, v9
	v_cvt_pk_bf16_f32 v168, v6, v8
	s_nop 0
	s_nop 0
	v_mad_u32_u24 v164, v187, s2, v14
	v_pk_mul_f32 v[122:123], v[122:123], v[82:83] op_sel_hi:[1,0]
	s_waitcnt lgkmcnt(0)
	v_mfma_f32_32x32x16_bf16 v[18:33], v[2:5], v[166:169], v[34:49]
	v_add_u32_e32 v2, v192, v164
	v_add_u32_e32 v129, 0x6800, v2
	ds_read2_b64 v[170:173], v129 offset0:152 offset1:154
	ds_read2_b64 v[174:177], v83 offset0:156 offset1:158
	v_mul_f32_e64 v124, v124, v82
	v_mul_f32_e64 v125, v125, v82
	v_pk_mul_f32 v[126:127], v[126:127], v[82:83] op_sel_hi:[1,0]
	v_pk_mul_f32 v[120:121], v[120:121], v[82:83] op_sel_hi:[1,0]
	s_nop 0
	s_waitcnt lgkmcnt(1)
	v_mfma_f32_32x32x16_bf16 v[2:17], v[170:173], v[166:169], v[50:65]
	s_nop 0
	s_nop 0
	s_nop 0
	s_nop 0
	s_nop 0
	s_nop 0
	s_nop 0
	s_nop 0
	ds_read2_b64 v[166:169], v129 offset0:156 offset1:158
	s_nop 0
	s_nop 0
	s_nop 0
	v_cvt_pk_bf16_f32 v125, v125, v127
	s_nop 0
	s_nop 0
	s_nop 0
	s_nop 0
	s_nop 0
	s_nop 0
	s_nop 0
	s_nop 0
	s_nop 0
	v_cvt_pk_bf16_f32 v124, v124, v126
	v_cvt_pk_bf16_f32 v123, v121, v123
	v_cvt_pk_bf16_f32 v122, v120, v122
	v_mul_u32_u24_e32 v120, 0x188, v187
	s_waitcnt lgkmcnt(1)
	v_mfma_f32_32x32x16_bf16 v[18:33], v[174:177], v[122:125], v[18:33]
	s_waitcnt lgkmcnt(0)
	v_mfma_f32_32x32x16_bf16 v[2:17], v[166:169], v[122:125], v[2:17]
	s_cbranch_execz .LBB0_977
	s_branch .LBB0_978

; #define LAS __attribute__((address_space(3)))
; __device__ __forceinline__ unsigned pk2(float lo, float hi) { return f2bf(lo) | (f2bf(hi) << 16); }
; __device__ __forceinline__ void attn_unit(const Args& A, const Ctx& C0, int l, int u_qrow0, int u_nq, int u_krow0, int u_krow1, int u_krow2, int u_g, const float* u_ck, const float* u_cv, unsigned u_vmask) {
;     ...
;         for (int kt = 0; kt < 6; ++kt) {
;             if ((u.vmask >> kt) & 1u) {
; #pragma unroll
;                 for (int s = 0; s < 2; ++s) {
;                     union { bf16x8 v; unsigned w[4]; } pf;
; #pragma unroll
;                     for (int e = 0; e < 4; ++e) pf.w[e] = pk2(sacc[kt][8 * s + 2 * e] * inv, sacc[kt][8 * s + 2 * e + 1] * inv);
; #pragma unroll
;                     for (int dt = 0; dt < 2; ++dt) { const LAS bf16* vp = Vt + (dt * 32 + li) * VP + kt * 32 + 16 * s + 4 * h;
;                         union { bf16x8 v; v2u w[2]; } vf; vf.w[0] = *(const LAS v2u*)vp; vf.w[1] = *(const LAS v2u*)(vp + 8);
;                         oacc[dt] = __builtin_amdgcn_mfma_f32_32x32x16_bf16(vf.v, pf.v, oacc[dt], 0, 0, 0); }
.LBB0_978:
	v_mov_b32_e32 v83, v82
	v_pk_mul_f32 v[36:37], v[94:95], v[82:83]
	v_pk_mul_f32 v[40:41], v[118:119], v[82:83]
	v_pk_mul_f32 v[34:35], v[92:93], v[82:83]
	v_pk_mul_f32 v[38:39], v[96:97], v[82:83]
	s_nop 0
	s_nop 0
	s_nop 0
	s_nop 0
	s_nop 0
	s_nop 0
	s_nop 0
	s_nop 0
	s_nop 0
	s_nop 0
	v_cvt_pk_bf16_f32 v242, v34, v36
	v_add_u32_e32 v34, v192, v120
	s_nop 0
	s_nop 0
	s_nop 0
	v_cvt_pk_bf16_f32 v241, v39, v41
	s_nop 0
	v_add_u32_e32 v129, 0x6800, v34
	s_nop 0
	s_nop 0
	v_cvt_pk_bf16_f32 v39, v35, v37
	ds_read2_b64 v[34:37], v129 offset0:160 offset1:162
	s_nop 0
	s_nop 0
	s_nop 0
	s_nop 0
	v_mov_b32_e32 v41, v241
	v_add_u32_e32 v0, v192, v164
	v_cvt_pk_bf16_f32 v40, v38, v40
	s_nop 0
	v_mov_b32_e32 v38, v242
	v_add_u32_e32 v128, 0x6800, v0
	s_and_b64 vcc, exec, s[42:43]
	s_waitcnt lgkmcnt(0)
	v_mfma_f32_32x32x16_bf16 v[18:33], v[34:37], v[38:41], v[18:33]
	ds_read2_b64 v[34:37], v128 offset0:160 offset1:162
	ds_read2_b64 v[42:45], v129 offset0:164 offset1:166
	s_waitcnt lgkmcnt(1)
	v_mfma_f32_32x32x16_bf16 v[2:17], v[34:37], v[38:41], v[2:17]
	v_mul_f32_e64 v40, v90, v82
	v_mul_f32_e64 v41, v91, v83
	v_mul_f32_e64 v36, v86, v82
	v_mul_f32_e64 v37, v87, v83
	v_mul_f32_e64 v38, v88, v82
	v_mul_f32_e64 v39, v89, v83
	s_nop 0
	s_nop 0
	s_nop 0
	s_nop 0
	s_nop 0
	v_pk_mul_f32 v[34:35], v[84:85], v[82:83]
	s_nop 0
	s_nop 0
	s_nop 0
	s_nop 0
	s_nop 0
	s_nop 0
	s_nop 0
	v_cvt_pk_bf16_f32 v34, v34, v36
	v_cvt_pk_bf16_f32 v36, v38, v40
	s_nop 0
	s_nop 0
	s_nop 0
	s_nop 0
	s_nop 0
	s_nop 0
	s_nop 0
	v_cvt_pk_bf16_f32 v35, v35, v37
	v_cvt_pk_bf16_f32 v37, v39, v41
	ds_read2_b64 v[38:41], v128 offset0:164 offset1:166
	s_nop 0
	s_nop 0
	s_nop 0
	s_nop 0
	s_nop 0
	s_waitcnt lgkmcnt(1)
	s_nop 0
	v_mfma_f32_32x32x16_bf16 v[18:33], v[42:45], v[34:37], v[18:33]
	s_waitcnt lgkmcnt(0)
	v_mfma_f32_32x32x16_bf16 v[2:17], v[38:41], v[34:37], v[2:17]
	s_cbranch_vccnz .LBB0_980
	v_pk_mul_f32 v[36:37], v[76:77], v[82:83]
	v_pk_mul_f32 v[40:41], v[80:81], v[82:83]
	v_pk_mul_f32 v[34:35], v[74:75], v[82:83]
	v_pk_mul_f32 v[38:39], v[78:79], v[82:83]
	s_nop 0
	s_nop 0
	s_nop 0
	s_nop 0
	s_nop 0
	s_nop 0
	s_nop 0
	s_nop 0
	s_nop 0
	s_nop 0
	s_nop 0
	s_nop 0
	s_nop 0
	s_nop 0
	v_cvt_pk_bf16_f32 v241, v39, v41
	s_nop 0
	s_nop 0
	v_cvt_pk_bf16_f32 v39, v35, v37
	v_cvt_pk_bf16_f32 v242, v34, v36
	ds_read2_b64 v[34:37], v129 offset0:168 offset1:170
	s_nop 0
	s_nop 0
	s_nop 0
	s_nop 0
	v_mov_b32_e32 v41, v241
	v_cvt_pk_bf16_f32 v40, v38, v40
	s_nop 0
	v_mov_b32_e32 v38, v242
	s_waitcnt lgkmcnt(0)
	s_nop 0
	v_mfma_f32_32x32x16_bf16 v[18:33], v[34:37], v[38:41], v[18:33]
	ds_read2_b64 v[34:37], v128 offset0:168 offset1:170
	ds_read2_b64 v[42:45], v129 offset0:172 offset1:174
	s_waitcnt lgkmcnt(1)
	v_mfma_f32_32x32x16_bf16 v[2:17], v[34:37], v[38:41], v[2:17]
	v_mul_f32_e64 v40, v72, v82
	v_mul_f32_e64 v41, v73, v83
	v_mul_f32_e64 v36, v68, v82
	v_mul_f32_e64 v37, v69, v83
	v_mul_f32_e64 v38, v70, v82
	v_mul_f32_e64 v39, v71, v83
	s_nop 0
	s_nop 0
	s_nop 0
	s_nop 0
	s_nop 0
	v_pk_mul_f32 v[34:35], v[66:67], v[82:83]
	s_nop 0
	s_nop 0
	s_nop 0
	s_nop 0
	s_nop 0
	s_nop 0
	s_nop 0
	v_cvt_pk_bf16_f32 v34, v34, v36
	v_cvt_pk_bf16_f32 v36, v38, v40
	s_nop 0
	s_nop 0
	s_nop 0
	s_nop 0
	s_nop 0
	s_nop 0
	s_nop 0
	v_cvt_pk_bf16_f32 v35, v35, v37
	v_cvt_pk_bf16_f32 v37, v39, v41
	ds_read2_b64 v[38:41], v128 offset0:172 offset1:174
	s_nop 0
	s_nop 0
	s_nop 0
	s_nop 0
	s_nop 0
	s_waitcnt lgkmcnt(1)
	s_nop 0
	v_mfma_f32_32x32x16_bf16 v[18:33], v[42:45], v[34:37], v[18:33]
	s_waitcnt lgkmcnt(0)
	v_mfma_f32_32x32x16_bf16 v[2:17], v[38:41], v[34:37], v[2:17]

; __device__ __forceinline__ float shflx(float v, int mask, int lane) { return __int_as_float(__builtin_amdgcn_ds_bpermute((lane ^ mask) << 2, __float_as_int(v))); }
; __device__ __forceinline__ void attn_unit(const Args& A, const Ctx& C0, int l, int u_qrow0, int u_nq, int u_krow0, int u_krow1, int u_krow2, int u_g, const float* u_ck, const float* u_cv, unsigned u_vmask) {
;     ...
;         float mx = sink;
; #pragma unroll
;         for (int kt = 0; kt < 6; ++kt) { const bool valid = (u.vmask >> kt) & 1u;
; #pragma unroll
;             for (int r = 0; r < 16; ++r) { const int j = kt * 32 + (r & 3) + 8 * (r >> 2) + 4 * h;
;                 const float lg = valid ? sacc[kt][r] * 0.125f + bL[j - qi + 63] : -1e30f; sacc[kt][r] = lg; mx = fmaxf(mx, lg); }
;             asm volatile("" ::: "memory"); }
;         mx = fmaxf(mx, shflx(mx, 32, C.lane));
;         float sum = 0.f;
; #pragma unroll
;         for (int kt = 0; kt < 6; ++kt)
; #pragma unroll
;             for (int r = 0; r < 16; ++r) { const float e = __expf(sacc[kt][r] - mx); sacc[kt][r] = e; sum += e; }
.LBB0_1066:
	v_max3_f32 v18, v186, v107, v106
	v_max3_f32 v18, v18, v83, v82
	v_max3_f32 v18, v18, v85, v84
	v_max3_f32 v18, v18, v87, v86
	v_max3_f32 v18, v18, v89, v88
	v_max3_f32 v18, v18, v91, v90
	v_max3_f32 v18, v18, v93, v92
	v_max3_f32 v18, v18, v95, v94
	v_max3_f32 v18, v18, v97, v96
	v_max3_f32 v18, v18, v67, v66
	v_max3_f32 v18, v18, v69, v68
	v_max3_f32 v18, v18, v71, v70
	v_max3_f32 v18, v18, v73, v72
	v_max3_f32 v18, v18, v75, v74
	v_max3_f32 v18, v18, v77, v76
	v_max3_f32 v18, v18, v79, v78
	v_max3_f32 v18, v18, v81, v80
	v_max3_f32 v18, v18, v103, v102
	v_max3_f32 v18, v18, v105, v104
	v_max3_f32 v18, v18, v109, v108
	v_max3_f32 v18, v18, v111, v110
	v_max3_f32 v18, v18, v59, v58
	v_max3_f32 v18, v18, v61, v60
	v_max3_f32 v18, v18, v63, v62
	v_max3_f32 v18, v18, v65, v64
	v_max3_f32 v18, v18, v149, v148
	v_max3_f32 v18, v18, v151, v150
	v_max3_f32 v18, v18, v153, v152
	v_max3_f32 v18, v18, v156, v154
	v_max3_f32 v18, v18, v160, v158
	v_max3_f32 v18, v18, v164, v162
	v_max3_f32 v18, v18, v168, v166
	s_waitcnt lgkmcnt(0)
	v_fmamk_f32 v48, v2, 0x3e000000, v48
	v_fmac_f32_e32 v49, 0x3e000000, v3
	v_max3_f32 v2, v18, v48, v49
	v_fmamk_f32 v46, v4, 0x3e000000, v46
	v_fmac_f32_e32 v47, 0x3e000000, v5
	v_max3_f32 v2, v2, v46, v47
	v_fmamk_f32 v44, v6, 0x3e000000, v44
	v_fmac_f32_e32 v45, 0x3e000000, v7
	v_max3_f32 v2, v2, v44, v45
	v_fmamk_f32 v42, v8, 0x3e000000, v42
	v_fmac_f32_e32 v43, 0x3e000000, v9
	v_max3_f32 v2, v2, v42, v43
	v_fmamk_f32 v40, v10, 0x3e000000, v40
	v_fmac_f32_e32 v41, 0x3e000000, v11
	v_max3_f32 v2, v2, v40, v41
	v_fmamk_f32 v38, v12, 0x3e000000, v38
	v_fmac_f32_e32 v39, 0x3e000000, v13
	v_max3_f32 v2, v2, v38, v39
	v_fmamk_f32 v36, v14, 0x3e000000, v36
	v_fmac_f32_e32 v37, 0x3e000000, v15
	v_max3_f32 v2, v2, v36, v37
	v_fmamk_f32 v34, v16, 0x3e000000, v34
	v_fmac_f32_e32 v35, 0x3e000000, v17
	v_max3_f32 v2, v2, v34, v35
	v_max3_f32 v2, v2, v157, v155
	v_max3_f32 v2, v2, v161, v159
	v_max3_f32 v2, v2, v165, v163
	v_max3_f32 v2, v2, v169, v167
	v_max3_f32 v2, v2, v171, v170
	v_max3_f32 v2, v2, v173, v172
	v_max3_f32 v2, v2, v175, v174
	v_max3_f32 v2, v2, v177, v176
	ds_bpermute_b32 v3, v189, v2
	s_waitcnt lgkmcnt(0)
	v_max_f32_e32 v3, v3, v3
	v_max_f32_e32 v178, v2, v3
	v_sub_f32_e32 v3, v85, v178
	v_mul_f32_e32 v3, 0x3fb8aa3b, v3
	v_exp_f32_e32 v54, v3
	v_sub_f32_e32 v3, v84, v178
	v_mul_f32_e32 v3, 0x3fb8aa3b, v3
	v_exp_f32_e32 v56, v3
	v_sub_f32_e32 v3, v87, v178
	v_mul_f32_e32 v3, 0x3fb8aa3b, v3
	v_exp_f32_e32 v55, v3
	v_sub_f32_e32 v3, v86, v178
	v_mul_f32_e32 v3, 0x3fb8aa3b, v3
	v_exp_f32_e32 v57, v3
	v_sub_f32_e32 v3, v89, v178
	v_mul_f32_e32 v3, 0x3fb8aa3b, v3
	v_exp_f32_e32 v120, v3
	v_sub_f32_e32 v3, v88, v178
	v_mul_f32_e32 v3, 0x3fb8aa3b, v3
	v_exp_f32_e32 v122, v3
	v_sub_f32_e32 v3, v91, v178
	v_mul_f32_e32 v3, 0x3fb8aa3b, v3
	v_exp_f32_e32 v121, v3
	v_sub_f32_e32 v3, v90, v178
	v_mul_f32_e32 v3, 0x3fb8aa3b, v3
	v_exp_f32_e32 v123, v3
	v_sub_f32_e32 v3, v93, v178
	v_mul_f32_e32 v3, 0x3fb8aa3b, v3
	v_exp_f32_e32 v124, v3
	v_sub_f32_e32 v3, v92, v178
	v_mul_f32_e32 v3, 0x3fb8aa3b, v3
	v_exp_f32_e32 v126, v3
	v_sub_f32_e32 v3, v95, v178
	v_mul_f32_e32 v3, 0x3fb8aa3b, v3
	v_exp_f32_e32 v125, v3
	v_sub_f32_e32 v3, v94, v178
	v_mul_f32_e32 v3, 0x3fb8aa3b, v3
	v_exp_f32_e32 v127, v3
	v_sub_f32_e32 v3, v97, v178
	v_mul_f32_e32 v3, 0x3fb8aa3b, v3
	v_exp_f32_e32 v112, v3
	v_sub_f32_e32 v3, v96, v178
	v_mul_f32_e32 v3, 0x3fb8aa3b, v3
	v_exp_f32_e32 v114, v3
	v_sub_f32_e32 v3, v67, v178
	v_mul_f32_e32 v3, 0x3fb8aa3b, v3
	v_exp_f32_e32 v113, v3
	v_sub_f32_e32 v3, v66, v178
	v_mul_f32_e32 v3, 0x3fb8aa3b, v3
	v_exp_f32_e32 v115, v3
	v_sub_f32_e32 v3, v69, v178
	v_mul_f32_e32 v3, 0x3fb8aa3b, v3
	v_exp_f32_e32 v116, v3
	v_sub_f32_e32 v3, v68, v178
	v_mul_f32_e32 v3, 0x3fb8aa3b, v3
	v_sub_f32_e32 v2, v107, v178
	v_exp_f32_e32 v118, v3
	v_sub_f32_e32 v3, v71, v178
	v_mul_f32_e32 v2, 0x3fb8aa3b, v2
	v_mul_f32_e32 v3, 0x3fb8aa3b, v3
	v_exp_f32_e32 v50, v2
	v_sub_f32_e32 v2, v106, v178
	v_exp_f32_e32 v117, v3
	v_sub_f32_e32 v3, v70, v178
	v_mul_f32_e32 v2, 0x3fb8aa3b, v2
	v_mul_f32_e32 v3, 0x3fb8aa3b, v3
	v_exp_f32_e32 v52, v2
	v_sub_f32_e32 v2, v83, v178
	v_exp_f32_e32 v119, v3
	v_sub_f32_e32 v3, v73, v178
	v_mul_f32_e32 v2, 0x3fb8aa3b, v2
	v_mul_f32_e32 v3, 0x3fb8aa3b, v3
	v_exp_f32_e32 v51, v2
	v_sub_f32_e32 v2, v82, v178
	v_exp_f32_e32 v26, v3
	v_sub_f32_e32 v3, v72, v178
	v_mul_f32_e32 v2, 0x3fb8aa3b, v2
	v_mul_f32_e32 v3, 0x3fb8aa3b, v3
	v_exp_f32_e32 v53, v2
	v_exp_f32_e32 v28, v3
	v_sub_f32_e32 v3, v75, v178
	v_add_f32_e32 v2, 0, v50
	v_mul_f32_e32 v3, 0x3fb8aa3b, v3
	v_add_f32_e32 v2, v52, v2
	v_exp_f32_e32 v27, v3
	v_sub_f32_e32 v3, v74, v178
	v_add_f32_e32 v2, v51, v2
	v_mul_f32_e32 v3, 0x3fb8aa3b, v3
	v_add_f32_e32 v2, v53, v2
	v_exp_f32_e32 v29, v3
	v_sub_f32_e32 v3, v77, v178
	v_add_f32_e32 v2, v54, v2
	v_mul_f32_e32 v3, 0x3fb8aa3b, v3
	v_add_f32_e32 v2, v56, v2
	v_exp_f32_e32 v30, v3
	v_sub_f32_e32 v3, v76, v178
	v_add_f32_e32 v2, v55, v2
	v_mul_f32_e32 v3, 0x3fb8aa3b, v3
	v_add_f32_e32 v2, v57, v2
	v_exp_f32_e32 v32, v3
	v_sub_f32_e32 v3, v79, v178
	v_add_f32_e32 v2, v120, v2
	v_mul_f32_e32 v3, 0x3fb8aa3b, v3
	v_add_f32_e32 v2, v122, v2
	v_exp_f32_e32 v31, v3
	v_sub_f32_e32 v3, v78, v178
	v_add_f32_e32 v2, v121, v2
	v_mul_f32_e32 v3, 0x3fb8aa3b, v3
	v_add_f32_e32 v2, v123, v2
	v_exp_f32_e32 v33, v3
	v_sub_f32_e32 v3, v81, v178
	v_add_f32_e32 v2, v124, v2
	v_mul_f32_e32 v3, 0x3fb8aa3b, v3
	v_add_f32_e32 v2, v126, v2
	v_exp_f32_e32 v18, v3
	v_sub_f32_e32 v3, v80, v178
	v_add_f32_e32 v2, v125, v2
	v_mul_f32_e32 v3, 0x3fb8aa3b, v3
	v_add_f32_e32 v2, v127, v2
	v_exp_f32_e32 v20, v3
	v_sub_f32_e32 v3, v103, v178
; __device__ __forceinline__ float shflx(float v, int mask, int lane) { return __int_as_float(__builtin_amdgcn_ds_bpermute((lane ^ mask) << 2, __float_as_int(v))); }
; __device__ __forceinline__ void attn_unit(const Args& A, const Ctx& C0, int l, int u_qrow0, int u_nq, int u_krow0, int u_krow1, int u_krow2, int u_g, const float* u_ck, const float* u_cv, unsigned u_vmask) {
;     ...
; #pragma unroll
;         for (int kt = 0; kt < 6; ++kt)
; #pragma unroll
;             for (int r = 0; r < 16; ++r) { const float e = __expf(sacc[kt][r] - mx); sacc[kt][r] = e; sum += e; }
;         sum += shflx(sum, 32, C.lane); sum += __expf(sink - mx);
	v_add_f32_e32 v2, v112, v2
	v_mul_f32_e32 v3, 0x3fb8aa3b, v3
	v_add_f32_e32 v2, v114, v2
	v_exp_f32_e32 v19, v3
	v_sub_f32_e32 v3, v102, v178
	v_add_f32_e32 v2, v113, v2
	v_mul_f32_e32 v3, 0x3fb8aa3b, v3
	v_add_f32_e32 v2, v115, v2
	v_exp_f32_e32 v21, v3
	v_sub_f32_e32 v3, v105, v178
	v_add_f32_e32 v2, v116, v2
	v_mul_f32_e32 v3, 0x3fb8aa3b, v3
	v_add_f32_e32 v2, v118, v2
	v_exp_f32_e32 v22, v3
	v_sub_f32_e32 v3, v104, v178
	v_add_f32_e32 v2, v117, v2
	v_mul_f32_e32 v3, 0x3fb8aa3b, v3
	v_add_f32_e32 v2, v119, v2
	v_exp_f32_e32 v24, v3
	v_sub_f32_e32 v3, v109, v178
	v_add_f32_e32 v2, v26, v2
	v_mul_f32_e32 v3, 0x3fb8aa3b, v3
	v_add_f32_e32 v2, v28, v2
	v_exp_f32_e32 v23, v3
	v_sub_f32_e32 v3, v108, v178
	v_add_f32_e32 v2, v27, v2
	v_mul_f32_e32 v3, 0x3fb8aa3b, v3
	v_add_f32_e32 v2, v29, v2
	v_exp_f32_e32 v25, v3
	v_sub_f32_e32 v3, v111, v178
	v_add_f32_e32 v2, v30, v2
	v_mul_f32_e32 v3, 0x3fb8aa3b, v3
	v_add_f32_e32 v2, v32, v2
	v_exp_f32_e32 v10, v3
	v_sub_f32_e32 v3, v110, v178
	v_add_f32_e32 v2, v31, v2
	v_mul_f32_e32 v3, 0x3fb8aa3b, v3
	v_add_f32_e32 v2, v33, v2
	v_exp_f32_e32 v12, v3
	v_sub_f32_e32 v3, v59, v178
	v_add_f32_e32 v2, v18, v2
	v_mul_f32_e32 v3, 0x3fb8aa3b, v3
	v_add_f32_e32 v2, v20, v2
	v_exp_f32_e32 v11, v3
	v_sub_f32_e32 v3, v58, v178
	v_add_f32_e32 v2, v19, v2
	v_mul_f32_e32 v3, 0x3fb8aa3b, v3
	v_add_f32_e32 v2, v21, v2
	v_exp_f32_e32 v13, v3
	v_sub_f32_e32 v3, v61, v178
	v_add_f32_e32 v2, v22, v2
	v_mul_f32_e32 v3, 0x3fb8aa3b, v3
	v_add_f32_e32 v2, v24, v2
	v_exp_f32_e32 v14, v3
	v_sub_f32_e32 v3, v60, v178
	v_add_f32_e32 v2, v23, v2
	v_mul_f32_e32 v3, 0x3fb8aa3b, v3
	v_add_f32_e32 v2, v25, v2
	v_exp_f32_e32 v16, v3
	v_sub_f32_e32 v3, v63, v178
	v_add_f32_e32 v2, v10, v2
	v_mul_f32_e32 v3, 0x3fb8aa3b, v3
	v_add_f32_e32 v2, v12, v2
	v_exp_f32_e32 v15, v3
	v_sub_f32_e32 v3, v62, v178
	v_add_f32_e32 v2, v11, v2
	v_mul_f32_e32 v3, 0x3fb8aa3b, v3
	v_add_f32_e32 v2, v13, v2
	v_exp_f32_e32 v17, v3
	v_add_f32_e32 v2, v14, v2
	v_add_f32_e32 v2, v16, v2
	v_add_f32_e32 v2, v15, v2
	v_add_f32_e32 v6, v17, v2
	v_sub_f32_e32 v2, v65, v178
	v_sub_f32_e32 v3, v64, v178
	v_mul_f32_e32 v2, 0x3fb8aa3b, v2
	v_mul_f32_e32 v3, 0x3fb8aa3b, v3
	v_exp_f32_e32 v2, v2
	v_exp_f32_e32 v4, v3
	v_sub_f32_e32 v3, v149, v178
	v_mul_f32_e32 v3, 0x3fb8aa3b, v3
	v_sub_f32_e32 v5, v148, v178
	v_exp_f32_e32 v3, v3
	v_mul_f32_e32 v5, 0x3fb8aa3b, v5
	v_exp_f32_e32 v5, v5
	v_add_f32_e32 v6, v2, v6
	v_sub_f32_e32 v59, v156, v178
	v_add_f32_e32 v6, v4, v6
	v_mul_f32_e32 v59, 0x3fb8aa3b, v59
	v_add_f32_e32 v6, v3, v6
	v_exp_f32_e32 v104, v59
	v_sub_f32_e32 v59, v154, v178
	v_add_f32_e32 v58, v5, v6
	v_sub_f32_e32 v6, v151, v178
	v_sub_f32_e32 v7, v150, v178
	v_mul_f32_e32 v59, 0x3fb8aa3b, v59
	v_mul_f32_e32 v6, 0x3fb8aa3b, v6
	v_mul_f32_e32 v7, 0x3fb8aa3b, v7
	v_exp_f32_e32 v106, v59
	v_sub_f32_e32 v59, v160, v178
	v_exp_f32_e32 v6, v6
	v_exp_f32_e32 v8, v7
	v_sub_f32_e32 v7, v153, v178
	v_mul_f32_e32 v59, 0x3fb8aa3b, v59
	v_mul_f32_e32 v7, 0x3fb8aa3b, v7
	v_sub_f32_e32 v9, v152, v178
	v_exp_f32_e32 v105, v59
	v_sub_f32_e32 v59, v158, v178
	v_exp_f32_e32 v7, v7
	v_mul_f32_e32 v9, 0x3fb8aa3b, v9
	v_mul_f32_e32 v59, 0x3fb8aa3b, v59
	v_exp_f32_e32 v9, v9
	v_exp_f32_e32 v107, v59
	v_sub_f32_e32 v59, v164, v178
	v_add_f32_e32 v58, v6, v58
	v_mul_f32_e32 v59, 0x3fb8aa3b, v59
	v_add_f32_e32 v58, v8, v58
	v_exp_f32_e32 v108, v59
	v_sub_f32_e32 v59, v162, v178
	v_add_f32_e32 v58, v7, v58
	v_mul_f32_e32 v59, 0x3fb8aa3b, v59
	v_add_f32_e32 v58, v9, v58
	v_exp_f32_e32 v110, v59
	v_sub_f32_e32 v59, v168, v178
	v_add_f32_e32 v58, v104, v58
	v_mul_f32_e32 v59, 0x3fb8aa3b, v59
	v_add_f32_e32 v58, v106, v58
	v_exp_f32_e32 v109, v59
	v_sub_f32_e32 v59, v166, v178
	v_sub_f32_e32 v48, v48, v178
	v_sub_f32_e32 v34, v34, v178
	v_add_f32_e32 v58, v105, v58
	v_mul_f32_e32 v59, 0x3fb8aa3b, v59
	v_mul_f32_e32 v48, 0x3fb8aa3b, v48
	v_mul_f32_e32 v34, 0x3fb8aa3b, v34
	v_add_f32_e32 v58, v107, v58
	v_exp_f32_e32 v111, v59
	v_exp_f32_e32 v92, v48
	v_sub_f32_e32 v48, v49, v178
	v_sub_f32_e32 v46, v46, v178
	v_exp_f32_e32 v89, v34
	v_sub_f32_e32 v34, v35, v178
	v_sub_f32_e32 v35, v157, v178
	v_add_f32_e32 v58, v108, v58
	v_mul_f32_e32 v48, 0x3fb8aa3b, v48
	v_mul_f32_e32 v46, 0x3fb8aa3b, v46
	v_mul_f32_e32 v35, 0x3fb8aa3b, v35
	v_add_f32_e32 v58, v110, v58
	v_exp_f32_e32 v94, v48
	v_exp_f32_e32 v93, v46
	v_sub_f32_e32 v46, v47, v178
	v_sub_f32_e32 v44, v44, v178
	v_exp_f32_e32 v74, v35
	v_sub_f32_e32 v35, v155, v178
	v_add_f32_e32 v58, v109, v58
	v_mul_f32_e32 v46, 0x3fb8aa3b, v46
	v_mul_f32_e32 v44, 0x3fb8aa3b, v44
	v_mul_f32_e32 v35, 0x3fb8aa3b, v35
	v_add_f32_e32 v58, v111, v58
	v_exp_f32_e32 v95, v46
	v_exp_f32_e32 v96, v44
	v_sub_f32_e32 v44, v45, v178
	v_sub_f32_e32 v42, v42, v178
	v_exp_f32_e32 v76, v35
	v_sub_f32_e32 v35, v161, v178
	v_add_f32_e32 v46, v92, v58
	v_mul_f32_e32 v44, 0x3fb8aa3b, v44
	v_mul_f32_e32 v42, 0x3fb8aa3b, v42
	v_mul_f32_e32 v35, 0x3fb8aa3b, v35
	v_add_f32_e32 v46, v94, v46
	v_exp_f32_e32 v102, v44
	v_exp_f32_e32 v97, v42
	v_sub_f32_e32 v42, v43, v178
	v_sub_f32_e32 v40, v40, v178
	v_exp_f32_e32 v75, v35
; #define LAS __attribute__((address_space(3)))
; __device__ __forceinline__ unsigned pk2(float lo, float hi) { return f2bf(lo) | (f2bf(hi) << 16); }
; __device__ __forceinline__ float shflx(float v, int mask, int lane) { return __int_as_float(__builtin_amdgcn_ds_bpermute((lane ^ mask) << 2, __float_as_int(v))); }
; __device__ __forceinline__ void attn_unit(const Args& A, const Ctx& C0, int l, int u_qrow0, int u_nq, int u_krow0, int u_krow1, int u_krow2, int u_g, const float* u_ck, const float* u_cv, unsigned u_vmask) {
;     ...
; #pragma unroll
;         for (int kt = 0; kt < 6; ++kt)
; #pragma unroll
;             for (int r = 0; r < 16; ++r) { const float e = __expf(sacc[kt][r] - mx); sacc[kt][r] = e; sum += e; }
;         sum += shflx(sum, 32, C.lane); sum += __expf(sink - mx);
;         const float inv = 1.f / sum;
;     ...
;         for (int kt = 0; kt < 6; ++kt) {
;             if ((u.vmask >> kt) & 1u) {
; #pragma unroll
;                 for (int s = 0; s < 2; ++s) {
;                     union { bf16x8 v; unsigned w[4]; } pf;
; #pragma unroll
;                     for (int e = 0; e < 4; ++e) pf.w[e] = pk2(sacc[kt][8 * s + 2 * e] * inv, sacc[kt][8 * s + 2 * e + 1] * inv);
; #pragma unroll
;                     for (int dt = 0; dt < 2; ++dt) { const LAS bf16* vp = Vt + (dt * 32 + li) * VP + kt * 32 + 16 * s + 4 * h;
;                         union { bf16x8 v; v2u w[2]; } vf; vf.w[0] = *(const LAS v2u*)vp; vf.w[1] = *(const LAS v2u*)(vp + 8);
;                         oacc[dt] = __builtin_amdgcn_mfma_f32_32x32x16_bf16(vf.v, pf.v, oacc[dt], 0, 0, 0); }
	v_sub_f32_e32 v35, v159, v178
	v_add_f32_e32 v46, v93, v46
	v_mul_f32_e32 v42, 0x3fb8aa3b, v42
	v_mul_f32_e32 v40, 0x3fb8aa3b, v40
	v_mul_f32_e32 v35, 0x3fb8aa3b, v35
	v_add_f32_e32 v46, v95, v46
	v_exp_f32_e32 v103, v42
	v_exp_f32_e32 v84, v40
	v_sub_f32_e32 v40, v41, v178
	v_sub_f32_e32 v38, v38, v178
	v_exp_f32_e32 v77, v35
	v_sub_f32_e32 v35, v165, v178
	v_add_f32_e32 v42, v96, v46
	v_mul_f32_e32 v40, 0x3fb8aa3b, v40
	v_mul_f32_e32 v38, 0x3fb8aa3b, v38
	v_mul_f32_e32 v35, 0x3fb8aa3b, v35
	v_add_f32_e32 v42, v102, v42
	v_exp_f32_e32 v86, v40
	v_exp_f32_e32 v85, v38
	v_sub_f32_e32 v38, v39, v178
	v_sub_f32_e32 v36, v36, v178
	v_exp_f32_e32 v78, v35
	v_sub_f32_e32 v35, v163, v178
	v_add_f32_e32 v42, v97, v42
	v_mul_f32_e32 v38, 0x3fb8aa3b, v38
	v_mul_f32_e32 v36, 0x3fb8aa3b, v36
	v_mul_f32_e32 v35, 0x3fb8aa3b, v35
	v_add_f32_e32 v42, v103, v42
	v_exp_f32_e32 v87, v38
	v_exp_f32_e32 v88, v36
	v_sub_f32_e32 v36, v37, v178
	v_exp_f32_e32 v80, v35
	v_sub_f32_e32 v35, v169, v178
	v_add_f32_e32 v38, v84, v42
	v_mul_f32_e32 v36, 0x3fb8aa3b, v36
	v_mul_f32_e32 v35, 0x3fb8aa3b, v35
	v_add_f32_e32 v38, v86, v38
	v_exp_f32_e32 v90, v36
	v_exp_f32_e32 v79, v35
	v_sub_f32_e32 v35, v167, v178
	v_add_f32_e32 v38, v85, v38
	v_mul_f32_e32 v34, 0x3fb8aa3b, v34
	v_mul_f32_e32 v35, 0x3fb8aa3b, v35
	v_add_f32_e32 v38, v87, v38
	v_exp_f32_e32 v91, v34
	v_exp_f32_e32 v81, v35
	v_sub_f32_e32 v35, v171, v178
	v_add_f32_e32 v34, v88, v38
	v_mul_f32_e32 v35, 0x3fb8aa3b, v35
	v_add_f32_e32 v34, v90, v34
	v_exp_f32_e32 v66, v35
	v_sub_f32_e32 v35, v170, v178
	v_add_f32_e32 v34, v89, v34
	v_mul_f32_e32 v35, 0x3fb8aa3b, v35
	v_add_f32_e32 v34, v91, v34
	v_exp_f32_e32 v68, v35
	v_sub_f32_e32 v35, v173, v178
	v_add_f32_e32 v34, v74, v34
	v_mul_f32_e32 v35, 0x3fb8aa3b, v35
	v_add_f32_e32 v34, v76, v34
	v_exp_f32_e32 v67, v35
	v_sub_f32_e32 v35, v172, v178
	v_add_f32_e32 v34, v75, v34
	v_mul_f32_e32 v35, 0x3fb8aa3b, v35
	v_add_f32_e32 v34, v77, v34
	v_exp_f32_e32 v69, v35
	v_sub_f32_e32 v35, v175, v178
	v_add_f32_e32 v34, v78, v34
	v_mul_f32_e32 v35, 0x3fb8aa3b, v35
	v_add_f32_e32 v34, v80, v34
	v_exp_f32_e32 v70, v35
	v_sub_f32_e32 v35, v174, v178
	v_add_f32_e32 v34, v79, v34
	v_mul_f32_e32 v35, 0x3fb8aa3b, v35
	v_add_f32_e32 v34, v81, v34
	v_exp_f32_e32 v72, v35
	v_sub_f32_e32 v35, v177, v178
	v_add_f32_e32 v34, v66, v34
	v_mul_f32_e32 v35, 0x3fb8aa3b, v35
	v_add_f32_e32 v34, v68, v34
	v_exp_f32_e32 v71, v35
	v_sub_f32_e32 v35, v176, v178
	v_add_f32_e32 v34, v67, v34
	v_mul_f32_e32 v35, 0x3fb8aa3b, v35
	v_add_f32_e32 v34, v69, v34
	v_exp_f32_e32 v73, v35
	v_add_f32_e32 v34, v70, v34
	v_add_f32_e32 v34, v72, v34
	v_add_f32_e32 v34, v71, v34
	v_add_f32_e32 v34, v73, v34
	ds_bpermute_b32 v35, v189, v34
	v_sub_f32_e32 v36, v186, v178
	v_mul_f32_e32 v36, 0x3fb8aa3b, v36
	v_exp_f32_e32 v36, v36
	s_waitcnt lgkmcnt(0)
	v_add_f32_e32 v34, v34, v35
	v_add_f32_e32 v34, v36, v34
	v_div_scale_f32 v35, s[2:3], v34, v34, 1.0
	v_rcp_f32_e32 v36, v35
	s_nop 0
	v_fma_f32 v37, -v35, v36, 1.0
	v_fmac_f32_e32 v36, v37, v36
	v_div_scale_f32 v37, vcc, 1.0, v34, 1.0
	v_mul_f32_e32 v38, v37, v36
	v_fma_f32 v39, -v35, v38, v37
	v_fmac_f32_e32 v38, v39, v36
	v_fma_f32 v35, -v35, v38, v37
	v_div_fmas_f32 v35, v35, v36, v38
	s_and_b64 vcc, exec, s[38:39]
	v_div_fixup_f32 v82, v35, v34, 1.0
	s_cbranch_vccnz .LBB0_1143
	v_pk_mul_f32 v[36:37], v[52:53], v[82:83] op_sel_hi:[1,0]
	v_pk_mul_f32 v[40:41], v[56:57], v[82:83] op_sel_hi:[1,0]
	v_pk_mul_f32 v[34:35], v[50:51], v[82:83] op_sel_hi:[1,0]
	v_pk_mul_f32 v[38:39], v[54:55], v[82:83] op_sel_hi:[1,0]
	s_nop 0
	s_nop 0
	s_nop 0
	s_nop 0
	s_nop 0
	s_nop 0
	s_nop 0
	s_nop 0
	s_nop 0
	s_nop 0
	s_nop 0
	s_nop 0
	s_nop 0
	s_nop 0
	s_nop 0
	s_nop 0
	v_cvt_pk_bf16_f32 v241, v35, v37
	v_cvt_pk_bf16_f32 v242, v34, v36
	ds_read2_b64 v[34:37], v129 offset0:128 offset1:130
	s_nop 0
	s_nop 0
	s_nop 0
	s_nop 0
	v_pk_mul_f32 v[126:127], v[126:127], v[82:83] op_sel_hi:[1,0]
	v_cvt_pk_bf16_f32 v41, v39, v41
	v_cvt_pk_bf16_f32 v40, v38, v40
	v_mov_b32_e32 v39, v241
	v_mov_b32_e32 v38, v242
	v_pk_mul_f32 v[120:121], v[120:121], v[82:83] op_sel_hi:[1,0]
	v_pk_mul_f32 v[122:123], v[122:123], v[82:83] op_sel_hi:[1,0]
	v_pk_mul_f32 v[124:125], v[124:125], v[82:83] op_sel_hi:[1,0]
	s_nop 0
	s_waitcnt lgkmcnt(0)
	v_mfma_f32_32x32x16_bf16 v[50:65], v[34:37], v[38:41], 0
	ds_read2_b64 v[34:37], v128 offset0:128 offset1:130
	ds_read2_b64 v[148:151], v129 offset0:132 offset1:134
	s_nop 0
	s_nop 0
	s_nop 0
	s_nop 0
	s_nop 0
	s_nop 0
	s_nop 0
	s_nop 0
	s_nop 0
	s_nop 0
	s_nop 0
	v_cvt_pk_bf16_f32 v120, v120, v122
	v_cvt_pk_bf16_f32 v122, v124, v126
	s_nop 0
	s_nop 0
	s_nop 0
	s_nop 0
	s_nop 0
	s_nop 0
	s_nop 0
	v_cvt_pk_bf16_f32 v121, v121, v123
	v_cvt_pk_bf16_f32 v123, v125, v127
	ds_read2_b64 v[124:127], v128 offset0:132 offset1:134
	s_waitcnt lgkmcnt(0)
	v_mfma_f32_32x32x16_bf16 v[34:49], v[34:37], v[38:41], 0
	s_nop 0
	s_nop 0
	s_nop 0
	s_nop 0
	s_nop 0
	s_nop 1
	v_mfma_f32_32x32x16_bf16 v[50:65], v[148:151], v[120:123], v[50:65]
	v_mfma_f32_32x32x16_bf16 v[34:49], v[124:127], v[120:123], v[34:49]
	s_branch .LBB0_1144

; #define LAS __attribute__((address_space(3)))
; __device__ __forceinline__ unsigned pk2(float lo, float hi) { return f2bf(lo) | (f2bf(hi) << 16); }
; __device__ __forceinline__ void attn_unit(const Args& A, const Ctx& C0, int l, int u_qrow0, int u_nq, int u_krow0, int u_krow1, int u_krow2, int u_g, const float* u_ck, const float* u_cv, unsigned u_vmask) {
;     ...
;         for (int kt = 0; kt < 6; ++kt) {
;             if ((u.vmask >> kt) & 1u) {
; #pragma unroll
;                 for (int s = 0; s < 2; ++s) {
;                     union { bf16x8 v; unsigned w[4]; } pf;
; #pragma unroll
;                     for (int e = 0; e < 4; ++e) pf.w[e] = pk2(sacc[kt][8 * s + 2 * e] * inv, sacc[kt][8 * s + 2 * e + 1] * inv);
; #pragma unroll
;                     for (int dt = 0; dt < 2; ++dt) { const LAS bf16* vp = Vt + (dt * 32 + li) * VP + kt * 32 + 16 * s + 4 * h;
;                         union { bf16x8 v; v2u w[2]; } vf; vf.w[0] = *(const LAS v2u*)vp; vf.w[1] = *(const LAS v2u*)(vp + 8);
;                         oacc[dt] = __builtin_amdgcn_mfma_f32_32x32x16_bf16(vf.v, pf.v, oacc[dt], 0, 0, 0); }
.LBB0_1144:
	s_and_b64 vcc, exec, s[40:41]
	s_cbranch_vccnz .LBB0_1146
	v_pk_mul_f32 v[114:115], v[114:115], v[82:83] op_sel_hi:[1,0]
	v_pk_mul_f32 v[118:119], v[118:119], v[82:83] op_sel_hi:[1,0]
	v_pk_mul_f32 v[112:113], v[112:113], v[82:83] op_sel_hi:[1,0]
	v_pk_mul_f32 v[116:117], v[116:117], v[82:83] op_sel_hi:[1,0]
	v_bfe_u32 v83, v119, 16, 1
	s_nop 0
	s_nop 0
	s_nop 0
	s_nop 0
	s_nop 0
	s_nop 0
	v_add3_u32 v83, v119, v83, s33
	s_nop 0
	s_nop 0
	s_nop 0
	v_bfe_u32 v120, v117, 16, 1
	v_add3_u32 v117, v117, v120, s33
	s_nop 0
	s_nop 0
	s_nop 0
	v_cvt_pk_bf16_f32 v241, v113, v115
	v_cvt_pk_bf16_f32 v242, v112, v114
	ds_read2_b64 v[112:115], v129 offset0:136 offset1:138
	s_nop 0
	s_nop 0
	s_nop 0
	v_lshrrev_b32_e32 v117, 16, v117
	v_and_or_b32 v119, v83, s96, v117
	v_cvt_pk_bf16_f32 v118, v116, v118
	v_mov_b32_e32 v117, v241
	v_mov_b32_e32 v116, v242
	v_pk_mul_f32 v[28:29], v[28:29], v[82:83] op_sel_hi:[1,0]
	v_pk_mul_f32 v[32:33], v[32:33], v[82:83] op_sel_hi:[1,0]
	s_waitcnt lgkmcnt(0)
	v_mfma_f32_32x32x16_bf16 v[50:65], v[112:115], v[116:119], v[50:65]
	ds_read2_b64 v[112:115], v128 offset0:136 offset1:138
	ds_read2_b64 v[120:123], v129 offset0:140 offset1:142
	v_mul_f32_e64 v26, v26, v82
	v_mul_f32_e64 v27, v27, v82
	v_mul_f32_e64 v30, v30, v82
	v_mul_f32_e64 v31, v31, v82
	s_nop 0
	s_waitcnt lgkmcnt(0)
	v_mfma_f32_32x32x16_bf16 v[34:49], v[112:115], v[116:119], v[34:49]
	s_nop 0
	v_bfe_u32 v113, v29, 16, 1
	v_bfe_u32 v114, v28, 16, 1
	v_add3_u32 v114, v28, v114, s33
	v_add3_u32 v113, v29, v113, s33
	s_nop 0
	s_nop 0
	s_nop 0
	s_nop 0
	s_nop 0
	s_nop 0
	v_cvt_pk_bf16_f32 v28, v30, v32
	v_bfe_u32 v32, v26, 16, 1
	v_cvt_pk_bf16_f32 v29, v31, v33
	v_bfe_u32 v33, v27, 16, 1
	s_nop 0
	s_nop 0
	v_add3_u32 v27, v27, v33, s33
	v_add3_u32 v26, v26, v32, s33
	s_nop 0
	s_nop 0
	ds_read2_b64 v[30:33], v128 offset0:140 offset1:142
	v_lshrrev_b32_e32 v26, 16, v26
	v_lshrrev_b32_e32 v27, 16, v27
	v_and_or_b32 v27, v113, s96, v27
	v_and_or_b32 v26, v114, s96, v26
	s_nop 1
	v_mfma_f32_32x32x16_bf16 v[50:65], v[120:123], v[26:29], v[50:65]
	s_waitcnt lgkmcnt(0)
	v_mfma_f32_32x32x16_bf16 v[34:49], v[30:33], v[26:29], v[34:49]
.LBB0_1146:
	s_and_b64 vcc, exec, s[44:45]
	s_cbranch_vccnz .LBB0_1148
	v_pk_mul_f32 v[20:21], v[20:21], v[82:83] op_sel_hi:[1,0]
	v_pk_mul_f32 v[24:25], v[24:25], v[82:83] op_sel_hi:[1,0]
	v_pk_mul_f32 v[18:19], v[18:19], v[82:83] op_sel_hi:[1,0]
	v_pk_mul_f32 v[22:23], v[22:23], v[82:83] op_sel_hi:[1,0]
	s_nop 0
	s_nop 0
	s_nop 0
	s_nop 0
	s_nop 0
	s_nop 0
	s_nop 0
	s_nop 0
	s_nop 0
	s_nop 0
	s_nop 0
	s_nop 0
	s_nop 0
	s_nop 0
	s_nop 0
	s_nop 0
	v_cvt_pk_bf16_f32 v241, v19, v21
	v_cvt_pk_bf16_f32 v242, v18, v20
	ds_read2_b64 v[18:21], v129 offset0:144 offset1:146
	s_nop 0
	s_nop 0
	s_nop 0
	s_nop 0
	v_cvt_pk_bf16_f32 v25, v23, v25
	v_cvt_pk_bf16_f32 v24, v22, v24
	v_mov_b32_e32 v23, v241
	v_mov_b32_e32 v22, v242
	v_pk_mul_f32 v[12:13], v[12:13], v[82:83] op_sel_hi:[1,0]
	v_pk_mul_f32 v[16:17], v[16:17], v[82:83] op_sel_hi:[1,0]
	s_waitcnt lgkmcnt(0)
	v_mfma_f32_32x32x16_bf16 v[50:65], v[18:21], v[22:25], v[50:65]
	ds_read2_b64 v[18:21], v128 offset0:144 offset1:146
	ds_read2_b64 v[26:29], v129 offset0:148 offset1:150
	v_mul_f32_e64 v14, v14, v82
	v_mul_f32_e64 v15, v15, v82
	v_mul_f32_e64 v10, v10, v82
	v_mul_f32_e64 v11, v11, v82
	s_waitcnt lgkmcnt(0)
	v_mfma_f32_32x32x16_bf16 v[34:49], v[18:21], v[22:25], v[34:49]
	s_nop 0
	s_nop 0
	v_bfe_u32 v20, v13, 16, 1
	v_bfe_u32 v21, v12, 16, 1
	v_add3_u32 v21, v12, v21, s33
	v_add3_u32 v20, v13, v20, s33
	s_nop 0
	s_nop 0
	s_nop 0
	s_nop 0
	s_nop 0
	s_nop 0
	v_cvt_pk_bf16_f32 v12, v14, v16
	v_bfe_u32 v16, v10, 16, 1
	v_cvt_pk_bf16_f32 v13, v15, v17
	v_bfe_u32 v17, v11, 16, 1
	s_nop 0
	s_nop 0
	v_add3_u32 v11, v11, v17, s33
	v_add3_u32 v10, v10, v16, s33
	s_nop 0
	s_nop 0
	ds_read2_b64 v[14:17], v128 offset0:148 offset1:150
	v_lshrrev_b32_e32 v10, 16, v10
	v_lshrrev_b32_e32 v11, 16, v11
	v_and_or_b32 v11, v20, s96, v11
	v_and_or_b32 v10, v21, s96, v10
	s_nop 1
	v_mfma_f32_32x32x16_bf16 v[50:65], v[26:29], v[10:13], v[50:65]
	s_waitcnt lgkmcnt(0)
	v_mfma_f32_32x32x16_bf16 v[34:49], v[14:17], v[10:13], v[34:49]
.LBB0_1148:
	s_and_b64 vcc, exec, s[62:63]
	s_cbranch_vccz .LBB0_1150
	v_pk_mul_f32 v[4:5], v[4:5], v[82:83] op_sel_hi:[1,0]
	v_pk_mul_f32 v[8:9], v[8:9], v[82:83] op_sel_hi:[1,0]
	v_pk_mul_f32 v[2:3], v[2:3], v[82:83] op_sel_hi:[1,0]
	v_pk_mul_f32 v[6:7], v[6:7], v[82:83] op_sel_hi:[1,0]
	s_nop 0
	s_nop 0
	s_nop 0
	s_nop 0
	s_nop 0
	s_nop 0
	s_nop 0
	s_nop 0
	s_nop 0
	s_nop 0
	s_nop 0
	s_nop 0
	s_nop 0
	s_nop 0
	s_nop 0
	s_nop 0
	v_cvt_pk_bf16_f32 v113, v3, v5
	v_cvt_pk_bf16_f32 v112, v2, v4
	ds_read2_b64 v[2:5], v129 offset0:152 offset1:154
	ds_read2_b64 v[116:119], v128 offset0:152 offset1:154
	ds_read2_b64 v[120:123], v129 offset0:156 offset1:158
	s_nop 0
	s_nop 0
	s_nop 0
	s_nop 0
	v_pk_mul_f32 v[110:111], v[110:111], v[82:83] op_sel_hi:[1,0]
	v_cvt_pk_bf16_f32 v115, v7, v9
	v_cvt_pk_bf16_f32 v114, v6, v8
	s_nop 0
	s_nop 0
	v_pk_mul_f32 v[104:105], v[104:105], v[82:83] op_sel_hi:[1,0]
	v_pk_mul_f32 v[106:107], v[106:107], v[82:83] op_sel_hi:[1,0]
	v_pk_mul_f32 v[108:109], v[108:109], v[82:83] op_sel_hi:[1,0]
	s_nop 0
	s_waitcnt lgkmcnt(0)
	v_mfma_f32_32x32x16_bf16 v[18:33], v[2:5], v[112:115], v[50:65]
	s_nop 0
	s_nop 0
	s_nop 0
	s_nop 0
	v_mfma_f32_32x32x16_bf16 v[2:17], v[116:119], v[112:115], v[34:49]
	s_nop 0
	s_nop 0
	s_nop 0
	s_nop 0
	s_nop 0
	s_nop 0
	s_nop 0
	s_nop 0
	v_cvt_pk_bf16_f32 v104, v104, v106
	v_cvt_pk_bf16_f32 v106, v108, v110
	s_nop 0
	s_nop 0
	s_nop 0
	s_nop 0
	s_nop 0
	s_nop 0
	v_cvt_pk_bf16_f32 v105, v105, v107
	v_cvt_pk_bf16_f32 v107, v109, v111
	ds_read2_b64 v[108:111], v128 offset0:156 offset1:158
	s_nop 0
	s_nop 0
	s_nop 0
	s_nop 0
	s_nop 0
	s_nop 1
	v_mfma_f32_32x32x16_bf16 v[18:33], v[120:123], v[104:107], v[18:33]
	s_waitcnt lgkmcnt(0)
	v_mfma_f32_32x32x16_bf16 v[2:17], v[108:111], v[104:107], v[2:17]
	s_cbranch_execz .LBB0_1151
	s_branch .LBB0_1152

; #define LAS __attribute__((address_space(3)))
; __device__ __forceinline__ unsigned pk2(float lo, float hi) { return f2bf(lo) | (f2bf(hi) << 16); }
; __device__ __forceinline__ void attn_unit(const Args& A, const Ctx& C0, int l, int u_qrow0, int u_nq, int u_krow0, int u_krow1, int u_krow2, int u_g, const float* u_ck, const float* u_cv, unsigned u_vmask) {
;     ...
;         for (int kt = 0; kt < 6; ++kt) {
;             if ((u.vmask >> kt) & 1u) {
; #pragma unroll
;                 for (int s = 0; s < 2; ++s) {
;                     union { bf16x8 v; unsigned w[4]; } pf;
; #pragma unroll
;                     for (int e = 0; e < 4; ++e) pf.w[e] = pk2(sacc[kt][8 * s + 2 * e] * inv, sacc[kt][8 * s + 2 * e + 1] * inv);
; #pragma unroll
;                     for (int dt = 0; dt < 2; ++dt) { const LAS bf16* vp = Vt + (dt * 32 + li) * VP + kt * 32 + 16 * s + 4 * h;
;                         union { bf16x8 v; v2u w[2]; } vf; vf.w[0] = *(const LAS v2u*)vp; vf.w[1] = *(const LAS v2u*)(vp + 8);
;                         oacc[dt] = __builtin_amdgcn_mfma_f32_32x32x16_bf16(vf.v, pf.v, oacc[dt], 0, 0, 0); }
.LBB0_1152:
	v_mov_b32_e32 v83, v82
	v_pk_mul_f32 v[36:37], v[94:95], v[82:83]
	v_pk_mul_f32 v[40:41], v[102:103], v[82:83]
	v_pk_mul_f32 v[34:35], v[92:93], v[82:83]
	v_pk_mul_f32 v[38:39], v[96:97], v[82:83]
	s_nop 0
	s_nop 0
	s_nop 0
	s_nop 0
	s_nop 0
	s_nop 0
	s_nop 0
	s_nop 0
	s_nop 0
	s_nop 0
	s_nop 0
	s_nop 0
	s_nop 0
	s_nop 0
	s_nop 0
	s_nop 0
	v_cvt_pk_bf16_f32 v241, v35, v37
	v_cvt_pk_bf16_f32 v242, v34, v36
	ds_read2_b64 v[34:37], v129 offset0:160 offset1:162
	s_nop 0
	s_nop 0
	s_nop 0
	s_nop 0
	v_cvt_pk_bf16_f32 v41, v39, v41
	v_cvt_pk_bf16_f32 v40, v38, v40
	v_mov_b32_e32 v39, v241
	v_mov_b32_e32 v38, v242
	s_and_b64 vcc, exec, s[42:43]
	s_waitcnt lgkmcnt(0)
	v_mfma_f32_32x32x16_bf16 v[18:33], v[34:37], v[38:41], v[18:33]
	ds_read2_b64 v[34:37], v128 offset0:160 offset1:162
	ds_read2_b64 v[42:45], v129 offset0:164 offset1:166
	s_waitcnt lgkmcnt(0)
	v_mfma_f32_32x32x16_bf16 v[2:17], v[34:37], v[38:41], v[2:17]
	v_mul_f32_e64 v36, v86, v82
	v_mul_f32_e64 v37, v87, v83
	v_mul_f32_e64 v40, v90, v82
	v_mul_f32_e64 v41, v91, v83
	v_mul_f32_e64 v38, v88, v82
	v_mul_f32_e64 v39, v89, v83
	s_nop 0
	s_nop 0
	v_bfe_u32 v48, v37, 16, 1
	v_bfe_u32 v49, v36, 16, 1
	v_add3_u32 v49, v36, v49, s33
	v_add3_u32 v48, v37, v48, s33
	s_nop 0
	s_nop 0
	s_nop 0
	s_nop 0
	v_pk_mul_f32 v[34:35], v[84:85], v[82:83]
	s_nop 0
	s_nop 0
	v_cvt_pk_bf16_f32 v36, v38, v40
	v_bfe_u32 v40, v34, 16, 1
	v_cvt_pk_bf16_f32 v37, v39, v41
	v_bfe_u32 v41, v35, 16, 1
	s_nop 0
	s_nop 0
	v_add3_u32 v35, v35, v41, s33
	v_add3_u32 v34, v34, v40, s33
	s_nop 0
	s_nop 0
	ds_read2_b64 v[38:41], v128 offset0:164 offset1:166
	v_lshrrev_b32_e32 v34, 16, v34
	v_lshrrev_b32_e32 v35, 16, v35
	v_and_or_b32 v35, v48, s96, v35
	v_and_or_b32 v34, v49, s96, v34
	s_nop 1
	v_mfma_f32_32x32x16_bf16 v[18:33], v[42:45], v[34:37], v[18:33]
	s_waitcnt lgkmcnt(0)
	v_mfma_f32_32x32x16_bf16 v[2:17], v[38:41], v[34:37], v[2:17]
	s_cbranch_vccnz .LBB0_1154
	v_pk_mul_f32 v[36:37], v[76:77], v[82:83]
	v_pk_mul_f32 v[40:41], v[80:81], v[82:83]
	v_pk_mul_f32 v[34:35], v[74:75], v[82:83]
	v_pk_mul_f32 v[38:39], v[78:79], v[82:83]
	s_nop 0
	s_nop 0
	s_nop 0
	s_nop 0
	s_nop 0
	s_nop 0
	s_nop 0
	s_nop 0
	s_nop 0
	s_nop 0
	s_nop 0
	s_nop 0
	s_nop 0
	s_nop 0
	s_nop 0
	s_nop 0
	v_cvt_pk_bf16_f32 v241, v35, v37
	v_cvt_pk_bf16_f32 v242, v34, v36
	ds_read2_b64 v[34:37], v129 offset0:168 offset1:170
	s_nop 0
	s_nop 0
	s_nop 0
	s_nop 0
	v_cvt_pk_bf16_f32 v41, v39, v41
	v_cvt_pk_bf16_f32 v40, v38, v40
	v_mov_b32_e32 v39, v241
	v_mov_b32_e32 v38, v242
	s_waitcnt lgkmcnt(0)
	s_nop 0
	v_mfma_f32_32x32x16_bf16 v[18:33], v[34:37], v[38:41], v[18:33]
	ds_read2_b64 v[34:37], v128 offset0:168 offset1:170
	ds_read2_b64 v[42:45], v129 offset0:172 offset1:174
	s_waitcnt lgkmcnt(0)
	v_mfma_f32_32x32x16_bf16 v[2:17], v[34:37], v[38:41], v[2:17]
	v_mul_f32_e64 v36, v68, v82
	v_mul_f32_e64 v37, v69, v83
	v_mul_f32_e64 v40, v72, v82
	v_mul_f32_e64 v41, v73, v83
	v_mul_f32_e64 v38, v70, v82
	v_mul_f32_e64 v39, v71, v83
	s_nop 0
	s_nop 0
	v_bfe_u32 v48, v37, 16, 1
	v_bfe_u32 v49, v36, 16, 1
	v_add3_u32 v49, v36, v49, s33
	v_add3_u32 v48, v37, v48, s33
	s_nop 0
	s_nop 0
	s_nop 0
	s_nop 0
	v_pk_mul_f32 v[34:35], v[66:67], v[82:83]
	s_nop 0
	s_nop 0
	v_cvt_pk_bf16_f32 v36, v38, v40
	v_bfe_u32 v40, v34, 16, 1
	v_cvt_pk_bf16_f32 v37, v39, v41
	v_bfe_u32 v41, v35, 16, 1
	s_nop 0
	s_nop 0
	v_add3_u32 v35, v35, v41, s33
	v_add3_u32 v34, v34, v40, s33
	s_nop 0
	s_nop 0
	ds_read2_b64 v[38:41], v128 offset0:172 offset1:174
	v_lshrrev_b32_e32 v34, 16, v34
	v_lshrrev_b32_e32 v35, 16, v35
	v_and_or_b32 v35, v48, s96, v35
	v_and_or_b32 v34, v49, s96, v34
	s_nop 1
	v_mfma_f32_32x32x16_bf16 v[18:33], v[42:45], v[34:37], v[18:33]
	s_waitcnt lgkmcnt(0)
	v_mfma_f32_32x32x16_bf16 v[2:17], v[38:41], v[34:37], v[2:17]

; #define LAS __attribute__((address_space(3)))
; #define LDS_WAIT() asm volatile("s_waitcnt lgkmcnt(0)" ::: "memory")
; __device__ __forceinline__ unsigned pk2(float lo, float hi) { return f2bf(lo) | (f2bf(hi) << 16); }
; __device__ __forceinline__ void transpose_item(const float* W, int K, int N, bf16* WT, LAS float* scr, int item, int lane, const float* kscale = nullptr) {
;     ...
;       for (int i = 0; i < 8; ++i) { const int kk = 8 * i + (lane >> 3); t[i] = *(const f32x4*)(W + (size_t)(k0 + kk) * N + n0 + 4 * (lane & 7)); sc[i] = kscale ? kscale[k0 + kk] : 1.0f; }
; #pragma unroll
;       for (int i = 0; i < 8; ++i) { const int kk = 8 * i + (lane >> 3); LAS float* d = scr + kk * 33 + 4 * (lane & 7); d[0] = t[i].x * sc[i]; d[1] = t[i].y * sc[i]; d[2] = t[i].z * sc[i]; d[3] = t[i].w * sc[i]; } }
;     LDS_WAIT(); asm volatile("" ::: "memory");
;     const int c = lane & 7;
; #pragma unroll
;     for (int j = 0; j < 4; ++j) { const int n = (lane >> 3) + 8 * j; const LAS float* s = scr + (8 * c) * 33 + n;
;         v4u o; o.x = pk2(s[0 * 33], s[1 * 33]); o.y = pk2(s[2 * 33], s[3 * 33]); o.z = pk2(s[4 * 33], s[5 * 33]); o.w = pk2(s[6 * 33], s[7 * 33]);
;         *(v4u*)(WT + (size_t)(n0 + n) * K + k0 + 8 * c) = o; }
.LBB0_1314:
	s_waitcnt vmcnt(0)
	v_pk_mul_f32 v[2:3], v[2:3], v[44:45] op_sel_hi:[1,0]
	v_add_u32_e32 v48, v37, v39
	ds_write2_b32 v48, v2, v3 offset1:1
	v_pk_mul_f32 v[2:3], v[4:5], v[44:45] op_sel_hi:[1,0]
	ds_write2_b32 v48, v2, v3 offset0:2 offset1:3
	v_pk_mul_f32 v[2:3], v[6:7], v[0:1] op_sel_hi:[1,0]
	v_add_u32_e32 v4, 0x420, v48
	ds_write2_b32 v4, v2, v3 offset1:1
	v_pk_mul_f32 v[2:3], v[8:9], v[0:1] op_sel_hi:[1,0]
	v_add_u32_e32 v0, 0x428, v48
	ds_write2_b32 v0, v2, v3 offset1:1
	v_pk_mul_f32 v[2:3], v[10:11], v[50:51] op_sel_hi:[1,0]
	v_add_u32_e32 v0, 0x840, v48
	ds_write2_b32 v0, v2, v3 offset1:1
	v_pk_mul_f32 v[2:3], v[12:13], v[50:51] op_sel_hi:[1,0]
	v_add_u32_e32 v0, 0x848, v48
	ds_write2_b32 v0, v2, v3 offset1:1
	v_pk_mul_f32 v[2:3], v[14:15], v[46:47] op_sel_hi:[1,0]
	v_add_u32_e32 v0, 0xc60, v48
	ds_write2_b32 v0, v2, v3 offset1:1
	v_pk_mul_f32 v[2:3], v[16:17], v[46:47] op_sel_hi:[1,0]
	v_add_u32_e32 v0, 0xc68, v48
	ds_write2_b32 v0, v2, v3 offset1:1
	v_pk_mul_f32 v[2:3], v[18:19], v[54:55] op_sel_hi:[1,0]
	v_add_u32_e32 v0, 0x1080, v48
	ds_write2_b32 v0, v2, v3 offset1:1
	v_pk_mul_f32 v[2:3], v[20:21], v[54:55] op_sel_hi:[1,0]
	v_add_u32_e32 v0, 0x1088, v48
	ds_write2_b32 v0, v2, v3 offset1:1
	v_pk_mul_f32 v[2:3], v[22:23], v[52:53] op_sel_hi:[1,0]
	v_add_u32_e32 v0, 0x14a0, v48
	ds_write2_b32 v0, v2, v3 offset1:1
	v_pk_mul_f32 v[2:3], v[24:25], v[52:53] op_sel_hi:[1,0]
	v_add_u32_e32 v0, 0x14a8, v48
	ds_write2_b32 v0, v2, v3 offset1:1
	v_pk_mul_f32 v[2:3], v[26:27], v[58:59] op_sel_hi:[1,0]
	v_add_u32_e32 v0, 0x18c0, v48
	s_mul_i32 s1, s36, 0x1600000
	ds_write2_b32 v0, v2, v3 offset1:1
	v_pk_mul_f32 v[2:3], v[28:29], v[58:59] op_sel_hi:[1,0]
	v_add_u32_e32 v0, 0x18c8, v48
	s_mul_hi_i32 s0, s36, 0x1600000
	s_add_u32 s18, s13, s1
	ds_write2_b32 v0, v2, v3 offset1:1
	v_pk_mul_f32 v[2:3], v[30:31], v[56:57] op_sel_hi:[1,0]
	v_add_u32_e32 v0, 0x1ce0, v48
	s_addc_u32 s19, s14, s0
	ds_write2_b32 v0, v2, v3 offset1:1
	v_pk_mul_f32 v[2:3], v[32:33], v[56:57] op_sel_hi:[1,0]
	v_add_u32_e32 v0, 0x1ce8, v48
	s_ashr_i32 s41, s40, 31
	ds_write2_b32 v0, v2, v3 offset1:1
	s_lshl_b64 s[0:1], s[40:41], 1
	s_waitcnt lgkmcnt(0)
	s_add_u32 s0, s18, s0
	s_addc_u32 s1, s19, s1
	v_lshlrev_b32_e32 v0, 1, v42
	v_lshl_add_u64 v[6:7], s[0:1], 0, v[0:1]
	ds_read_b32 v0, v47
	ds_read_b32 v2, v47 offset:132
	ds_read_b32 v3, v47 offset:264
	ds_read_b32 v4, v47 offset:396
	ds_read_b32 v5, v47 offset:528
	ds_read_b32 v8, v47 offset:660
	ds_read_b32 v9, v47 offset:792
	ds_read_b32 v10, v47 offset:924
	s_waitcnt lgkmcnt(7)
	s_nop 0
	s_nop 0
	s_waitcnt lgkmcnt(6)
	s_nop 0
	s_nop 0
	s_nop 0
	v_cvt_pk_bf16_f32 v2, v0, v2
	s_waitcnt lgkmcnt(5)
	s_nop 0
	s_nop 0
	s_waitcnt lgkmcnt(4)
	s_nop 0
	s_nop 0
	s_nop 0
	v_cvt_pk_bf16_f32 v3, v3, v4
	s_waitcnt lgkmcnt(3)
	s_nop 0
	s_nop 0
	s_waitcnt lgkmcnt(2)
	s_nop 0
	s_nop 0
	s_nop 0
	v_cvt_pk_bf16_f32 v4, v5, v8
	s_waitcnt lgkmcnt(1)
	s_nop 0
	v_or_b32_e32 v8, s38, v35
	s_nop 0
	s_waitcnt lgkmcnt(0)
	s_nop 0
	v_cvt_pk_bf16_f32 v5, v9, v10
	v_ashrrev_i32_e32 v9, 31, v8
	s_nop 0
	s_nop 0
	v_lshlrev_b64 v[8:9], 12, v[8:9]
	s_nop 0
	v_lshl_add_u64 v[8:9], v[6:7], 0, v[8:9]
	flat_store_dwordx4 v[8:9], v[2:5]
	ds_read_b32 v0, v47 offset:32
	ds_read_b32 v2, v47 offset:164
	ds_read_b32 v3, v47 offset:296
	ds_read_b32 v4, v47 offset:428
	ds_read_b32 v5, v47 offset:560
	ds_read_b32 v8, v47 offset:692
	ds_read_b32 v9, v47 offset:824
	ds_read_b32 v10, v47 offset:956
	s_waitcnt lgkmcnt(0)
	s_nop 0
	s_nop 0
	s_nop 0
	s_nop 0
	s_nop 0
	v_cvt_pk_bf16_f32 v2, v0, v2
	s_nop 0
	s_nop 0
	s_nop 0
	s_nop 0
	s_nop 0
	v_cvt_pk_bf16_f32 v3, v3, v4
	s_nop 0
	s_nop 0
	s_nop 0
	s_nop 0
	s_nop 0
	v_cvt_pk_bf16_f32 v4, v5, v8
	s_nop 0
	v_or_b32_e32 v8, s38, v41
	s_nop 0
	s_nop 0
	v_cvt_pk_bf16_f32 v5, v9, v10
	v_ashrrev_i32_e32 v9, 31, v8
	s_nop 0
	s_nop 0
	v_lshlrev_b64 v[8:9], 12, v[8:9]
	s_nop 0
	v_lshl_add_u64 v[8:9], v[6:7], 0, v[8:9]
	flat_store_dwordx4 v[8:9], v[2:5]
	ds_read_b32 v0, v47 offset:64
	ds_read_b32 v2, v47 offset:196
	ds_read_b32 v3, v47 offset:328
	ds_read_b32 v4, v47 offset:460
	ds_read_b32 v5, v47 offset:592
	ds_read_b32 v8, v47 offset:724
	ds_read_b32 v9, v47 offset:856
	ds_read_b32 v10, v47 offset:988
	s_waitcnt lgkmcnt(0)
	s_nop 0
	s_nop 0
	s_nop 0
	s_nop 0
	s_nop 0
	v_cvt_pk_bf16_f32 v2, v0, v2
	s_nop 0
	s_nop 0
	s_nop 0
	s_nop 0
	s_nop 0
	v_cvt_pk_bf16_f32 v3, v3, v4
	s_nop 0
	s_nop 0
	s_nop 0
	s_nop 0
	s_nop 0
	v_cvt_pk_bf16_f32 v4, v5, v8
	s_nop 0
	v_or_b32_e32 v8, s38, v43
	s_nop 0
	s_nop 0
	v_cvt_pk_bf16_f32 v5, v9, v10
	v_ashrrev_i32_e32 v9, 31, v8
	s_nop 0
	s_nop 0
	v_lshlrev_b64 v[8:9], 12, v[8:9]
	s_nop 0
	v_lshl_add_u64 v[8:9], v[6:7], 0, v[8:9]
	flat_store_dwordx4 v[8:9], v[2:5]
	ds_read_b32 v0, v47 offset:96
	ds_read_b32 v2, v47 offset:228
	ds_read_b32 v3, v47 offset:360
	ds_read_b32 v4, v47 offset:492
	ds_read_b32 v5, v47 offset:624
	ds_read_b32 v8, v47 offset:756
	ds_read_b32 v9, v47 offset:888
	ds_read_b32 v10, v47 offset:1020
	s_waitcnt lgkmcnt(0)
	s_nop 0
	s_nop 0
	s_nop 0
	s_nop 0
	s_nop 0
	v_cvt_pk_bf16_f32 v2, v0, v2
	s_nop 0
	s_nop 0
	s_nop 0
	s_nop 0
	s_nop 0
	v_cvt_pk_bf16_f32 v3, v3, v4
	s_nop 0
	s_nop 0
	s_nop 0
	s_nop 0
	s_nop 0
	v_cvt_pk_bf16_f32 v4, v5, v8
	s_nop 0
	v_or_b32_e32 v8, s38, v45
	s_nop 0
	s_nop 0
	v_cvt_pk_bf16_f32 v5, v9, v10
	v_ashrrev_i32_e32 v9, 31, v8
	s_nop 0
	s_nop 0
	v_lshlrev_b64 v[8:9], 12, v[8:9]
	s_nop 0
	v_lshl_add_u64 v[6:7], v[6:7], 0, v[8:9]
	flat_store_dwordx4 v[6:7], v[2:5]
	s_waitcnt lgkmcnt(0)

; #define LAS __attribute__((address_space(3)))
; #define LDS_WAIT() asm volatile("s_waitcnt lgkmcnt(0)" ::: "memory")
; __device__ __forceinline__ unsigned pk2(float lo, float hi) { return f2bf(lo) | (f2bf(hi) << 16); }
; __device__ __forceinline__ void transpose_item(const float* W, int K, int N, bf16* WT, LAS float* scr, int item, int lane, const float* kscale = nullptr) {
;     const int nblk = N / 32, kb = item / nblk, nb = item % nblk, k0 = 64 * kb, n0 = 32 * nb;
;     { f32x4 t[8]; float sc[8];
; #pragma unroll
;       for (int i = 0; i < 8; ++i) { const int kk = 8 * i + (lane >> 3); t[i] = *(const f32x4*)(W + (size_t)(k0 + kk) * N + n0 + 4 * (lane & 7)); sc[i] = kscale ? kscale[k0 + kk] : 1.0f; }
; #pragma unroll
;       for (int i = 0; i < 8; ++i) { const int kk = 8 * i + (lane >> 3); LAS float* d = scr + kk * 33 + 4 * (lane & 7); d[0] = t[i].x * sc[i]; d[1] = t[i].y * sc[i]; d[2] = t[i].z * sc[i]; d[3] = t[i].w * sc[i]; } }
;     LDS_WAIT(); asm volatile("" ::: "memory");
;     const int c = lane & 7;
; #pragma unroll
;     for (int j = 0; j < 4; ++j) { const int n = (lane >> 3) + 8 * j; const LAS float* s = scr + (8 * c) * 33 + n;
;         v4u o; o.x = pk2(s[0 * 33], s[1 * 33]); o.y = pk2(s[2 * 33], s[3 * 33]); o.z = pk2(s[4 * 33], s[5 * 33]); o.w = pk2(s[6 * 33], s[7 * 33]);
;         *(v4u*)(WT + (size_t)(n0 + n) * K + k0 + 8 * c) = o; }
;     LDS_WAIT(); asm volatile("" ::: "memory");
; __device__ __forceinline__ void phase_prologue(const Args& A, const Ctx& C0) {
;     ...
;         { const int g = r >> 3; transpose_item(A.in[I_POOLW] + (size_t)(l * 4 + g) * 128 * 128, 128, 128, WS_PTR(bf16, WS_PWT) + (size_t)(l * 4 + g) * 128 * 128, scr, r & 7, C.lane); }
.LBB0_1318:
	s_cmpk_gt_u32 s18, 0x1d7f
	s_cbranch_scc0 .LBB0_1320
	s_add_i32 s0, s18, 0xffffe280
	s_lshr_b32 s0, s0, 3
	s_lshl_b32 s1, s36, 2
	s_add_i32 s0, s0, s1
	s_ashr_i32 s1, s0, 31
	v_readlane_b32 s40, v255, 4
	s_lshl_b64 s[30:31], s[0:1], 16
	v_readlane_b32 s44, v255, 8
	v_readlane_b32 s45, v255, 9
	s_add_u32 s19, s44, s30
	s_addc_u32 s27, s45, s31
	s_lshl_b64 s[0:1], s[0:1], 15
	s_add_u32 s37, s2, s0
	s_addc_u32 s1, s3, s1
	s_and_b32 s0, s18, 7
	s_add_i32 s30, s0, 0xfffc
	s_and_b32 s30, s30, 0xffff
	s_min_u32 s30, s0, s30
	s_cmp_gt_u32 s0, 3
	s_cselect_b32 s38, 64, 0
	s_lshl_b32 s0, s30, 5
	s_lshl_b32 s30, s30, 7
	s_add_u32 s30, s19, s30
	v_or_b32_e32 v4, s38, v35
	s_addc_u32 s31, s27, 0
	v_lshlrev_b32_e32 v0, 2, v40
	s_waitcnt lgkmcnt(0)
	v_lshl_add_u64 v[2:3], s[30:31], 0, v[0:1]
	v_lshlrev_b32_e32 v0, 9, v4
	v_lshl_add_u64 v[2:3], v[2:3], 0, v[0:1]
	s_movk_i32 s19, 0x2000
	v_add_co_u32_e32 v12, vcc, s19, v2
	s_movk_i32 s19, 0x4000
	s_nop 0
	v_addc_co_u32_e32 v13, vcc, 0, v3, vcc
	v_add_co_u32_e32 v20, vcc, s19, v2
	s_movk_i32 s19, 0x6000
	s_nop 0
	v_addc_co_u32_e32 v21, vcc, 0, v3, vcc
	v_add_co_u32_e32 v28, vcc, s19, v2
	global_load_dwordx4 v[4:7], v[2:3], off
	s_nop 0
	v_addc_co_u32_e32 v29, vcc, 0, v3, vcc
	global_load_dwordx4 v[8:11], v[12:13], off offset:-4096
	s_nop 0
	global_load_dwordx4 v[12:15], v[12:13], off
	s_nop 0
	global_load_dwordx4 v[16:19], v[20:21], off offset:-4096
	s_nop 0
	global_load_dwordx4 v[20:23], v[20:21], off
	s_nop 0
	global_load_dwordx4 v[24:27], v[28:29], off offset:-4096
	s_nop 0
	global_load_dwordx4 v[28:31], v[28:29], off
	s_movk_i32 s19, 0x7000
	v_add_co_u32_e32 v2, vcc, s19, v2
	v_add_u32_e32 v32, v37, v39
	s_nop 0
	v_addc_co_u32_e32 v3, vcc, 0, v3, vcc
	global_load_dwordx4 v[48:51], v[2:3], off
	v_add_u32_e32 v33, 0x420, v32
	v_add_u32_e32 v44, 0x428, v32
	v_add_u32_e32 v46, 0x840, v32
	v_add_u32_e32 v52, 0x848, v32
	v_add_u32_e32 v53, 0xc60, v32
	v_add_u32_e32 v54, 0xc68, v32
	v_add_u32_e32 v55, 0x1080, v32
	v_add_u32_e32 v56, 0x1088, v32
	v_add_u32_e32 v57, 0x14a0, v32
	v_add_u32_e32 v58, 0x14a8, v32
	v_add_u32_e32 v59, 0x18c0, v32
	v_add_u32_e32 v60, 0x18c8, v32
	v_add_u32_e32 v61, 0x1ce0, v32
	v_add_u32_e32 v62, 0x1ce8, v32
	s_lshl_b32 s19, s38, 1
	s_add_u32 s30, s37, s19
	s_addc_u32 s31, s1, 0
	v_lshlrev_b32_e32 v0, 1, v42
	v_lshl_add_u64 v[2:3], s[30:31], 0, v[0:1]
	v_readlane_b32 s41, v255, 5
	v_readlane_b32 s42, v255, 6
	v_readlane_b32 s43, v255, 7
	v_readlane_b32 s46, v255, 10
	v_readlane_b32 s47, v255, 11
	v_readlane_b32 s48, v255, 12
	v_readlane_b32 s49, v255, 13
	v_readlane_b32 s50, v255, 14
	v_readlane_b32 s51, v255, 15
	v_readlane_b32 s52, v255, 16
	v_readlane_b32 s53, v255, 17
	v_readlane_b32 s54, v255, 18
	v_readlane_b32 s55, v255, 19
	s_waitcnt vmcnt(0)
	ds_write2_b32 v32, v4, v5 offset1:1
	ds_write2_b32 v32, v6, v7 offset0:2 offset1:3
	ds_write2_b32 v33, v8, v9 offset1:1
	ds_write2_b32 v44, v10, v11 offset1:1
	ds_write2_b32 v46, v12, v13 offset1:1
	ds_write2_b32 v52, v14, v15 offset1:1
	ds_write2_b32 v53, v16, v17 offset1:1
	ds_write2_b32 v54, v18, v19 offset1:1
	ds_write2_b32 v55, v20, v21 offset1:1
	ds_write2_b32 v56, v22, v23 offset1:1
	ds_write2_b32 v57, v24, v25 offset1:1
	ds_write2_b32 v58, v26, v27 offset1:1
	ds_write2_b32 v59, v28, v29 offset1:1
	ds_write2_b32 v60, v30, v31 offset1:1
	ds_write2_b32 v61, v48, v49 offset1:1
	ds_write2_b32 v62, v50, v51 offset1:1
	s_waitcnt lgkmcnt(0)
	ds_read_b32 v0, v47
	ds_read_b32 v4, v47 offset:132
	ds_read_b32 v5, v47 offset:264
	ds_read_b32 v6, v47 offset:396
	ds_read_b32 v7, v47 offset:528
	ds_read_b32 v8, v47 offset:660
	ds_read_b32 v9, v47 offset:792
	ds_read_b32 v10, v47 offset:924
	s_waitcnt lgkmcnt(7)
	s_nop 0
	s_waitcnt lgkmcnt(6)
	s_nop 0
	s_waitcnt lgkmcnt(5)
	s_nop 0
	s_waitcnt lgkmcnt(3)
	s_nop 0
	s_nop 0
	s_nop 0
	s_waitcnt lgkmcnt(2)
	s_nop 0
	s_nop 0
	s_nop 0
	s_nop 0
	s_nop 0
	s_nop 0
	s_nop 0
	s_nop 0
	v_cvt_pk_bf16_f32 v4, v0, v4
	s_nop 0
	v_cvt_pk_bf16_f32 v5, v5, v6
	v_cvt_pk_bf16_f32 v6, v7, v8
	s_waitcnt lgkmcnt(1)
	s_nop 0
	s_nop 0
	s_waitcnt lgkmcnt(0)
	s_nop 0
	s_nop 0
	s_nop 0
	v_cvt_pk_bf16_f32 v7, v9, v10
	v_or_b32_e32 v0, s0, v35
	v_lshlrev_b32_e32 v0, 8, v0
	v_lshl_add_u64 v[8:9], v[2:3], 0, v[0:1]
	flat_store_dwordx4 v[8:9], v[4:7]
	ds_read_b32 v0, v47 offset:32
	ds_read_b32 v4, v47 offset:164
	ds_read_b32 v5, v47 offset:296
	ds_read_b32 v6, v47 offset:428
	ds_read_b32 v7, v47 offset:560
	ds_read_b32 v8, v47 offset:692
	ds_read_b32 v9, v47 offset:824
	ds_read_b32 v10, v47 offset:956
	s_waitcnt lgkmcnt(0)
	s_nop 0
	s_nop 0
	s_nop 0
	s_nop 0
	s_nop 0
	v_cvt_pk_bf16_f32 v4, v0, v4
	s_nop 0
	s_nop 0
	s_nop 0
	s_nop 0
	s_nop 0
	v_cvt_pk_bf16_f32 v5, v5, v6
	s_nop 0
	s_nop 0
	s_nop 0
	s_nop 0
	s_nop 0
	v_cvt_pk_bf16_f32 v6, v7, v8
	s_nop 0
	s_nop 0
	s_nop 0
	s_nop 0
	s_nop 0
	v_cvt_pk_bf16_f32 v7, v9, v10
	v_or_b32_e32 v0, s0, v41
	v_lshlrev_b32_e32 v0, 8, v0
	v_lshl_add_u64 v[8:9], v[2:3], 0, v[0:1]
	flat_store_dwordx4 v[8:9], v[4:7]
	ds_read_b32 v0, v47 offset:64
	ds_read_b32 v4, v47 offset:196
	ds_read_b32 v5, v47 offset:328
	ds_read_b32 v6, v47 offset:460
	ds_read_b32 v7, v47 offset:592
	ds_read_b32 v8, v47 offset:724
	ds_read_b32 v9, v47 offset:856
	ds_read_b32 v10, v47 offset:988
	s_waitcnt lgkmcnt(0)
	s_nop 0
	s_nop 0
	s_nop 0
	s_nop 0
	s_nop 0
	v_cvt_pk_bf16_f32 v4, v0, v4
	s_nop 0
	s_nop 0
	s_nop 0
	s_nop 0
	s_nop 0
	v_cvt_pk_bf16_f32 v5, v5, v6
	s_nop 0
	s_nop 0
	s_nop 0
	s_nop 0
	s_nop 0
	v_cvt_pk_bf16_f32 v6, v7, v8
	s_nop 0
	s_nop 0
	s_nop 0
	s_nop 0
	s_nop 0
	v_cvt_pk_bf16_f32 v7, v9, v10
	v_or_b32_e32 v0, s0, v43
	v_lshlrev_b32_e32 v0, 8, v0
	v_lshl_add_u64 v[8:9], v[2:3], 0, v[0:1]
	flat_store_dwordx4 v[8:9], v[4:7]
	ds_read_b32 v0, v47 offset:96
	ds_read_b32 v4, v47 offset:228
	ds_read_b32 v5, v47 offset:360
	ds_read_b32 v6, v47 offset:492
	ds_read_b32 v7, v47 offset:624
	ds_read_b32 v8, v47 offset:756
	ds_read_b32 v9, v47 offset:888
	ds_read_b32 v10, v47 offset:1020
	s_waitcnt lgkmcnt(0)
	s_nop 0
	s_nop 0
	s_nop 0
	s_nop 0
	s_nop 0
	v_cvt_pk_bf16_f32 v4, v0, v4
	s_nop 0
	s_nop 0
	s_nop 0
	s_nop 0
	s_nop 0
	v_cvt_pk_bf16_f32 v5, v5, v6
	s_nop 0
	s_nop 0
	s_nop 0
	s_nop 0
	s_nop 0
	v_cvt_pk_bf16_f32 v6, v7, v8
	s_nop 0
	s_nop 0
	s_nop 0
	s_nop 0
	s_nop 0
	v_cvt_pk_bf16_f32 v7, v9, v10
	v_or_b32_e32 v0, s0, v45
	v_lshlrev_b32_e32 v0, 8, v0
	v_lshl_add_u64 v[2:3], v[2:3], 0, v[0:1]
	flat_store_dwordx4 v[2:3], v[4:7]
	s_waitcnt lgkmcnt(0)
	s_mov_b64 s[0:1], 0
; #define LAS __attribute__((address_space(3)))
; #define LDS_WAIT() asm volatile("s_waitcnt lgkmcnt(0)" ::: "memory")
; __device__ __forceinline__ unsigned pk2(float lo, float hi) { return f2bf(lo) | (f2bf(hi) << 16); }
; __device__ __forceinline__ void transpose_item(const float* W, int K, int N, bf16* WT, LAS float* scr, int item, int lane, const float* kscale = nullptr) {
;     const int nblk = N / 32, kb = item / nblk, nb = item % nblk, k0 = 64 * kb, n0 = 32 * nb;
;     { f32x4 t[8]; float sc[8];
; #pragma unroll
;       for (int i = 0; i < 8; ++i) { const int kk = 8 * i + (lane >> 3); t[i] = *(const f32x4*)(W + (size_t)(k0 + kk) * N + n0 + 4 * (lane & 7)); sc[i] = kscale ? kscale[k0 + kk] : 1.0f; }
; #pragma unroll
;       for (int i = 0; i < 8; ++i) { const int kk = 8 * i + (lane >> 3); LAS float* d = scr + kk * 33 + 4 * (lane & 7); d[0] = t[i].x * sc[i]; d[1] = t[i].y * sc[i]; d[2] = t[i].z * sc[i]; d[3] = t[i].w * sc[i]; } }
;     LDS_WAIT(); asm volatile("" ::: "memory");
;     const int c = lane & 7;
; #pragma unroll
;     for (int j = 0; j < 4; ++j) { const int n = (lane >> 3) + 8 * j; const LAS float* s = scr + (8 * c) * 33 + n;
;         v4u o; o.x = pk2(s[0 * 33], s[1 * 33]); o.y = pk2(s[2 * 33], s[3 * 33]); o.z = pk2(s[4 * 33], s[5 * 33]); o.w = pk2(s[6 * 33], s[7 * 33]);
;         *(v4u*)(WT + (size_t)(n0 + n) * K + k0 + 8 * c) = o; }
;     LDS_WAIT(); asm volatile("" ::: "memory");
; __device__ __forceinline__ void phase_prologue(const Args& A, const Ctx& C0) {
;     ...
;         if (r < I_OUT) { transpose_item(A.in[I_WOUT] + (size_t)l * D * D, D, D, WS_PTR(bf16, WS_WOUTT) + (size_t)l * D * D, scr, r, C.lane); continue; } r -= I_OUT;
.LBB0_1320:
	s_andn2_b64 vcc, exec, s[0:1]
	s_cbranch_vccnz .LBB0_1322
	s_ashr_i32 s37, s36, 31
	v_readlane_b32 s40, v255, 4
	s_lshl_b64 s[0:1], s[36:37], 24
	v_readlane_b32 s42, v255, 6
	v_readlane_b32 s43, v255, 7
	s_add_u32 s19, s42, s0
	s_addc_u32 s27, s43, s1
	s_lshl_b64 s[0:1], s[36:37], 23
	s_add_u32 s37, s11, s0
	s_addc_u32 s1, s12, s1
	s_add_i32 s0, s18, 0xea80
	s_and_b32 s38, s0, 0xffc0
	s_lshl_b32 s0, s36, 10
	s_sub_i32 s0, s15, s0
	s_and_b32 s0, s0, 0x7e0
	s_lshl_b32 s30, s0, 2
	s_add_u32 s30, s19, s30
	v_or_b32_e32 v4, s38, v35
	s_addc_u32 s31, s27, 0
	v_lshlrev_b32_e32 v0, 2, v40
	s_waitcnt lgkmcnt(0)
	v_lshl_add_u64 v[2:3], s[30:31], 0, v[0:1]
	v_lshlrev_b32_e32 v0, 13, v4
	v_lshl_add_u64 v[2:3], v[2:3], 0, v[0:1]
	s_mov_b32 s19, 0x10000
	v_add_co_u32_e32 v8, vcc, s19, v2
	s_mov_b32 s19, 0x20000
	s_nop 0
	v_addc_co_u32_e32 v9, vcc, 0, v3, vcc
	v_add_co_u32_e32 v12, vcc, s19, v2
	s_mov_b32 s19, 0x30000
	s_nop 0
	v_addc_co_u32_e32 v13, vcc, 0, v3, vcc
	v_add_co_u32_e32 v16, vcc, s19, v2
	s_mov_b32 s19, 0x40000
	s_nop 0
	v_addc_co_u32_e32 v17, vcc, 0, v3, vcc
	v_add_co_u32_e32 v20, vcc, s19, v2
	s_mov_b32 s19, 0x50000
	s_nop 0
	v_addc_co_u32_e32 v21, vcc, 0, v3, vcc
	v_add_co_u32_e32 v24, vcc, s19, v2
	global_load_dwordx4 v[4:7], v[2:3], off
	s_nop 0
	global_load_dwordx4 v[8:11], v[8:9], off
	v_addc_co_u32_e32 v25, vcc, 0, v3, vcc
	global_load_dwordx4 v[12:15], v[12:13], off
	s_nop 0
	global_load_dwordx4 v[16:19], v[16:17], off
	s_nop 0
	global_load_dwordx4 v[20:23], v[20:21], off
	s_nop 0
	global_load_dwordx4 v[24:27], v[24:25], off
	s_mov_b32 s19, 0x60000
	v_add_co_u32_e32 v28, vcc, s19, v2
	s_mov_b32 s19, 0x70000
	s_nop 0
	v_addc_co_u32_e32 v29, vcc, 0, v3, vcc
	global_load_dwordx4 v[28:31], v[28:29], off
	v_add_co_u32_e32 v2, vcc, s19, v2
	v_add_u32_e32 v32, v37, v39
	s_nop 0
	v_addc_co_u32_e32 v3, vcc, 0, v3, vcc
	global_load_dwordx4 v[48:51], v[2:3], off
	v_add_u32_e32 v33, 0x420, v32
	v_add_u32_e32 v44, 0x428, v32
	v_add_u32_e32 v46, 0x840, v32
	v_add_u32_e32 v52, 0x848, v32
	v_add_u32_e32 v53, 0xc60, v32
	v_add_u32_e32 v54, 0xc68, v32
	v_add_u32_e32 v55, 0x1080, v32
	v_add_u32_e32 v56, 0x1088, v32
	v_add_u32_e32 v57, 0x14a0, v32
	v_add_u32_e32 v58, 0x14a8, v32
	v_add_u32_e32 v59, 0x18c0, v32
	v_add_u32_e32 v60, 0x18c8, v32
	v_add_u32_e32 v61, 0x1ce0, v32
	v_add_u32_e32 v62, 0x1ce8, v32
	s_lshl_b32 s19, s38, 1
	s_add_u32 s30, s37, s19
	s_addc_u32 s31, s1, 0
	v_lshlrev_b32_e32 v0, 1, v42
	v_lshl_add_u64 v[2:3], s[30:31], 0, v[0:1]
	v_readlane_b32 s41, v255, 5
	v_readlane_b32 s44, v255, 8
	v_readlane_b32 s45, v255, 9
	v_readlane_b32 s46, v255, 10
	v_readlane_b32 s47, v255, 11
	v_readlane_b32 s48, v255, 12
	v_readlane_b32 s49, v255, 13
	v_readlane_b32 s50, v255, 14
	v_readlane_b32 s51, v255, 15
	v_readlane_b32 s52, v255, 16
	v_readlane_b32 s53, v255, 17
	v_readlane_b32 s54, v255, 18
	v_readlane_b32 s55, v255, 19
	s_waitcnt vmcnt(0)
	ds_write2_b32 v32, v4, v5 offset1:1
	ds_write2_b32 v32, v6, v7 offset0:2 offset1:3
	ds_write2_b32 v33, v8, v9 offset1:1
	ds_write2_b32 v44, v10, v11 offset1:1
	ds_write2_b32 v46, v12, v13 offset1:1
	ds_write2_b32 v52, v14, v15 offset1:1
	ds_write2_b32 v53, v16, v17 offset1:1
	ds_write2_b32 v54, v18, v19 offset1:1
	ds_write2_b32 v55, v20, v21 offset1:1
	ds_write2_b32 v56, v22, v23 offset1:1
	ds_write2_b32 v57, v24, v25 offset1:1
	ds_write2_b32 v58, v26, v27 offset1:1
	ds_write2_b32 v59, v28, v29 offset1:1
	ds_write2_b32 v60, v30, v31 offset1:1
	ds_write2_b32 v61, v48, v49 offset1:1
	ds_write2_b32 v62, v50, v51 offset1:1
	s_waitcnt lgkmcnt(0)
	ds_read_b32 v0, v47
	ds_read_b32 v4, v47 offset:132
	ds_read_b32 v5, v47 offset:264
	ds_read_b32 v6, v47 offset:396
	ds_read_b32 v7, v47 offset:528
	ds_read_b32 v8, v47 offset:660
	ds_read_b32 v9, v47 offset:792
	ds_read_b32 v10, v47 offset:924
	s_waitcnt lgkmcnt(7)
	s_nop 0
	s_waitcnt lgkmcnt(6)
	s_nop 0
	s_nop 0
	s_nop 0
	s_nop 0
	v_cvt_pk_bf16_f32 v4, v0, v4
	s_waitcnt lgkmcnt(5)
	s_nop 0
	s_nop 0
	s_waitcnt lgkmcnt(4)
	s_nop 0
	s_nop 0
	s_nop 0
	v_cvt_pk_bf16_f32 v5, v5, v6
	s_waitcnt lgkmcnt(3)
	s_nop 0
	s_nop 0
	s_waitcnt lgkmcnt(2)
	s_nop 0
	s_nop 0
	s_nop 0
	v_cvt_pk_bf16_f32 v6, v7, v8
	s_waitcnt lgkmcnt(1)
	s_nop 0
	s_nop 0
	s_waitcnt lgkmcnt(0)
	s_nop 0
	s_nop 0
	s_nop 0
	v_cvt_pk_bf16_f32 v7, v9, v10
	v_or_b32_e32 v0, s0, v35
	v_lshlrev_b32_e32 v0, 12, v0
	v_lshl_add_u64 v[8:9], v[2:3], 0, v[0:1]
	flat_store_dwordx4 v[8:9], v[4:7]
	ds_read_b32 v0, v47 offset:32
	ds_read_b32 v4, v47 offset:164
	ds_read_b32 v5, v47 offset:296
	ds_read_b32 v6, v47 offset:428
	ds_read_b32 v7, v47 offset:560
	ds_read_b32 v8, v47 offset:692
	ds_read_b32 v9, v47 offset:824
	ds_read_b32 v10, v47 offset:956
	s_waitcnt lgkmcnt(0)
	s_nop 0
	s_nop 0
	s_nop 0
	s_nop 0
	s_nop 0
	v_cvt_pk_bf16_f32 v4, v0, v4
	s_nop 0
	s_nop 0
	s_nop 0
	s_nop 0
	s_nop 0
	v_cvt_pk_bf16_f32 v5, v5, v6
	s_nop 0
	s_nop 0
	s_nop 0
	s_nop 0
	s_nop 0
	v_cvt_pk_bf16_f32 v6, v7, v8
	s_nop 0
	s_nop 0
	s_nop 0
	s_nop 0
	s_nop 0
	v_cvt_pk_bf16_f32 v7, v9, v10
	v_or_b32_e32 v0, s0, v41
	v_lshlrev_b32_e32 v0, 12, v0
	v_lshl_add_u64 v[8:9], v[2:3], 0, v[0:1]
	flat_store_dwordx4 v[8:9], v[4:7]
	ds_read_b32 v0, v47 offset:64
	ds_read_b32 v4, v47 offset:196
	ds_read_b32 v5, v47 offset:328
	ds_read_b32 v6, v47 offset:460
	ds_read_b32 v7, v47 offset:592
	ds_read_b32 v8, v47 offset:724
	ds_read_b32 v9, v47 offset:856
	ds_read_b32 v10, v47 offset:988
	s_waitcnt lgkmcnt(0)
	s_nop 0
	s_nop 0
	s_nop 0
	s_nop 0
	s_nop 0
	v_cvt_pk_bf16_f32 v4, v0, v4
	s_nop 0
	s_nop 0
	s_nop 0
	s_nop 0
	s_nop 0
	v_cvt_pk_bf16_f32 v5, v5, v6
	s_nop 0
	s_nop 0
	s_nop 0
	s_nop 0
	s_nop 0
	v_cvt_pk_bf16_f32 v6, v7, v8
	s_nop 0
	s_nop 0
	s_nop 0
	s_nop 0
	s_nop 0
	v_cvt_pk_bf16_f32 v7, v9, v10
	v_or_b32_e32 v0, s0, v43
	v_lshlrev_b32_e32 v0, 12, v0
	v_lshl_add_u64 v[8:9], v[2:3], 0, v[0:1]
	flat_store_dwordx4 v[8:9], v[4:7]
	ds_read_b32 v0, v47 offset:96
	ds_read_b32 v4, v47 offset:228
	ds_read_b32 v5, v47 offset:360
	ds_read_b32 v6, v47 offset:492
	ds_read_b32 v7, v47 offset:624
	ds_read_b32 v8, v47 offset:756
	ds_read_b32 v9, v47 offset:888
	ds_read_b32 v10, v47 offset:1020
	s_waitcnt lgkmcnt(0)
	s_nop 0
	s_nop 0
	s_nop 0
	s_nop 0
	s_nop 0
	v_cvt_pk_bf16_f32 v4, v0, v4
	s_nop 0
	s_nop 0
	s_nop 0
	s_nop 0
	s_nop 0
	v_cvt_pk_bf16_f32 v5, v5, v6
	s_nop 0
	s_nop 0
	s_nop 0
	s_nop 0
	s_nop 0
	v_cvt_pk_bf16_f32 v6, v7, v8
	s_nop 0
	s_nop 0
	s_nop 0
	s_nop 0
	s_nop 0
	v_cvt_pk_bf16_f32 v7, v9, v10
	v_or_b32_e32 v0, s0, v45
	v_lshlrev_b32_e32 v0, 12, v0
	v_lshl_add_u64 v[2:3], v[2:3], 0, v[0:1]
	flat_store_dwordx4 v[2:3], v[4:7]
	s_waitcnt lgkmcnt(0)

; __device__ __forceinline__ unsigned pk2(float lo, float hi) { return f2bf(lo) | (f2bf(hi) << 16); }
; __device__ __forceinline__ void phase_prologue(const Args& A, const Ctx& C0) {
;     ...
;       for (int m = gw; m < M; m += 2 * NGW) { const int m2 = (m + NGW < M) ? m + NGW : m;
;           const float* srca = m < MP ? A.in[I_XP] + (size_t)m * D : A.in[I_XS] + (size_t)(m - MP) * D; const float* srcb = m2 < MP ? A.in[I_XP] + (size_t)m2 * D : A.in[I_XS] + (size_t)(m2 - MP) * D;
;           const f32x4* xa = (const f32x4*)srca + C.lane; const f32x4* xb = (const f32x4*)srcb + C.lane; f32x4 va[8], vb[8]; float sa = 0.f, sb = 0.f;
; #pragma unroll
;           for (int j = 0; j < 8; ++j) { va[j] = xa[64 * j]; vb[j] = xb[64 * j]; }
; #pragma unroll
;           for (int j = 0; j < 8; ++j) { sa += (va[j].x * va[j].x + va[j].y * va[j].y) + (va[j].z * va[j].z + va[j].w * va[j].w); sb += (vb[j].x * vb[j].x + vb[j].y * vb[j].y) + (vb[j].z * vb[j].z + vb[j].w * vb[j].w); }
;           sa = wave_sum_l(sa, C.lane); sb = wave_sum_l(sb, C.lane);
; #pragma unroll
;           for (int j = 0; j < 8; ++j) { v2u p; p.x = pk2(va[j].x, va[j].y); p.y = pk2(va[j].z, va[j].w); ((v2u*)(HB + (size_t)m * D) + C.lane)[64 * j] = p;
;               if (m2 != m) { v2u q; q.x = pk2(vb[j].x, vb[j].y); q.y = pk2(vb[j].z, vb[j].w); ((v2u*)(HB + (size_t)m2 * D) + C.lane)[64 * j] = q; } }
;           if (C.lane == 0) { SS[m] = sa; if (m2 != m) SS[m2] = sb; } }
.LBB0_1358:
	s_add_i32 s2, s12, 0xffff8000
	v_lshl_add_u64 v[2:3], s[0:1], 0, v[0:1]
	s_movk_i32 s13, 0x1000
	global_load_dwordx4 v[54:57], v0, s[0:1]
	global_load_dwordx4 v[46:49], v0, s[0:1] offset:1024
	global_load_dwordx4 v[38:41], v0, s[0:1] offset:2048
	global_load_dwordx4 v[30:33], v0, s[0:1] offset:3072
	s_add_u32 s0, s26, s48
	v_add_co_u32_e32 v2, vcc, s13, v2
	s_addc_u32 s1, s27, s49
	s_nop 0
	v_addc_co_u32_e32 v3, vcc, 0, v3, vcc
	global_load_dwordx4 v[22:25], v[2:3], off
	s_cmp_lt_i32 s12, 0x8000
	s_cselect_b32 s1, s1, 0
	s_cselect_b32 s0, s0, s2
	s_cselect_b32 s2, s81, s83
	s_cselect_b32 s3, s80, s82
	s_lshl_b64 s[0:1], s[0:1], 13
	s_add_u32 s0, s3, s0
	s_addc_u32 s1, s2, s1
	global_load_dwordx4 v[72:75], v0, s[0:1]
	global_load_dwordx4 v[58:61], v0, s[0:1] offset:1024
	global_load_dwordx4 v[50:53], v0, s[0:1] offset:2048
	global_load_dwordx4 v[42:45], v0, s[0:1] offset:3072
	v_lshl_add_u64 v[4:5], s[0:1], 0, v[0:1]
	v_add_co_u32_e32 v6, vcc, s13, v4
	s_cmp_lg_u32 s12, s50
	s_nop 0
	v_addc_co_u32_e32 v7, vcc, 0, v5, vcc
	global_load_dwordx4 v[34:37], v[6:7], off
	global_load_dwordx4 v[26:29], v[6:7], off offset:1024
	global_load_dwordx4 v[18:21], v[2:3], off offset:1024
	global_load_dwordx4 v[14:17], v[6:7], off offset:2048
	global_load_dwordx4 v[10:13], v[2:3], off offset:2048
	s_nop 0
	global_load_dwordx4 v[2:5], v[2:3], off offset:3072
	s_nop 0
	global_load_dwordx4 v[6:9], v[6:7], off offset:3072
	s_cselect_b64 s[2:3], -1, 0
	s_lshl_b64 s[0:1], s[50:51], 12
	s_cmp_eq_u32 s12, s50
	s_waitcnt vmcnt(0)
	v_mul_f32_e32 v63, v55, v55
	v_mul_f32_e32 v68, v57, v57
	v_mul_f32_e32 v69, v47, v47
	v_mul_f32_e32 v70, v49, v49
	v_mul_f32_e32 v71, v39, v39
	v_mul_f32_e32 v76, v41, v41
	v_fmac_f32_e32 v63, v54, v54
	v_fmac_f32_e32 v68, v56, v56
	v_fmac_f32_e32 v69, v46, v46
	v_fmac_f32_e32 v70, v48, v48
	v_mul_f32_e32 v77, v31, v31
	v_mul_f32_e32 v78, v33, v33
	v_fmac_f32_e32 v71, v38, v38
	v_fmac_f32_e32 v76, v40, v40
	v_add_f32_e32 v63, v63, v68
	v_add_f32_e32 v68, v69, v70
	v_fmac_f32_e32 v77, v30, v30
	v_fmac_f32_e32 v78, v32, v32
	v_add_f32_e32 v69, v71, v76
	v_mul_f32_e32 v71, v23, v23
	v_mul_f32_e32 v76, v25, v25
	v_add_f32_e32 v63, v63, v68
	v_add_f32_e32 v70, v77, v78
	v_fmac_f32_e32 v71, v22, v22
	v_fmac_f32_e32 v76, v24, v24
	v_add_f32_e32 v63, v63, v69
	v_add_f32_e32 v68, v71, v76
	v_add_f32_e32 v63, v63, v70
	v_add_f32_e32 v63, v63, v68
	v_mul_f32_e32 v68, v73, v73
	v_mul_f32_e32 v69, v75, v75
	v_mul_f32_e32 v70, v59, v59
	v_mul_f32_e32 v71, v61, v61
	v_mul_f32_e32 v76, v51, v51
	v_mul_f32_e32 v77, v53, v53
	v_fmac_f32_e32 v68, v72, v72
	v_fmac_f32_e32 v69, v74, v74
	v_fmac_f32_e32 v70, v58, v58
	v_fmac_f32_e32 v71, v60, v60
	v_mul_f32_e32 v78, v43, v43
	v_mul_f32_e32 v79, v45, v45
	v_fmac_f32_e32 v76, v50, v50
	v_fmac_f32_e32 v77, v52, v52
	v_add_f32_e32 v68, v68, v69
	v_add_f32_e32 v69, v70, v71
	v_fmac_f32_e32 v78, v42, v42
	v_fmac_f32_e32 v79, v44, v44
	v_add_f32_e32 v70, v76, v77
	v_mul_f32_e32 v76, v35, v35
	v_mul_f32_e32 v77, v37, v37
	v_add_f32_e32 v68, v68, v69
	v_add_f32_e32 v71, v78, v79
	v_fmac_f32_e32 v76, v34, v34
	v_fmac_f32_e32 v77, v36, v36
	v_add_f32_e32 v68, v68, v70
	v_add_f32_e32 v69, v76, v77
	v_add_f32_e32 v68, v68, v71
	v_add_f32_e32 v68, v68, v69
	v_mul_f32_e32 v69, v27, v27
	v_mul_f32_e32 v70, v29, v29
	v_fmac_f32_e32 v69, v26, v26
	v_fmac_f32_e32 v70, v28, v28
	v_add_f32_e32 v69, v69, v70
	v_add_f32_e32 v68, v68, v69
	v_mul_f32_e32 v69, v19, v19
	v_mul_f32_e32 v70, v21, v21
	v_fmac_f32_e32 v69, v18, v18
	v_fmac_f32_e32 v70, v20, v20
	v_add_f32_e32 v69, v69, v70
	v_add_f32_e32 v63, v63, v69
	v_mul_f32_e32 v69, v15, v15
	v_mul_f32_e32 v70, v17, v17
	v_fmac_f32_e32 v69, v14, v14
	v_fmac_f32_e32 v70, v16, v16
	v_add_f32_e32 v69, v69, v70
	v_add_f32_e32 v68, v68, v69
	v_mul_f32_e32 v69, v11, v11
	v_mul_f32_e32 v70, v13, v13
	v_fmac_f32_e32 v69, v10, v10
	v_fmac_f32_e32 v70, v12, v12
	v_add_f32_e32 v69, v69, v70
	v_add_f32_e32 v63, v63, v69
	v_mul_f32_e32 v69, v7, v7
	v_mul_f32_e32 v70, v9, v9
	v_fmac_f32_e32 v69, v6, v6
	v_fmac_f32_e32 v70, v8, v8
	v_add_f32_e32 v69, v69, v70
	v_add_f32_e32 v68, v68, v69
	v_mul_f32_e32 v69, v3, v3
	v_mul_f32_e32 v70, v5, v5
	v_fmac_f32_e32 v69, v2, v2
	v_fmac_f32_e32 v70, v4, v4
	v_add_f32_e32 v69, v69, v70
	v_add_f32_e32 v63, v63, v69
	v_add_f32_dpp v68, v68, v68 quad_perm:[1,0,3,2] row_mask:0xf bank_mask:0xf bound_ctrl:1
	v_lshl_add_u64 v[70:71], s[24:25], 0, v[66:67]
	v_add_f32_dpp v63, v63, v63 quad_perm:[1,0,3,2] row_mask:0xf bank_mask:0xf bound_ctrl:1
	v_add_f32_dpp v68, v68, v68 quad_perm:[2,3,0,1] row_mask:0xf bank_mask:0xf bound_ctrl:1
	s_nop 0
	v_add_f32_dpp v63, v63, v63 quad_perm:[2,3,0,1] row_mask:0xf bank_mask:0xf bound_ctrl:1
	v_add_f32_dpp v68, v68, v68 row_half_mirror row_mask:0xf bank_mask:0xf bound_ctrl:1
	s_nop 0
	v_add_f32_dpp v63, v63, v63 row_half_mirror row_mask:0xf bank_mask:0xf bound_ctrl:1
	v_add_f32_dpp v68, v68, v68 row_mirror row_mask:0xf bank_mask:0xf bound_ctrl:1
	s_nop 0
	v_add_f32_dpp v63, v63, v63 row_mirror row_mask:0xf bank_mask:0xf bound_ctrl:1
	v_readlane_b32 s17, v68, 0
	v_readlane_b32 s13, v63, 0
	v_readlane_b32 s14, v63, 16
	v_readlane_b32 s15, v63, 32
	v_readlane_b32 s16, v63, 48
	s_nop 0
	s_nop 0
	s_nop 0
	s_nop 0
	s_nop 0
	v_cvt_pk_bf16_f32 v72, v72, v73
	s_nop 0
	s_nop 0
	s_nop 0
	s_nop 0
	s_nop 0
	v_cvt_pk_bf16_f32 v73, v74, v75
	v_add_co_u32_e32 v74, vcc, 0x256d7000, v70
	v_readlane_b32 s18, v68, 16
	v_readlane_b32 s19, v68, 32
	v_readlane_b32 s30, v68, 48
	v_lshl_add_u64 v[68:69], v[64:65], 0, s[0:1]
	s_nop 0
	v_addc_co_u32_e32 v75, vcc, 0, v71, vcc
	flat_store_dwordx2 v[74:75], v[72:73] offset:2304
	s_cbranch_scc1 .LBB0_1360
	s_nop 0
	s_nop 0
	s_nop 0
	s_nop 0
	s_nop 0
	v_cvt_pk_bf16_f32 v54, v54, v55
	s_nop 0
	s_nop 0
	s_nop 0
	s_nop 0
	s_nop 0
	v_cvt_pk_bf16_f32 v55, v56, v57
	flat_store_dwordx2 v[68:69], v[54:55]
; __device__ __forceinline__ unsigned pk2(float lo, float hi) { return f2bf(lo) | (f2bf(hi) << 16); }
; __device__ __forceinline__ void phase_prologue(const Args& A, const Ctx& C0) {
;     ...
; #pragma unroll
;           for (int j = 0; j < 8; ++j) { v2u p; p.x = pk2(va[j].x, va[j].y); p.y = pk2(va[j].z, va[j].w); ((v2u*)(HB + (size_t)m * D) + C.lane)[64 * j] = p;
;               if (m2 != m) { v2u q; q.x = pk2(vb[j].x, vb[j].y); q.y = pk2(vb[j].z, vb[j].w); ((v2u*)(HB + (size_t)m2 * D) + C.lane)[64 * j] = q; } }
.LBB0_1360:
	s_nop 0
	s_nop 0
	s_nop 0
	s_nop 0
	s_nop 0
	v_cvt_pk_bf16_f32 v54, v58, v59
	s_nop 0
	s_nop 0
	s_nop 0
	s_nop 0
	s_nop 0
	v_cvt_pk_bf16_f32 v55, v60, v61
	v_add_co_u32_e32 v56, vcc, 0x256d7000, v70
	v_cndmask_b32_e64 v58, 0, 1, s[2:3]
	s_nop 0
	v_addc_co_u32_e32 v57, vcc, 0, v71, vcc
	v_cmp_ne_u32_e64 s[0:1], 1, v58
	s_andn2_b64 vcc, exec, s[2:3]
	flat_store_dwordx2 v[56:57], v[54:55] offset:2816
	s_cbranch_vccnz .LBB0_1362
	s_nop 0
	s_nop 0
	s_nop 0
	s_nop 0
	s_nop 0
	v_cvt_pk_bf16_f32 v46, v46, v47
	s_nop 0
	s_nop 0
	s_nop 0
	s_nop 0
	s_nop 0
	v_cvt_pk_bf16_f32 v47, v48, v49
	flat_store_dwordx2 v[68:69], v[46:47] offset:512
.LBB0_1362:
	s_nop 0
	s_nop 0
	s_nop 0
	s_nop 0
	s_nop 0
	v_cvt_pk_bf16_f32 v46, v50, v51
	s_nop 0
	s_nop 0
	s_nop 0
	s_nop 0
	s_nop 0
	v_cvt_pk_bf16_f32 v47, v52, v53
	v_add_co_u32_e32 v48, vcc, 0x256d7000, v70
	s_nop 1
	v_addc_co_u32_e32 v49, vcc, 0, v71, vcc
	s_and_b64 vcc, exec, s[0:1]
	flat_store_dwordx2 v[48:49], v[46:47] offset:3328
	s_cbranch_vccnz .LBB0_1364
	s_nop 0
	s_nop 0
	s_nop 0
	s_nop 0
	s_nop 0
	v_cvt_pk_bf16_f32 v38, v38, v39
	s_nop 0
	s_nop 0
	s_nop 0
	s_nop 0
	s_nop 0
	v_cvt_pk_bf16_f32 v39, v40, v41
	flat_store_dwordx2 v[68:69], v[38:39] offset:1024
.LBB0_1364:
	s_nop 0
	s_nop 0
	s_nop 0
	s_nop 0
	s_nop 0
	v_cvt_pk_bf16_f32 v38, v42, v43
	s_nop 0
	s_nop 0
	s_nop 0
	s_nop 0
	s_nop 0
	v_cvt_pk_bf16_f32 v39, v44, v45
	v_add_co_u32_e32 v40, vcc, 0x256d7000, v70
	s_nop 1
	v_addc_co_u32_e32 v41, vcc, 0, v71, vcc
	s_and_b64 vcc, exec, s[0:1]
	flat_store_dwordx2 v[40:41], v[38:39] offset:3840
	s_cbranch_vccnz .LBB0_1366
	s_nop 0
	s_nop 0
	s_nop 0
	s_nop 0
	s_nop 0
	v_cvt_pk_bf16_f32 v30, v30, v31
	s_nop 0
	s_nop 0
	s_nop 0
	s_nop 0
	s_nop 0
	v_cvt_pk_bf16_f32 v31, v32, v33
	flat_store_dwordx2 v[68:69], v[30:31] offset:1536
.LBB0_1366:
	s_nop 0
	s_nop 0
	s_nop 0
	s_nop 0
	s_nop 0
	v_cvt_pk_bf16_f32 v30, v34, v35
	s_nop 0
	s_nop 0
	s_nop 0
	s_nop 0
	s_nop 0
	v_cvt_pk_bf16_f32 v31, v36, v37
	v_add_co_u32_e32 v32, vcc, 0x256d8000, v70
	s_nop 1
	v_addc_co_u32_e32 v33, vcc, 0, v71, vcc
	s_and_b64 vcc, exec, s[0:1]
	flat_store_dwordx2 v[32:33], v[30:31] offset:256
	s_cbranch_vccnz .LBB0_1368
	s_nop 0
	s_nop 0
	s_nop 0
	s_nop 0
	s_nop 0
	v_cvt_pk_bf16_f32 v22, v22, v23
	s_nop 0
	s_nop 0
	s_nop 0
	s_nop 0
	s_nop 0
	v_cvt_pk_bf16_f32 v23, v24, v25
	flat_store_dwordx2 v[68:69], v[22:23] offset:2048
.LBB0_1368:
	s_nop 0
	s_nop 0
	s_nop 0
	s_nop 0
	s_nop 0
	v_cvt_pk_bf16_f32 v22, v26, v27
	s_nop 0
	s_nop 0
	s_nop 0
	s_nop 0
	s_nop 0
	v_cvt_pk_bf16_f32 v23, v28, v29
	v_add_co_u32_e32 v24, vcc, 0x256d8000, v70
	s_nop 1
	v_addc_co_u32_e32 v25, vcc, 0, v71, vcc
	s_and_b64 vcc, exec, s[0:1]
	flat_store_dwordx2 v[24:25], v[22:23] offset:768
	s_cbranch_vccnz .LBB0_1370
	s_nop 0
	s_nop 0
	s_nop 0
	s_nop 0
	s_nop 0
	v_cvt_pk_bf16_f32 v18, v18, v19
	s_nop 0
	s_nop 0
	s_nop 0
	s_nop 0
	s_nop 0
	v_cvt_pk_bf16_f32 v19, v20, v21
	flat_store_dwordx2 v[68:69], v[18:19] offset:2560
.LBB0_1370:
	s_nop 0
	s_nop 0
	s_nop 0
	s_nop 0
	s_nop 0
	v_cvt_pk_bf16_f32 v14, v14, v15
	s_nop 0
	s_nop 0
	s_nop 0
	s_nop 0
	s_nop 0
	v_cvt_pk_bf16_f32 v15, v16, v17
	v_add_co_u32_e32 v16, vcc, 0x256d8000, v70
	s_nop 1
	v_addc_co_u32_e32 v17, vcc, 0, v71, vcc
	s_and_b64 vcc, exec, s[0:1]
	flat_store_dwordx2 v[16:17], v[14:15] offset:1280
	s_cbranch_vccnz .LBB0_1372
	s_nop 0
	s_nop 0
	s_nop 0
	s_nop 0
	s_nop 0
	v_cvt_pk_bf16_f32 v10, v10, v11
	s_nop 0
	s_nop 0
	s_nop 0
	s_nop 0
	s_nop 0
	v_cvt_pk_bf16_f32 v11, v12, v13
	flat_store_dwordx2 v[68:69], v[10:11] offset:3072
.LBB0_1372:
	s_nop 0
	s_nop 0
	s_nop 0
	s_nop 0
	s_nop 0
	v_cvt_pk_bf16_f32 v6, v6, v7
	s_nop 0
	s_nop 0
	s_nop 0
	s_nop 0
	s_nop 0
	v_cvt_pk_bf16_f32 v7, v8, v9
	v_add_co_u32_e32 v8, vcc, 0x256d8000, v70
	s_nop 1
	v_addc_co_u32_e32 v9, vcc, 0, v71, vcc
	s_and_b64 vcc, exec, s[0:1]
	flat_store_dwordx2 v[8:9], v[6:7] offset:1792
	s_cbranch_vccnz .LBB0_1374
	s_nop 0
	s_nop 0
	s_nop 0
	s_nop 0
	s_nop 0
	v_cvt_pk_bf16_f32 v2, v2, v3
	s_nop 0
	s_nop 0
	s_nop 0
	s_nop 0
	s_nop 0
	v_cvt_pk_bf16_f32 v3, v4, v5
	flat_store_dwordx2 v[68:69], v[2:3] offset:3584
